# GEMM K-loops: one static s_setprio 1 for waves 4-7 per tile (flips already removed), reset to 0 at loop exit
# baseline (speedup 1.0000x reference)
; #define G8_STAGE(bufoff, gbase) do { _Pragma("unroll") for (int _i = 0; _i < 2; ++_i) \
;     __builtin_amdgcn_global_load_lds((const unsigned*)((const char*)(gbase) + voffA[_i]), (LAS unsigned*)(lds + (bufoff) + ldsw + _i * 8192), 16, 0, 0); } while (0)
; #define G8_LDA(dst, b, h) do { _Pragma("unroll") for (int m = 0; m < 4; ++m) _Pragma("unroll") for (int k = 0; k < 2; ++k) dst[m][k] = *(const LAS h16x8*)(lds + G8_SA(b, h) + aoff + m * 2048 + k * 1024); } while (0)
; #define G8_LDB(dst, b, h) do { _Pragma("unroll") for (int n = 0; n < 2; ++n) _Pragma("unroll") for (int k = 0; k < 2; ++k) dst[n][k] = *(const LAS h16x8*)(lds + G8_SB(b, h) + boff + n * 2048 + k * 1024); } while (0)
; #define G8_MMA(ai, bj, At, Bt_) do { __builtin_amdgcn_s_setprio(1); _Pragma("unroll") for (int m = 0; m < 4; ++m) _Pragma("unroll") for (int n = 0; n < 2; ++n) _Pragma("unroll") for (int k = 0; k < 2; ++k) \
;     acc[ai][bj][m][n] = __builtin_amdgcn_mfma_f32_16x16x32_f16(Bt_[n][k], At[m][k], acc[ai][bj][m][n], 0, 0, 0); __builtin_amdgcn_s_setprio(0); } while (0)
; #define G8_BAR __builtin_amdgcn_s_barrier()
; template <class Epi>
; __device__ __forceinline__ void gemm_phase(LAS unsigned char* lds, const h16* A, const h16* Bt, int K, const Order& S, const Epi& E) {
;     ...
;   for (;;) {
;     const bool has_next = S.next(ui + 1, nxt);
;     const char* nA = has_next ? (const char*)A + (size_t)nxt.pm * tstep : cA;
;     const char* nB = has_next ? (const char*)Bt + (size_t)nxt.pn * tstep : cB;
;     for (int t = 0; t < nt; t += 2) {
;       const bool last = (t == nt - 2);
;       const char* a1 = cA + (size_t)(t + 1) * kstep;
;       const char* a2 = last ? nA : cA + (size_t)(t + 2) * kstep;
;       const char* b2 = last ? nB : cB + (size_t)(t + 2) * kstep;
;       const char* a3 = a2 + kstep;
;       const char* b3 = b2 + kstep;
;       if (Epi::MID_T >= 0 && t == Epi::MID_T) E.mid(acc, ui, wr, fr);
;       G8_LDB(B0, 0, 0); G8_SCHED; G8_LDA(At, 0, 0); G8_STAGE(G8_SA(1, 1), a1 + hstep);
;       G8_WAIT_L(8); G8_BAR; G8_WAIT_L(0); G8_MMA(0, 0, At, B0); G8_BAR; G8_SCHED;
;     ...
; #pragma unroll
;     for (int a = 0; a < 2; ++a)
; #pragma unroll
;       for (int b = 0; b < 2; ++b)
; #pragma unroll
;         for (int m = 0; m < 4; ++m)
; #pragma unroll
;           for (int n = 0; n < 2; ++n) acc[a][b][m][n] = (f32x4){0.f, 0.f, 0.f, 0.f};
;     cur = nxt; cA = nA; cB = nB; ++ui;
.LBB0_194:
	v_mov_b64_e32 v[2:3], 0x380
	s_ashr_i32 s19, s18, 31
	v_cmp_lt_i64_e32 vcc, s[14:15], v[2:3]
	s_lshl_b64 s[14:15], s[18:19], 19
	s_add_u32 s20, s29, s14
	s_addc_u32 s21, s30, s15
	s_and_b64 s[14:15], vcc, exec
	s_cselect_b32 s19, s21, s57
	s_cselect_b32 s25, s20, s56
	s_ashr_i32 s17, s16, 31
	s_lshl_b64 s[14:15], s[16:17], 19
	s_add_u32 s22, s31, s14
	s_addc_u32 s23, s34, s15
	s_and_b64 s[14:15], vcc, exec
	s_cselect_b32 s17, s23, s55
	s_cselect_b32 s26, s22, s54
	s_add_u32 s10, s56, 0x40080
	s_addc_u32 s11, s57, 0
	s_add_u32 s27, s54, 0x100
	v_mov_b32_e32 v2, 0
	s_addc_u32 s53, s55, 0
	s_mov_b32 s54, -2
	v_mov_b32_e32 v3, v2
	v_mov_b32_e32 v4, v2
	v_mov_b32_e32 v5, v2
	v_mov_b32_e32 v6, v2
	v_mov_b32_e32 v7, v2
	v_mov_b32_e32 v8, v2
	v_mov_b32_e32 v9, v2
	v_mov_b32_e32 v18, v2
	v_mov_b32_e32 v19, v2
	v_mov_b32_e32 v20, v2
	v_mov_b32_e32 v21, v2
	v_mov_b32_e32 v22, v2
	v_mov_b32_e32 v23, v2
	v_mov_b32_e32 v24, v2
	v_mov_b32_e32 v25, v2
	v_mov_b32_e32 v34, v2
	v_mov_b32_e32 v35, v2
	v_mov_b32_e32 v36, v2
	v_mov_b32_e32 v37, v2
	v_mov_b32_e32 v38, v2
	v_mov_b32_e32 v39, v2
	v_mov_b32_e32 v40, v2
	v_mov_b32_e32 v41, v2
	v_mov_b32_e32 v50, v2
	v_mov_b32_e32 v51, v2
	v_mov_b32_e32 v52, v2
	v_mov_b32_e32 v53, v2
	v_mov_b32_e32 v54, v2
	v_mov_b32_e32 v55, v2
	v_mov_b32_e32 v56, v2
	v_mov_b32_e32 v57, v2
	v_mov_b32_e32 v10, v2
	v_mov_b32_e32 v11, v2
	v_mov_b32_e32 v12, v2
	v_mov_b32_e32 v13, v2
	v_mov_b32_e32 v14, v2
	v_mov_b32_e32 v15, v2
	v_mov_b32_e32 v16, v2
	v_mov_b32_e32 v17, v2
	v_mov_b32_e32 v26, v2
	v_mov_b32_e32 v27, v2
	v_mov_b32_e32 v28, v2
	v_mov_b32_e32 v29, v2
	v_mov_b32_e32 v30, v2
	v_mov_b32_e32 v31, v2
	v_mov_b32_e32 v32, v2
	v_mov_b32_e32 v33, v2
	v_mov_b32_e32 v42, v2
	v_mov_b32_e32 v43, v2
	v_mov_b32_e32 v44, v2
	v_mov_b32_e32 v45, v2
	v_mov_b32_e32 v46, v2
	v_mov_b32_e32 v47, v2
	v_mov_b32_e32 v48, v2
	v_mov_b32_e32 v49, v2
	v_mov_b32_e32 v58, v2
	v_mov_b32_e32 v59, v2
	v_mov_b32_e32 v60, v2
	v_mov_b32_e32 v61, v2
	v_mov_b32_e32 v62, v2
	v_mov_b32_e32 v63, v2
	v_mov_b32_e32 v64, v2
	v_mov_b32_e32 v65, v2
	v_mov_b32_e32 v66, v2
	v_mov_b32_e32 v67, v2
	v_mov_b32_e32 v68, v2
	v_mov_b32_e32 v69, v2
	v_mov_b32_e32 v70, v2
	v_mov_b32_e32 v71, v2
	v_mov_b32_e32 v72, v2
	v_mov_b32_e32 v73, v2
	v_mov_b32_e32 v82, v2
	v_mov_b32_e32 v83, v2
	v_mov_b32_e32 v84, v2
	v_mov_b32_e32 v85, v2
	v_mov_b32_e32 v86, v2
	v_mov_b32_e32 v87, v2
	v_mov_b32_e32 v88, v2
	v_mov_b32_e32 v89, v2
	v_mov_b32_e32 v98, v2
	v_mov_b32_e32 v99, v2
	v_mov_b32_e32 v100, v2
	v_mov_b32_e32 v101, v2
	v_mov_b32_e32 v102, v2
	v_mov_b32_e32 v103, v2
	v_mov_b32_e32 v104, v2
	v_mov_b32_e32 v105, v2
	v_mov_b32_e32 v114, v2
	v_mov_b32_e32 v115, v2
	v_mov_b32_e32 v116, v2
	v_mov_b32_e32 v117, v2
	v_mov_b32_e32 v118, v2
	v_mov_b32_e32 v119, v2
	v_mov_b32_e32 v120, v2
	v_mov_b32_e32 v121, v2
	v_mov_b32_e32 v74, v2
	v_mov_b32_e32 v75, v2
	v_mov_b32_e32 v76, v2
	v_mov_b32_e32 v77, v2
	v_mov_b32_e32 v78, v2
	v_mov_b32_e32 v79, v2
	v_mov_b32_e32 v80, v2
	v_mov_b32_e32 v81, v2
	v_mov_b32_e32 v90, v2
	v_mov_b32_e32 v91, v2
	v_mov_b32_e32 v92, v2
	v_mov_b32_e32 v93, v2
	v_mov_b32_e32 v94, v2
	v_mov_b32_e32 v95, v2
	v_mov_b32_e32 v96, v2
	v_mov_b32_e32 v97, v2
	v_mov_b32_e32 v106, v2
	v_mov_b32_e32 v107, v2
	v_mov_b32_e32 v108, v2
	v_mov_b32_e32 v109, v2
	v_mov_b32_e32 v110, v2
	v_mov_b32_e32 v111, v2
	v_mov_b32_e32 v112, v2
	v_mov_b32_e32 v113, v2
	v_mov_b32_e32 v122, v2
	v_mov_b32_e32 v123, v2
	v_mov_b32_e32 v124, v2
	v_mov_b32_e32 v125, v2
	v_mov_b32_e32 v126, v2
	v_mov_b32_e32 v127, v2
	v_mov_b32_e32 v128, v2
	v_mov_b32_e32 v129, v2
	v_readfirstlane_b32 vcc_lo, v145
	s_cmp_lt_u32 vcc_lo, 0x100
	s_cbranch_scc1 .Lgprio_g1
	s_setprio 1
.Lgprio_g1:
	ds_read_b128 v[152:155], v161
	ds_read_b128 v[178:181], v162
	ds_read_b128 v[182:185], v163
	ds_read_b128 v[186:189], v164
.LBB0_195:
	s_add_u32 s12, s10, 0xfffc0080
	s_addc_u32 s13, s11, -1
	s_cmp_eq_u32 s54, 12
	s_cselect_b32 s15, s19, s13
	s_cselect_b32 s14, s25, s12
	s_cselect_b32 s13, s17, s53
	s_cselect_b32 s12, s26, s27
	s_mov_b32 m0, s50
	v_lshl_add_u64 v[140:141], s[10:11], 0, v[136:137]
	ds_read_b128 v[202:205], v159
	ds_read_b128 v[206:209], v159 offset:1024
	ds_read_b128 v[210:213], v159 offset:2048
	ds_read_b128 v[214:217], v159 offset:3072
	ds_read_b128 v[218:221], v159 offset:4096
	ds_read_b128 v[222:225], v159 offset:5120
	ds_read_b128 v[226:229], v159 offset:6144
	ds_read_b128 v[230:233], v159 offset:7168
	global_load_lds_dwordx4 v[140:141], off
	v_lshl_add_u64 v[140:141], s[10:11], 0, v[138:139]
	s_mov_b32 m0, s51
	s_nop 0
	global_load_lds_dwordx4 v[140:141], off
	s_waitcnt lgkmcnt(8)
	s_barrier
	s_waitcnt lgkmcnt(0)
	s_nop 0
	s_waitcnt lgkmcnt(0)
	v_mfma_f32_16x16x32_f16 v[126:129], v[152:155], v[202:205], v[126:129]
	v_mfma_f32_16x16x32_f16 v[122:125], v[182:185], v[202:205], v[122:125]
	v_mfma_f32_16x16x32_f16 v[110:113], v[152:155], v[210:213], v[110:113]
	v_mfma_f32_16x16x32_f16 v[106:109], v[182:185], v[210:213], v[106:109]
	v_mfma_f32_16x16x32_f16 v[94:97], v[152:155], v[218:221], v[94:97]
	v_mfma_f32_16x16x32_f16 v[90:93], v[182:185], v[218:221], v[90:93]
	v_mfma_f32_16x16x32_f16 v[78:81], v[152:155], v[226:229], v[78:81]
	v_mfma_f32_16x16x32_f16 v[74:77], v[182:185], v[226:229], v[74:77]
	v_mfma_f32_16x16x32_f16 v[126:129], v[178:181], v[206:209], v[126:129]
	v_mfma_f32_16x16x32_f16 v[122:125], v[186:189], v[206:209], v[122:125]
	v_mfma_f32_16x16x32_f16 v[110:113], v[178:181], v[214:217], v[110:113]
	v_mfma_f32_16x16x32_f16 v[106:109], v[186:189], v[214:217], v[106:109]
	v_mfma_f32_16x16x32_f16 v[94:97], v[178:181], v[222:225], v[94:97]
	v_mfma_f32_16x16x32_f16 v[90:93], v[186:189], v[222:225], v[90:93]
	v_mfma_f32_16x16x32_f16 v[78:81], v[178:181], v[230:233], v[78:81]
	v_mfma_f32_16x16x32_f16 v[74:77], v[186:189], v[230:233], v[74:77]
	s_nop 0
	s_barrier
; #define G8_STAGE(bufoff, gbase) do { _Pragma("unroll") for (int _i = 0; _i < 2; ++_i) \
;     __builtin_amdgcn_global_load_lds((const unsigned*)((const char*)(gbase) + voffA[_i]), (LAS unsigned*)(lds + (bufoff) + ldsw + _i * 8192), 16, 0, 0); } while (0)
; #define G8_LDA(dst, b, h) do { _Pragma("unroll") for (int m = 0; m < 4; ++m) _Pragma("unroll") for (int k = 0; k < 2; ++k) dst[m][k] = *(const LAS h16x8*)(lds + G8_SA(b, h) + aoff + m * 2048 + k * 1024); } while (0)
; #define G8_LDB(dst, b, h) do { _Pragma("unroll") for (int n = 0; n < 2; ++n) _Pragma("unroll") for (int k = 0; k < 2; ++k) dst[n][k] = *(const LAS h16x8*)(lds + G8_SB(b, h) + boff + n * 2048 + k * 1024); } while (0)
; #define G8_MMA(ai, bj, At, Bt_) do { __builtin_amdgcn_s_setprio(1); _Pragma("unroll") for (int m = 0; m < 4; ++m) _Pragma("unroll") for (int n = 0; n < 2; ++n) _Pragma("unroll") for (int k = 0; k < 2; ++k) \
;     acc[ai][bj][m][n] = __builtin_amdgcn_mfma_f32_16x16x32_f16(Bt_[n][k], At[m][k], acc[ai][bj][m][n], 0, 0, 0); __builtin_amdgcn_s_setprio(0); } while (0)
; #define G8_WAIT_V(n) asm volatile("s_waitcnt vmcnt(" #n ")" ::: "memory")
; #define G8_WAIT_L(n) asm volatile("s_waitcnt lgkmcnt(" #n ")" ::: "memory")
; #define G8_BAR __builtin_amdgcn_s_barrier()
; #define G8_SCHED __builtin_amdgcn_sched_barrier(0)
; template <class Epi>
; __device__ __forceinline__ void gemm_phase(LAS unsigned char* lds, const h16* A, const h16* Bt, int K, const Order& S, const Epi& E) {
;     ...
;       G8_LDB(B1, 0, 1); G8_STAGE(G8_SB(0, 0), b2);
;       G8_BAR; G8_WAIT_L(0); G8_MMA(0, 1, At, B1); G8_BAR;
;       G8_LDA(At, 0, 1); G8_STAGE(G8_SA(0, 0), a2);
;       G8_BAR; G8_WAIT_L(0); G8_MMA(1, 0, At, B0); G8_BAR; G8_SCHED;
;       G8_STAGE(G8_SB(0, 1), b2 + hstep);
;       G8_WAIT_V(6); G8_BAR; G8_MMA(1, 1, At, B1); G8_BAR;
;       G8_LDB(B0, 1, 0); G8_SCHED; G8_LDA(At, 1, 0); G8_STAGE(G8_SA(0, 1), a2 + hstep);
;       G8_WAIT_L(8); G8_BAR; G8_WAIT_L(0); G8_MMA(0, 0, At, B0); G8_BAR; G8_SCHED;
	s_mov_b32 m0, s36
	v_lshl_add_u64 v[140:141], s[12:13], 0, v[132:133]
	ds_read_b128 v[234:237], v165
	ds_read_b128 v[238:241], v166
	ds_read_b128 v[242:245], v167
	ds_read_b128 v[246:249], v168
	global_load_lds_dwordx4 v[140:141], off
	v_lshl_add_u64 v[156:157], s[12:13], 0, v[130:131]
	s_mov_b32 m0, s37
	s_nop 0
	global_load_lds_dwordx4 v[156:157], off
	s_barrier
	s_waitcnt lgkmcnt(0)
	s_nop 0
	s_waitcnt lgkmcnt(0)
	v_mfma_f32_16x16x32_f16 v[118:121], v[234:237], v[202:205], v[118:121]
	v_mfma_f32_16x16x32_f16 v[114:117], v[242:245], v[202:205], v[114:117]
	v_mfma_f32_16x16x32_f16 v[102:105], v[234:237], v[210:213], v[102:105]
	v_mfma_f32_16x16x32_f16 v[98:101], v[242:245], v[210:213], v[98:101]
	v_mfma_f32_16x16x32_f16 v[86:89], v[234:237], v[218:221], v[86:89]
	v_mfma_f32_16x16x32_f16 v[82:85], v[242:245], v[218:221], v[82:85]
	v_mfma_f32_16x16x32_f16 v[70:73], v[234:237], v[226:229], v[70:73]
	v_mfma_f32_16x16x32_f16 v[66:69], v[242:245], v[226:229], v[66:69]
	v_mfma_f32_16x16x32_f16 v[118:121], v[238:241], v[206:209], v[118:121]
	v_mfma_f32_16x16x32_f16 v[114:117], v[246:249], v[206:209], v[114:117]
	v_mfma_f32_16x16x32_f16 v[102:105], v[238:241], v[214:217], v[102:105]
	v_mfma_f32_16x16x32_f16 v[98:101], v[246:249], v[214:217], v[98:101]
	v_mfma_f32_16x16x32_f16 v[86:89], v[238:241], v[222:225], v[86:89]
	v_mfma_f32_16x16x32_f16 v[82:85], v[246:249], v[222:225], v[82:85]
	v_mfma_f32_16x16x32_f16 v[70:73], v[238:241], v[230:233], v[70:73]
	v_mfma_f32_16x16x32_f16 v[66:69], v[246:249], v[230:233], v[66:69]
	s_nop 0
	s_mov_b32 m0, s35
	v_lshl_add_u64 v[250:251], s[14:15], 0, v[132:133]
	s_barrier
	ds_read_b128 v[202:205], v159 offset:16384
	ds_read_b128 v[206:209], v159 offset:17408
	ds_read_b128 v[210:213], v159 offset:18432
	ds_read_b128 v[214:217], v159 offset:19456
	ds_read_b128 v[218:221], v159 offset:20480
	ds_read_b128 v[222:225], v159 offset:21504
	ds_read_b128 v[226:229], v159 offset:22528
	ds_read_b128 v[230:233], v159 offset:23552
	global_load_lds_dwordx4 v[250:251], off
	v_lshl_add_u64 v[252:253], s[14:15], 0, v[130:131]
	s_mov_b32 m0, s38
	s_nop 0
	global_load_lds_dwordx4 v[252:253], off
	s_waitcnt vmcnt(10)
	s_barrier
	s_waitcnt lgkmcnt(0)
	s_nop 0
	s_waitcnt lgkmcnt(0)
	v_mfma_f32_16x16x32_f16 v[62:65], v[152:155], v[202:205], v[62:65]
	v_mfma_f32_16x16x32_f16 v[58:61], v[182:185], v[202:205], v[58:61]
	v_mfma_f32_16x16x32_f16 v[46:49], v[152:155], v[210:213], v[46:49]
	v_mfma_f32_16x16x32_f16 v[42:45], v[182:185], v[210:213], v[42:45]
	v_mfma_f32_16x16x32_f16 v[30:33], v[152:155], v[218:221], v[30:33]
	v_mfma_f32_16x16x32_f16 v[26:29], v[182:185], v[218:221], v[26:29]
	v_mfma_f32_16x16x32_f16 v[14:17], v[152:155], v[226:229], v[14:17]
	v_mfma_f32_16x16x32_f16 v[10:13], v[182:185], v[226:229], v[10:13]
	v_mfma_f32_16x16x32_f16 v[62:65], v[178:181], v[206:209], v[62:65]
	v_mfma_f32_16x16x32_f16 v[58:61], v[186:189], v[206:209], v[58:61]
	v_mfma_f32_16x16x32_f16 v[46:49], v[178:181], v[214:217], v[46:49]
	v_mfma_f32_16x16x32_f16 v[42:45], v[186:189], v[214:217], v[42:45]
	v_mfma_f32_16x16x32_f16 v[30:33], v[178:181], v[222:225], v[30:33]
	v_mfma_f32_16x16x32_f16 v[26:29], v[186:189], v[222:225], v[26:29]
	v_mfma_f32_16x16x32_f16 v[14:17], v[178:181], v[230:233], v[14:17]
	v_mfma_f32_16x16x32_f16 v[10:13], v[186:189], v[230:233], v[10:13]
	s_nop 0
	s_barrier
	s_add_u32 s56, s12, 0x40000
	s_addc_u32 s57, s13, 0
	s_mov_b32 m0, s39
	v_lshl_add_u64 v[152:153], s[56:57], 0, v[132:133]
	global_load_lds_dwordx4 v[152:153], off
	v_lshl_add_u64 v[152:153], s[56:57], 0, v[130:131]
	s_mov_b32 m0, s40
	s_nop 0
	global_load_lds_dwordx4 v[152:153], off
	ds_read_b128 v[152:155], v169
	ds_read_b128 v[178:181], v170
	ds_read_b128 v[182:185], v171
	ds_read_b128 v[186:189], v172
	s_waitcnt vmcnt(6)
	s_barrier
	s_nop 0
	v_mfma_f32_16x16x32_f16 v[54:57], v[234:237], v[202:205], v[54:57]
	v_mfma_f32_16x16x32_f16 v[50:53], v[242:245], v[202:205], v[50:53]
	v_mfma_f32_16x16x32_f16 v[38:41], v[234:237], v[210:213], v[38:41]
	v_mfma_f32_16x16x32_f16 v[34:37], v[242:245], v[210:213], v[34:37]
	v_mfma_f32_16x16x32_f16 v[22:25], v[234:237], v[218:221], v[22:25]
	v_mfma_f32_16x16x32_f16 v[18:21], v[242:245], v[218:221], v[18:21]
	v_mfma_f32_16x16x32_f16 v[6:9], v[234:237], v[226:229], v[6:9]
	v_mfma_f32_16x16x32_f16 v[2:5], v[242:245], v[226:229], v[2:5]
	v_mfma_f32_16x16x32_f16 v[54:57], v[238:241], v[206:209], v[54:57]
	v_mfma_f32_16x16x32_f16 v[50:53], v[246:249], v[206:209], v[50:53]
	v_mfma_f32_16x16x32_f16 v[38:41], v[238:241], v[214:217], v[38:41]
	v_mfma_f32_16x16x32_f16 v[34:37], v[246:249], v[214:217], v[34:37]
	v_mfma_f32_16x16x32_f16 v[22:25], v[238:241], v[222:225], v[22:25]
	v_mfma_f32_16x16x32_f16 v[18:21], v[246:249], v[222:225], v[18:21]
	v_mfma_f32_16x16x32_f16 v[6:9], v[238:241], v[230:233], v[6:9]
	v_mfma_f32_16x16x32_f16 v[2:5], v[246:249], v[230:233], v[2:5]
	s_nop 0
	s_barrier
	s_add_u32 s14, s14, 0x40000
	s_addc_u32 s15, s15, 0
	s_mov_b32 m0, s41
	v_lshl_add_u64 v[234:235], s[14:15], 0, v[132:133]
	ds_read_b128 v[202:205], v159 offset:32768
	ds_read_b128 v[206:209], v159 offset:33792
	ds_read_b128 v[210:213], v159 offset:34816
	ds_read_b128 v[214:217], v159 offset:35840
	ds_read_b128 v[218:221], v159 offset:36864
	ds_read_b128 v[222:225], v159 offset:37888
	ds_read_b128 v[226:229], v159 offset:38912
	ds_read_b128 v[230:233], v159 offset:39936
	global_load_lds_dwordx4 v[234:235], off
	v_lshl_add_u64 v[234:235], s[14:15], 0, v[130:131]
	s_mov_b32 m0, s42
	s_nop 0
	global_load_lds_dwordx4 v[234:235], off
	s_waitcnt lgkmcnt(8)
	s_barrier
; #define G8_STAGE(bufoff, gbase) do { _Pragma("unroll") for (int _i = 0; _i < 2; ++_i) \
;     __builtin_amdgcn_global_load_lds((const unsigned*)((const char*)(gbase) + voffA[_i]), (LAS unsigned*)(lds + (bufoff) + ldsw + _i * 8192), 16, 0, 0); } while (0)
; #define G8_LDA(dst, b, h) do { _Pragma("unroll") for (int m = 0; m < 4; ++m) _Pragma("unroll") for (int k = 0; k < 2; ++k) dst[m][k] = *(const LAS h16x8*)(lds + G8_SA(b, h) + aoff + m * 2048 + k * 1024); } while (0)
; #define G8_LDB(dst, b, h) do { _Pragma("unroll") for (int n = 0; n < 2; ++n) _Pragma("unroll") for (int k = 0; k < 2; ++k) dst[n][k] = *(const LAS h16x8*)(lds + G8_SB(b, h) + boff + n * 2048 + k * 1024); } while (0)
; #define G8_MMA(ai, bj, At, Bt_) do { __builtin_amdgcn_s_setprio(1); _Pragma("unroll") for (int m = 0; m < 4; ++m) _Pragma("unroll") for (int n = 0; n < 2; ++n) _Pragma("unroll") for (int k = 0; k < 2; ++k) \
;     acc[ai][bj][m][n] = __builtin_amdgcn_mfma_f32_16x16x32_f16(Bt_[n][k], At[m][k], acc[ai][bj][m][n], 0, 0, 0); __builtin_amdgcn_s_setprio(0); } while (0)
; #define G8_WAIT_V(n) asm volatile("s_waitcnt vmcnt(" #n ")" ::: "memory")
; #define G8_WAIT_L(n) asm volatile("s_waitcnt lgkmcnt(" #n ")" ::: "memory")
; #define G8_BAR __builtin_amdgcn_s_barrier()
; #define G8_SCHED __builtin_amdgcn_sched_barrier(0)
; template <class Epi>
; __device__ __forceinline__ void gemm_phase(LAS unsigned char* lds, const h16* A, const h16* Bt, int K, const Order& S, const Epi& E) {
;     ...
;       G8_WAIT_L(8); G8_BAR; G8_WAIT_L(0); G8_MMA(0, 0, At, B0); G8_BAR; G8_SCHED;
;       G8_LDB(B1, 1, 1); G8_STAGE(G8_SB(1, 0), b3);
;       G8_BAR; G8_WAIT_L(0); G8_MMA(0, 1, At, B1); G8_BAR;
;       G8_LDA(At, 1, 1); G8_STAGE(G8_SA(1, 0), a3);
;       G8_BAR; G8_WAIT_L(0); G8_MMA(1, 0, At, B0); G8_BAR; G8_SCHED;
;       G8_STAGE(G8_SB(1, 1), b3 + hstep);
;       G8_WAIT_V(6); G8_BAR; G8_MMA(1, 1, At, B1); G8_BAR;
;     }
;   __device__ __forceinline__ void operator()(const f32x4 (&acc)[2][2][4][2], const g8::Unit& u, int ui, int wr, int wc, int fr, int fq) const {
;     const int hs = u.pn * 4 + wc;
;     int gi = -1;
;     if (hs < 4) gi = 0; else if (hs < 6) gi = 1; else if (hs >= 16 && hs < 20) gi = 2; else if (hs == 22) gi = 4; else if (hs == 24) gi = 5;
	s_waitcnt lgkmcnt(0)
	s_nop 0
	s_waitcnt lgkmcnt(0)
	v_mfma_f32_16x16x32_f16 v[126:129], v[152:155], v[202:205], v[126:129]
	v_mfma_f32_16x16x32_f16 v[122:125], v[182:185], v[202:205], v[122:125]
	v_mfma_f32_16x16x32_f16 v[110:113], v[152:155], v[210:213], v[110:113]
	v_mfma_f32_16x16x32_f16 v[106:109], v[182:185], v[210:213], v[106:109]
	v_mfma_f32_16x16x32_f16 v[94:97], v[152:155], v[218:221], v[94:97]
	v_mfma_f32_16x16x32_f16 v[90:93], v[182:185], v[218:221], v[90:93]
	v_mfma_f32_16x16x32_f16 v[78:81], v[152:155], v[226:229], v[78:81]
	v_mfma_f32_16x16x32_f16 v[74:77], v[182:185], v[226:229], v[74:77]
	v_mfma_f32_16x16x32_f16 v[126:129], v[178:181], v[206:209], v[126:129]
	v_mfma_f32_16x16x32_f16 v[122:125], v[186:189], v[206:209], v[122:125]
	v_mfma_f32_16x16x32_f16 v[110:113], v[178:181], v[214:217], v[110:113]
	v_mfma_f32_16x16x32_f16 v[106:109], v[186:189], v[214:217], v[106:109]
	v_mfma_f32_16x16x32_f16 v[94:97], v[178:181], v[222:225], v[94:97]
	v_mfma_f32_16x16x32_f16 v[90:93], v[186:189], v[222:225], v[90:93]
	v_mfma_f32_16x16x32_f16 v[78:81], v[178:181], v[230:233], v[78:81]
	v_mfma_f32_16x16x32_f16 v[74:77], v[186:189], v[230:233], v[74:77]
	s_nop 0
	s_barrier
	s_mov_b32 m0, s44
	v_lshl_add_u64 v[140:141], v[140:141], 0, s[94:95]
	ds_read_b128 v[234:237], v173
	ds_read_b128 v[238:241], v174
	ds_read_b128 v[242:245], v175
	ds_read_b128 v[246:249], v176
	global_load_lds_dwordx4 v[140:141], off
	v_lshl_add_u64 v[140:141], v[156:157], 0, s[94:95]
	s_mov_b32 m0, s45
	s_nop 0
	global_load_lds_dwordx4 v[140:141], off
	s_barrier
	s_waitcnt lgkmcnt(0)
	s_nop 0
	s_waitcnt lgkmcnt(0)
	v_mfma_f32_16x16x32_f16 v[118:121], v[234:237], v[202:205], v[118:121]
	v_mfma_f32_16x16x32_f16 v[114:117], v[242:245], v[202:205], v[114:117]
	v_mfma_f32_16x16x32_f16 v[102:105], v[234:237], v[210:213], v[102:105]
	v_mfma_f32_16x16x32_f16 v[98:101], v[242:245], v[210:213], v[98:101]
	v_mfma_f32_16x16x32_f16 v[86:89], v[234:237], v[218:221], v[86:89]
	v_mfma_f32_16x16x32_f16 v[82:85], v[242:245], v[218:221], v[82:85]
	v_mfma_f32_16x16x32_f16 v[70:73], v[234:237], v[226:229], v[70:73]
	v_mfma_f32_16x16x32_f16 v[66:69], v[242:245], v[226:229], v[66:69]
	v_mfma_f32_16x16x32_f16 v[118:121], v[238:241], v[206:209], v[118:121]
	v_mfma_f32_16x16x32_f16 v[114:117], v[246:249], v[206:209], v[114:117]
	v_mfma_f32_16x16x32_f16 v[102:105], v[238:241], v[214:217], v[102:105]
	v_mfma_f32_16x16x32_f16 v[98:101], v[246:249], v[214:217], v[98:101]
	v_mfma_f32_16x16x32_f16 v[86:89], v[238:241], v[222:225], v[86:89]
	v_mfma_f32_16x16x32_f16 v[82:85], v[246:249], v[222:225], v[82:85]
	v_mfma_f32_16x16x32_f16 v[70:73], v[238:241], v[230:233], v[70:73]
	v_mfma_f32_16x16x32_f16 v[66:69], v[246:249], v[230:233], v[66:69]
	s_nop 0
	s_mov_b32 m0, s46
	v_lshl_add_u64 v[140:141], v[250:251], 0, s[94:95]
	s_barrier
	ds_read_b128 v[202:205], v159 offset:49152
	ds_read_b128 v[206:209], v159 offset:50176
	ds_read_b128 v[210:213], v159 offset:51200
	ds_read_b128 v[214:217], v159 offset:52224
	ds_read_b128 v[218:221], v159 offset:53248
	ds_read_b128 v[222:225], v159 offset:54272
	ds_read_b128 v[226:229], v159 offset:55296
	ds_read_b128 v[230:233], v159 offset:56320
	global_load_lds_dwordx4 v[140:141], off
	v_lshl_add_u64 v[140:141], v[252:253], 0, s[94:95]
	s_mov_b32 m0, s47
	s_nop 0
	global_load_lds_dwordx4 v[140:141], off
	s_waitcnt vmcnt(10)
	s_barrier
	s_waitcnt lgkmcnt(0)
	s_nop 0
	s_waitcnt lgkmcnt(0)
	v_mfma_f32_16x16x32_f16 v[62:65], v[152:155], v[202:205], v[62:65]
	v_mfma_f32_16x16x32_f16 v[58:61], v[182:185], v[202:205], v[58:61]
	v_mfma_f32_16x16x32_f16 v[46:49], v[152:155], v[210:213], v[46:49]
	v_mfma_f32_16x16x32_f16 v[42:45], v[182:185], v[210:213], v[42:45]
	v_mfma_f32_16x16x32_f16 v[30:33], v[152:155], v[218:221], v[30:33]
	v_mfma_f32_16x16x32_f16 v[26:29], v[182:185], v[218:221], v[26:29]
	v_mfma_f32_16x16x32_f16 v[14:17], v[152:155], v[226:229], v[14:17]
	v_mfma_f32_16x16x32_f16 v[10:13], v[182:185], v[226:229], v[10:13]
	v_mfma_f32_16x16x32_f16 v[62:65], v[178:181], v[206:209], v[62:65]
	v_mfma_f32_16x16x32_f16 v[58:61], v[186:189], v[206:209], v[58:61]
	v_mfma_f32_16x16x32_f16 v[46:49], v[178:181], v[214:217], v[46:49]
	v_mfma_f32_16x16x32_f16 v[42:45], v[186:189], v[214:217], v[42:45]
	v_mfma_f32_16x16x32_f16 v[30:33], v[178:181], v[222:225], v[30:33]
	v_mfma_f32_16x16x32_f16 v[26:29], v[186:189], v[222:225], v[26:29]
	v_mfma_f32_16x16x32_f16 v[14:17], v[178:181], v[230:233], v[14:17]
	v_mfma_f32_16x16x32_f16 v[10:13], v[186:189], v[230:233], v[10:13]
	s_nop 0
	s_barrier
	s_add_u32 s12, s12, 0x40080
	s_addc_u32 s13, s13, 0
	s_mov_b32 m0, s48
	v_lshl_add_u64 v[140:141], s[12:13], 0, v[132:133]
	global_load_lds_dwordx4 v[140:141], off
	v_lshl_add_u64 v[140:141], s[12:13], 0, v[130:131]
	s_mov_b32 m0, s49
	s_nop 0
	global_load_lds_dwordx4 v[140:141], off
	ds_read_b128 v[152:155], v161
	ds_read_b128 v[178:181], v162
	ds_read_b128 v[182:185], v163
	ds_read_b128 v[186:189], v164
	s_waitcnt vmcnt(6)
	s_barrier
	s_nop 0
	v_mfma_f32_16x16x32_f16 v[54:57], v[234:237], v[202:205], v[54:57]
	v_mfma_f32_16x16x32_f16 v[50:53], v[242:245], v[202:205], v[50:53]
	v_mfma_f32_16x16x32_f16 v[38:41], v[234:237], v[210:213], v[38:41]
	v_mfma_f32_16x16x32_f16 v[34:37], v[242:245], v[210:213], v[34:37]
	v_mfma_f32_16x16x32_f16 v[22:25], v[234:237], v[218:221], v[22:25]
	v_mfma_f32_16x16x32_f16 v[18:21], v[242:245], v[218:221], v[18:21]
	v_mfma_f32_16x16x32_f16 v[6:9], v[234:237], v[226:229], v[6:9]
	v_mfma_f32_16x16x32_f16 v[2:5], v[242:245], v[226:229], v[2:5]
	v_mfma_f32_16x16x32_f16 v[54:57], v[238:241], v[206:209], v[54:57]
	v_mfma_f32_16x16x32_f16 v[50:53], v[246:249], v[206:209], v[50:53]
	v_mfma_f32_16x16x32_f16 v[38:41], v[238:241], v[214:217], v[38:41]
	v_mfma_f32_16x16x32_f16 v[34:37], v[246:249], v[214:217], v[34:37]
	v_mfma_f32_16x16x32_f16 v[22:25], v[238:241], v[222:225], v[22:25]
	v_mfma_f32_16x16x32_f16 v[18:21], v[246:249], v[222:225], v[18:21]
	v_mfma_f32_16x16x32_f16 v[6:9], v[238:241], v[230:233], v[6:9]
	v_mfma_f32_16x16x32_f16 v[2:5], v[246:249], v[230:233], v[2:5]
	s_nop 0
	s_add_i32 s54, s54, 2
	s_add_u32 s10, s10, 0x100
	s_addc_u32 s11, s11, 0
	s_add_u32 s27, s27, 0x100
	s_addc_u32 s53, s53, 0
	s_cmp_gt_u32 s54, 13
	s_barrier
	s_cbranch_scc0 .LBB0_195
	s_waitcnt lgkmcnt(0)
	s_setprio 0
	s_lshl_b32 s10, s24, 2
	s_or_b32 s19, s10, s43
	s_cmp_lt_i32 s19, 4
	s_cbranch_scc1 .LBB0_203
	s_cmp_lt_u32 s19, 6
	s_cbranch_scc1 .LBB0_204
	s_cmp_eq_u32 s24, 4
	s_cbranch_scc1 .LBB0_205
	s_cmp_lt_i32 s19, 24
	s_cbranch_scc1 .LBB0_206
	s_cmp_eq_u32 s19, 24
	s_mov_b64 s[10:11], -1
	s_cbranch_scc0 .LBB0_202
	s_mov_b64 s[10:11], 0

; #define G8_STAGE(bufoff, gbase) do { _Pragma("unroll") for (int _i = 0; _i < 2; ++_i) \
;     __builtin_amdgcn_global_load_lds((const unsigned*)((const char*)(gbase) + voffA[_i]), (LAS unsigned*)(lds + (bufoff) + ldsw + _i * 8192), 16, 0, 0); } while (0)
; #define G8_LDA(dst, b, h) do { _Pragma("unroll") for (int m = 0; m < 4; ++m) _Pragma("unroll") for (int k = 0; k < 2; ++k) dst[m][k] = *(const LAS h16x8*)(lds + G8_SA(b, h) + aoff + m * 2048 + k * 1024); } while (0)
; #define G8_LDB(dst, b, h) do { _Pragma("unroll") for (int n = 0; n < 2; ++n) _Pragma("unroll") for (int k = 0; k < 2; ++k) dst[n][k] = *(const LAS h16x8*)(lds + G8_SB(b, h) + boff + n * 2048 + k * 1024); } while (0)
; #define G8_MMA(ai, bj, At, Bt_) do { __builtin_amdgcn_s_setprio(1); _Pragma("unroll") for (int m = 0; m < 4; ++m) _Pragma("unroll") for (int n = 0; n < 2; ++n) _Pragma("unroll") for (int k = 0; k < 2; ++k) \
;     acc[ai][bj][m][n] = __builtin_amdgcn_mfma_f32_16x16x32_f16(Bt_[n][k], At[m][k], acc[ai][bj][m][n], 0, 0, 0); __builtin_amdgcn_s_setprio(0); } while (0)
; #define G8_BAR __builtin_amdgcn_s_barrier()
; template <class Epi>
; __device__ __forceinline__ void gemm_phase(LAS unsigned char* lds, const h16* A, const h16* Bt, int K, const Order& S, const Epi& E) {
;     ...
;   for (;;) {
;     const bool has_next = S.next(ui + 1, nxt);
;     const char* nA = has_next ? (const char*)A + (size_t)nxt.pm * tstep : cA;
;     const char* nB = has_next ? (const char*)Bt + (size_t)nxt.pn * tstep : cB;
;     for (int t = 0; t < nt; t += 2) {
;       const bool last = (t == nt - 2);
;       const char* a1 = cA + (size_t)(t + 1) * kstep;
;       const char* a2 = last ? nA : cA + (size_t)(t + 2) * kstep;
;       const char* b2 = last ? nB : cB + (size_t)(t + 2) * kstep;
;       const char* a3 = a2 + kstep;
;       const char* b3 = b2 + kstep;
;       if (Epi::MID_T >= 0 && t == Epi::MID_T) E.mid(acc, ui, wr, fr);
;       G8_LDB(B0, 0, 0); G8_SCHED; G8_LDA(At, 0, 0); G8_STAGE(G8_SA(1, 1), a1 + hstep);
;       G8_WAIT_L(8); G8_BAR; G8_WAIT_L(0); G8_MMA(0, 0, At, B0); G8_BAR; G8_SCHED;
;     ...
; #pragma unroll
;     for (int a = 0; a < 2; ++a)
; #pragma unroll
;       for (int b = 0; b < 2; ++b)
; #pragma unroll
;         for (int m = 0; m < 4; ++m)
; #pragma unroll
;           for (int n = 0; n < 2; ++n) acc[a][b][m][n] = (f32x4){0.f, 0.f, 0.f, 0.f};
;     cur = nxt; cA = nA; cB = nB; ++ui;
.LBB0_2283:
	s_ashr_i32 s17, s16, 31
	v_cmp_lt_i64_e32 vcc, s[18:19], v[148:149]
	s_lshl_b64 s[18:19], s[16:17], 18
	s_add_u32 s18, s31, s18
	s_addc_u32 s19, s34, s19
	s_and_b64 s[20:21], vcc, exec
	s_cselect_b32 s3, s19, s25
	s_cselect_b32 s17, s18, s24
	s_ashr_i32 s15, s14, 31
	s_lshl_b64 s[20:21], s[14:15], 18
	s_add_u32 s20, s35, s20
	s_addc_u32 s21, s36, s21
	s_and_b64 s[28:29], vcc, exec
	s_cselect_b32 s15, s21, s27
	s_cselect_b32 s23, s20, s26
	s_add_u32 s24, s24, 0x20080
	s_addc_u32 s25, s25, 0
	s_add_u32 s53, s26, 0x100
	v_mov_b32_e32 v6, 0
	s_addc_u32 s54, s27, 0
	s_mov_b32 s55, -2
	v_mov_b32_e32 v7, v6
	v_mov_b32_e32 v8, v6
	v_mov_b32_e32 v9, v6
	v_mov_b32_e32 v2, v6
	s_waitcnt lgkmcnt(0)
	v_mov_b32_e32 v3, v6
	v_mov_b32_e32 v4, v6
	v_mov_b32_e32 v5, v6
	v_mov_b32_e32 v22, v6
	v_mov_b32_e32 v23, v6
	v_mov_b32_e32 v24, v6
	v_mov_b32_e32 v25, v6
	v_mov_b32_e32 v18, v6
	v_mov_b32_e32 v19, v6
	v_mov_b32_e32 v20, v6
	v_mov_b32_e32 v21, v6
	v_mov_b32_e32 v42, v6
	v_mov_b32_e32 v43, v6
	v_mov_b32_e32 v44, v6
	v_mov_b32_e32 v45, v6
	v_mov_b32_e32 v38, v6
	v_mov_b32_e32 v39, v6
	v_mov_b32_e32 v40, v6
	v_mov_b32_e32 v41, v6
	v_mov_b32_e32 v70, v6
	v_mov_b32_e32 v71, v6
	v_mov_b32_e32 v72, v6
	v_mov_b32_e32 v73, v6
	v_mov_b32_e32 v66, v6
	v_mov_b32_e32 v67, v6
	v_mov_b32_e32 v68, v6
	v_mov_b32_e32 v69, v6
	v_mov_b32_e32 v14, v6
	v_mov_b32_e32 v15, v6
	v_mov_b32_e32 v16, v6
	v_mov_b32_e32 v17, v6
	v_mov_b32_e32 v10, v6
	v_mov_b32_e32 v11, v6
	v_mov_b32_e32 v12, v6
	v_mov_b32_e32 v13, v6
	v_mov_b32_e32 v30, v6
	v_mov_b32_e32 v31, v6
	v_mov_b32_e32 v32, v6
	v_mov_b32_e32 v33, v6
	v_mov_b32_e32 v26, v6
	v_mov_b32_e32 v27, v6
	v_mov_b32_e32 v28, v6
	v_mov_b32_e32 v29, v6
	v_mov_b32_e32 v58, v6
	v_mov_b32_e32 v59, v6
	v_mov_b32_e32 v60, v6
	v_mov_b32_e32 v61, v6
	v_mov_b32_e32 v54, v6
	v_mov_b32_e32 v55, v6
	v_mov_b32_e32 v56, v6
	v_mov_b32_e32 v57, v6
	v_mov_b32_e32 v78, v6
	v_mov_b32_e32 v79, v6
	v_mov_b32_e32 v80, v6
	v_mov_b32_e32 v81, v6
	v_mov_b32_e32 v74, v6
	v_mov_b32_e32 v75, v6
	v_mov_b32_e32 v76, v6
	v_mov_b32_e32 v77, v6
	v_mov_b32_e32 v86, v6
	v_mov_b32_e32 v87, v6
	v_mov_b32_e32 v88, v6
	v_mov_b32_e32 v89, v6
	v_mov_b32_e32 v82, v6
	v_mov_b32_e32 v83, v6
	v_mov_b32_e32 v84, v6
	v_mov_b32_e32 v85, v6
	v_mov_b32_e32 v102, v6
	v_mov_b32_e32 v103, v6
	v_mov_b32_e32 v104, v6
	v_mov_b32_e32 v105, v6
	v_mov_b32_e32 v98, v6
	v_mov_b32_e32 v99, v6
	v_mov_b32_e32 v100, v6
	v_mov_b32_e32 v101, v6
	v_mov_b32_e32 v118, v6
	v_mov_b32_e32 v119, v6
	v_mov_b32_e32 v120, v6
	v_mov_b32_e32 v121, v6
	v_mov_b32_e32 v114, v6
	v_mov_b32_e32 v115, v6
	v_mov_b32_e32 v116, v6
	v_mov_b32_e32 v117, v6
	v_mov_b32_e32 v134, v6
	v_mov_b32_e32 v135, v6
	v_mov_b32_e32 v136, v6
	v_mov_b32_e32 v137, v6
	v_mov_b32_e32 v130, v6
	v_mov_b32_e32 v131, v6
	v_mov_b32_e32 v132, v6
	v_mov_b32_e32 v133, v6
	v_mov_b32_e32 v94, v6
	v_mov_b32_e32 v95, v6
	v_mov_b32_e32 v96, v6
	v_mov_b32_e32 v97, v6
	v_mov_b32_e32 v90, v6
	v_mov_b32_e32 v91, v6
	v_mov_b32_e32 v92, v6
	v_mov_b32_e32 v93, v6
	v_mov_b32_e32 v110, v6
	v_mov_b32_e32 v111, v6
	v_mov_b32_e32 v112, v6
	v_mov_b32_e32 v113, v6
	v_mov_b32_e32 v106, v6
	v_mov_b32_e32 v107, v6
	v_mov_b32_e32 v108, v6
	v_mov_b32_e32 v109, v6
	v_mov_b32_e32 v126, v6
	v_mov_b32_e32 v127, v6
	v_mov_b32_e32 v128, v6
	v_mov_b32_e32 v129, v6
	v_mov_b32_e32 v122, v6
	v_mov_b32_e32 v123, v6
	v_mov_b32_e32 v124, v6
	v_mov_b32_e32 v125, v6
	v_mov_b32_e32 v138, v6
	v_mov_b32_e32 v139, v6
	v_mov_b32_e32 v140, v6
	v_mov_b32_e32 v141, v6
	v_mov_b32_e32 v62, v6
	v_mov_b32_e32 v63, v6
	v_mov_b32_e32 v64, v6
	v_mov_b32_e32 v65, v6
	v_readfirstlane_b32 vcc_lo, v145
	s_cmp_lt_u32 vcc_lo, 0x100
	s_cbranch_scc1 .Lgprio_gl
	s_setprio 1
.Lgprio_gl:
.LBB0_2284:
	v_or_b32_e32 v34, 0x10000, v171
	v_add_u32_e32 v46, 0x10400, v171
	v_add_u32_e32 v50, 0x10800, v171
	v_add_u32_e32 v160, 0x10c00, v171
	ds_read_b128 v[34:37], v34
	ds_read_b128 v[46:49], v46
	ds_read_b128 v[50:53], v50
	ds_read_b128 v[160:163], v160
	s_add_u32 s26, s24, 0xfffe0080
	s_addc_u32 s27, s25, -1
	s_cmp_eq_u32 s55, 4
	s_cselect_b32 s29, s3, s27
	s_cselect_b32 s28, s17, s26
	s_cselect_b32 s27, s15, s54
	s_cselect_b32 s26, s23, s53
	v_lshl_add_u64 v[168:169], s[24:25], 0, v[156:157]
	s_add_i32 m0, s37, 0xc000
	ds_read_b128 v[164:167], v170
	ds_read_b128 v[174:177], v170 offset:1024
	ds_read_b128 v[178:181], v170 offset:2048
	ds_read_b128 v[182:185], v170 offset:3072
	ds_read_b128 v[186:189], v170 offset:4096
	ds_read_b128 v[202:205], v170 offset:5120
	ds_read_b128 v[206:209], v170 offset:6144
	ds_read_b128 v[210:213], v170 offset:7168
	global_load_lds_dwordx4 v[168:169], off
	v_lshl_add_u64 v[168:169], s[24:25], 0, v[158:159]
	s_add_i32 m0, s37, 0xe000
	s_nop 0
	global_load_lds_dwordx4 v[168:169], off
	s_waitcnt lgkmcnt(8)
	s_barrier
	s_waitcnt lgkmcnt(0)
	s_nop 0
	s_waitcnt lgkmcnt(0)
	v_mfma_f32_16x16x32_f16 v[62:65], v[34:37], v[164:167], v[62:65]
	v_mfma_f32_16x16x32_f16 v[138:141], v[50:53], v[164:167], v[138:141]
	v_mfma_f32_16x16x32_f16 v[122:125], v[34:37], v[178:181], v[122:125]
	v_mfma_f32_16x16x32_f16 v[126:129], v[50:53], v[178:181], v[126:129]
	v_mfma_f32_16x16x32_f16 v[106:109], v[34:37], v[186:189], v[106:109]
	v_mfma_f32_16x16x32_f16 v[110:113], v[50:53], v[186:189], v[110:113]
	v_mfma_f32_16x16x32_f16 v[90:93], v[34:37], v[206:209], v[90:93]
	v_mfma_f32_16x16x32_f16 v[94:97], v[50:53], v[206:209], v[94:97]
	v_mfma_f32_16x16x32_f16 v[62:65], v[46:49], v[174:177], v[62:65]
	v_mfma_f32_16x16x32_f16 v[138:141], v[160:163], v[174:177], v[138:141]
	v_mfma_f32_16x16x32_f16 v[122:125], v[46:49], v[182:185], v[122:125]
	v_mfma_f32_16x16x32_f16 v[126:129], v[160:163], v[182:185], v[126:129]
	v_mfma_f32_16x16x32_f16 v[106:109], v[46:49], v[202:205], v[106:109]
	v_mfma_f32_16x16x32_f16 v[110:113], v[160:163], v[202:205], v[110:113]
	v_mfma_f32_16x16x32_f16 v[90:93], v[46:49], v[210:213], v[90:93]
	v_mfma_f32_16x16x32_f16 v[94:97], v[160:163], v[210:213], v[94:97]
	s_nop 0
	s_barrier
; #define G8_STAGE(bufoff, gbase) do { _Pragma("unroll") for (int _i = 0; _i < 2; ++_i) \
;     __builtin_amdgcn_global_load_lds((const unsigned*)((const char*)(gbase) + voffA[_i]), (LAS unsigned*)(lds + (bufoff) + ldsw + _i * 8192), 16, 0, 0); } while (0)
; #define G8_LDA(dst, b, h) do { _Pragma("unroll") for (int m = 0; m < 4; ++m) _Pragma("unroll") for (int k = 0; k < 2; ++k) dst[m][k] = *(const LAS h16x8*)(lds + G8_SA(b, h) + aoff + m * 2048 + k * 1024); } while (0)
; #define G8_LDB(dst, b, h) do { _Pragma("unroll") for (int n = 0; n < 2; ++n) _Pragma("unroll") for (int k = 0; k < 2; ++k) dst[n][k] = *(const LAS h16x8*)(lds + G8_SB(b, h) + boff + n * 2048 + k * 1024); } while (0)
; #define G8_MMA(ai, bj, At, Bt_) do { __builtin_amdgcn_s_setprio(1); _Pragma("unroll") for (int m = 0; m < 4; ++m) _Pragma("unroll") for (int n = 0; n < 2; ++n) _Pragma("unroll") for (int k = 0; k < 2; ++k) \
;     acc[ai][bj][m][n] = __builtin_amdgcn_mfma_f32_16x16x32_f16(Bt_[n][k], At[m][k], acc[ai][bj][m][n], 0, 0, 0); __builtin_amdgcn_s_setprio(0); } while (0)
; #define G8_WAIT_V(n) asm volatile("s_waitcnt vmcnt(" #n ")" ::: "memory")
; #define G8_WAIT_L(n) asm volatile("s_waitcnt lgkmcnt(" #n ")" ::: "memory")
; #define G8_BAR __builtin_amdgcn_s_barrier()
; #define G8_SCHED __builtin_amdgcn_sched_barrier(0)
; template <class Epi>
; __device__ __forceinline__ void gemm_phase(LAS unsigned char* lds, const h16* A, const h16* Bt, int K, const Order& S, const Epi& E) {
;     ...
;       G8_LDB(B1, 0, 1); G8_STAGE(G8_SB(0, 0), b2);
;       G8_BAR; G8_WAIT_L(0); G8_MMA(0, 1, At, B1); G8_BAR;
;       G8_LDA(At, 0, 1); G8_STAGE(G8_SA(0, 0), a2);
;       G8_BAR; G8_WAIT_L(0); G8_MMA(1, 0, At, B0); G8_BAR; G8_SCHED;
;       G8_STAGE(G8_SB(0, 1), b2 + hstep);
;       G8_WAIT_V(6); G8_BAR; G8_MMA(1, 1, At, B1); G8_BAR;
;       G8_LDB(B0, 1, 0); G8_SCHED; G8_LDA(At, 1, 0); G8_STAGE(G8_SA(0, 1), a2 + hstep);
;       G8_WAIT_L(8); G8_BAR; G8_WAIT_L(0); G8_MMA(0, 0, At, B0); G8_BAR; G8_SCHED;
	v_or_b32_e32 v168, 0x14000, v171
	v_add_u32_e32 v169, 0x14400, v171
	ds_read_b128 v[214:217], v168
	ds_read_b128 v[218:221], v169
	v_add_u32_e32 v168, 0x14800, v171
	v_add_u32_e32 v169, 0x14c00, v171
	s_mov_b32 m0, s38
	ds_read_b128 v[222:225], v168
	ds_read_b128 v[226:229], v169
	v_lshl_add_u64 v[168:169], s[26:27], 0, v[0:1]
	global_load_lds_dwordx4 v[168:169], off
	v_lshl_add_u64 v[230:231], s[26:27], 0, v[152:153]
	s_mov_b32 m0, s39
	s_nop 0
	global_load_lds_dwordx4 v[230:231], off
	s_barrier
	s_waitcnt lgkmcnt(0)
	s_nop 0
	s_waitcnt lgkmcnt(0)
	v_mfma_f32_16x16x32_f16 v[130:133], v[214:217], v[164:167], v[130:133]
	v_mfma_f32_16x16x32_f16 v[134:137], v[222:225], v[164:167], v[134:137]
	v_mfma_f32_16x16x32_f16 v[114:117], v[214:217], v[178:181], v[114:117]
	v_mfma_f32_16x16x32_f16 v[118:121], v[222:225], v[178:181], v[118:121]
	v_mfma_f32_16x16x32_f16 v[98:101], v[214:217], v[186:189], v[98:101]
	v_mfma_f32_16x16x32_f16 v[102:105], v[222:225], v[186:189], v[102:105]
	v_mfma_f32_16x16x32_f16 v[82:85], v[214:217], v[206:209], v[82:85]
	v_mfma_f32_16x16x32_f16 v[86:89], v[222:225], v[206:209], v[86:89]
	v_mfma_f32_16x16x32_f16 v[130:133], v[218:221], v[174:177], v[130:133]
	v_mfma_f32_16x16x32_f16 v[134:137], v[226:229], v[174:177], v[134:137]
	v_mfma_f32_16x16x32_f16 v[114:117], v[218:221], v[182:185], v[114:117]
	v_mfma_f32_16x16x32_f16 v[118:121], v[226:229], v[182:185], v[118:121]
	v_mfma_f32_16x16x32_f16 v[98:101], v[218:221], v[202:205], v[98:101]
	v_mfma_f32_16x16x32_f16 v[102:105], v[226:229], v[202:205], v[102:105]
	v_mfma_f32_16x16x32_f16 v[82:85], v[218:221], v[210:213], v[82:85]
	v_mfma_f32_16x16x32_f16 v[86:89], v[226:229], v[210:213], v[86:89]
	s_nop 0
	s_mov_b32 m0, s37
	v_lshl_add_u64 v[232:233], s[28:29], 0, v[0:1]
	s_barrier
	ds_read_b128 v[164:167], v170 offset:16384
	ds_read_b128 v[174:177], v170 offset:17408
	ds_read_b128 v[178:181], v170 offset:18432
	ds_read_b128 v[182:185], v170 offset:19456
	ds_read_b128 v[186:189], v170 offset:20480
	ds_read_b128 v[202:205], v170 offset:21504
	ds_read_b128 v[206:209], v170 offset:22528
	ds_read_b128 v[210:213], v170 offset:23552
	global_load_lds_dwordx4 v[232:233], off
	v_lshl_add_u64 v[234:235], s[28:29], 0, v[152:153]
	s_mov_b32 m0, s40
	s_nop 0
	global_load_lds_dwordx4 v[234:235], off
	s_barrier
	s_waitcnt lgkmcnt(0)
	s_nop 0
	s_waitcnt lgkmcnt(0)
	v_mfma_f32_16x16x32_f16 v[74:77], v[34:37], v[164:167], v[74:77]
	v_mfma_f32_16x16x32_f16 v[78:81], v[50:53], v[164:167], v[78:81]
	v_mfma_f32_16x16x32_f16 v[54:57], v[34:37], v[178:181], v[54:57]
	v_mfma_f32_16x16x32_f16 v[58:61], v[50:53], v[178:181], v[58:61]
	v_mfma_f32_16x16x32_f16 v[26:29], v[34:37], v[186:189], v[26:29]
	v_mfma_f32_16x16x32_f16 v[30:33], v[50:53], v[186:189], v[30:33]
	v_mfma_f32_16x16x32_f16 v[10:13], v[34:37], v[206:209], v[10:13]
	v_mfma_f32_16x16x32_f16 v[14:17], v[50:53], v[206:209], v[14:17]
	v_mfma_f32_16x16x32_f16 v[74:77], v[46:49], v[174:177], v[74:77]
	v_mfma_f32_16x16x32_f16 v[78:81], v[160:163], v[174:177], v[78:81]
	v_mfma_f32_16x16x32_f16 v[54:57], v[46:49], v[182:185], v[54:57]
	v_mfma_f32_16x16x32_f16 v[58:61], v[160:163], v[182:185], v[58:61]
	v_mfma_f32_16x16x32_f16 v[26:29], v[46:49], v[202:205], v[26:29]
	v_mfma_f32_16x16x32_f16 v[30:33], v[160:163], v[202:205], v[30:33]
	v_mfma_f32_16x16x32_f16 v[10:13], v[46:49], v[210:213], v[10:13]
	v_mfma_f32_16x16x32_f16 v[14:17], v[160:163], v[210:213], v[14:17]
	s_nop 0
	s_barrier
	s_add_u32 s56, s26, 0x20000
	s_addc_u32 s57, s27, 0
	s_mov_b32 m0, s41
	v_lshl_add_u64 v[34:35], s[56:57], 0, v[0:1]
	global_load_lds_dwordx4 v[34:35], off
	v_lshl_add_u64 v[34:35], s[56:57], 0, v[152:153]
	s_mov_b32 m0, s42
	s_nop 0
	global_load_lds_dwordx4 v[34:35], off
	s_waitcnt vmcnt(6)
	s_barrier
	s_nop 0
	v_mfma_f32_16x16x32_f16 v[38:41], v[214:217], v[178:181], v[38:41]
	v_mfma_f32_16x16x32_f16 v[42:45], v[222:225], v[178:181], v[42:45]
	v_mfma_f32_16x16x32_f16 v[18:21], v[214:217], v[186:189], v[18:21]
	v_mfma_f32_16x16x32_f16 v[22:25], v[222:225], v[186:189], v[22:25]
	v_mfma_f32_16x16x32_f16 v[2:5], v[214:217], v[206:209], v[2:5]
	v_mfma_f32_16x16x32_f16 v[6:9], v[222:225], v[206:209], v[6:9]
	v_mfma_f32_16x16x32_f16 v[34:37], v[214:217], v[164:167], v[66:69]
	v_mfma_f32_16x16x32_f16 v[46:49], v[222:225], v[164:167], v[70:73]
	v_mfma_f32_16x16x32_f16 v[38:41], v[218:221], v[182:185], v[38:41]
	v_mfma_f32_16x16x32_f16 v[42:45], v[226:229], v[182:185], v[42:45]
	v_mfma_f32_16x16x32_f16 v[18:21], v[218:221], v[202:205], v[18:21]
	v_mfma_f32_16x16x32_f16 v[22:25], v[226:229], v[202:205], v[22:25]
	v_mfma_f32_16x16x32_f16 v[2:5], v[218:221], v[210:213], v[2:5]
	v_mfma_f32_16x16x32_f16 v[6:9], v[226:229], v[210:213], v[6:9]
	v_mfma_f32_16x16x32_f16 v[34:37], v[218:221], v[174:177], v[34:37]
	v_mfma_f32_16x16x32_f16 v[46:49], v[226:229], v[174:177], v[46:49]
	s_nop 0
	v_or_b32_e32 v50, 0x18000, v171
	v_add_u32_e32 v66, 0x18400, v171
	v_add_u32_e32 v70, 0x18800, v171
	v_add_u32_e32 v160, 0x18c00, v171
	s_barrier
	ds_read_b128 v[50:53], v50
	ds_read_b128 v[66:69], v66
	ds_read_b128 v[70:73], v70
	ds_read_b128 v[160:163], v160
	s_add_u32 s28, s28, 0x20000
	s_addc_u32 s29, s29, 0
	s_mov_b32 m0, s43
	v_lshl_add_u64 v[214:215], s[28:29], 0, v[0:1]
	ds_read_b128 v[164:167], v170 offset:32768
	ds_read_b128 v[174:177], v170 offset:33792
	ds_read_b128 v[178:181], v170 offset:34816
	ds_read_b128 v[182:185], v170 offset:35840
	ds_read_b128 v[186:189], v170 offset:36864
	ds_read_b128 v[202:205], v170 offset:37888
	ds_read_b128 v[206:209], v170 offset:38912
	ds_read_b128 v[210:213], v170 offset:39936
	global_load_lds_dwordx4 v[214:215], off
	v_lshl_add_u64 v[214:215], s[28:29], 0, v[152:153]
	s_mov_b32 m0, s44
	s_nop 0
	global_load_lds_dwordx4 v[214:215], off
	s_waitcnt lgkmcnt(8)
	s_barrier
; #define G8_STAGE(bufoff, gbase) do { _Pragma("unroll") for (int _i = 0; _i < 2; ++_i) \
;     __builtin_amdgcn_global_load_lds((const unsigned*)((const char*)(gbase) + voffA[_i]), (LAS unsigned*)(lds + (bufoff) + ldsw + _i * 8192), 16, 0, 0); } while (0)
; #define G8_LDA(dst, b, h) do { _Pragma("unroll") for (int m = 0; m < 4; ++m) _Pragma("unroll") for (int k = 0; k < 2; ++k) dst[m][k] = *(const LAS h16x8*)(lds + G8_SA(b, h) + aoff + m * 2048 + k * 1024); } while (0)
; #define G8_LDB(dst, b, h) do { _Pragma("unroll") for (int n = 0; n < 2; ++n) _Pragma("unroll") for (int k = 0; k < 2; ++k) dst[n][k] = *(const LAS h16x8*)(lds + G8_SB(b, h) + boff + n * 2048 + k * 1024); } while (0)
; #define G8_MMA(ai, bj, At, Bt_) do { __builtin_amdgcn_s_setprio(1); _Pragma("unroll") for (int m = 0; m < 4; ++m) _Pragma("unroll") for (int n = 0; n < 2; ++n) _Pragma("unroll") for (int k = 0; k < 2; ++k) \
;     acc[ai][bj][m][n] = __builtin_amdgcn_mfma_f32_16x16x32_f16(Bt_[n][k], At[m][k], acc[ai][bj][m][n], 0, 0, 0); __builtin_amdgcn_s_setprio(0); } while (0)
; #define G8_WAIT_V(n) asm volatile("s_waitcnt vmcnt(" #n ")" ::: "memory")
; #define G8_WAIT_L(n) asm volatile("s_waitcnt lgkmcnt(" #n ")" ::: "memory")
; #define G8_BAR __builtin_amdgcn_s_barrier()
; #define G8_SCHED __builtin_amdgcn_sched_barrier(0)
; template <class Epi>
; __device__ __forceinline__ void gemm_phase(LAS unsigned char* lds, const h16* A, const h16* Bt, int K, const Order& S, const Epi& E) {
;     ...
;       G8_WAIT_L(8); G8_BAR; G8_WAIT_L(0); G8_MMA(0, 0, At, B0); G8_BAR; G8_SCHED;
;       G8_LDB(B1, 1, 1); G8_STAGE(G8_SB(1, 0), b3);
;       G8_BAR; G8_WAIT_L(0); G8_MMA(0, 1, At, B1); G8_BAR;
;       G8_LDA(At, 1, 1); G8_STAGE(G8_SA(1, 0), a3);
;       G8_BAR; G8_WAIT_L(0); G8_MMA(1, 0, At, B0); G8_BAR; G8_SCHED;
;       G8_STAGE(G8_SB(1, 1), b3 + hstep);
;       G8_WAIT_V(6); G8_BAR; G8_MMA(1, 1, At, B1); G8_BAR;
	s_waitcnt lgkmcnt(0)
	s_nop 0
	s_waitcnt lgkmcnt(0)
	v_mfma_f32_16x16x32_f16 v[62:65], v[50:53], v[164:167], v[62:65]
	v_mfma_f32_16x16x32_f16 v[138:141], v[70:73], v[164:167], v[138:141]
	v_mfma_f32_16x16x32_f16 v[122:125], v[50:53], v[178:181], v[122:125]
	v_mfma_f32_16x16x32_f16 v[126:129], v[70:73], v[178:181], v[126:129]
	v_mfma_f32_16x16x32_f16 v[106:109], v[50:53], v[186:189], v[106:109]
	v_mfma_f32_16x16x32_f16 v[110:113], v[70:73], v[186:189], v[110:113]
	v_mfma_f32_16x16x32_f16 v[90:93], v[50:53], v[206:209], v[90:93]
	v_mfma_f32_16x16x32_f16 v[94:97], v[70:73], v[206:209], v[94:97]
	v_mfma_f32_16x16x32_f16 v[62:65], v[66:69], v[174:177], v[62:65]
	v_mfma_f32_16x16x32_f16 v[138:141], v[160:163], v[174:177], v[138:141]
	v_mfma_f32_16x16x32_f16 v[122:125], v[66:69], v[182:185], v[122:125]
	v_mfma_f32_16x16x32_f16 v[126:129], v[160:163], v[182:185], v[126:129]
	v_mfma_f32_16x16x32_f16 v[106:109], v[66:69], v[202:205], v[106:109]
	v_mfma_f32_16x16x32_f16 v[110:113], v[160:163], v[202:205], v[110:113]
	v_mfma_f32_16x16x32_f16 v[90:93], v[66:69], v[210:213], v[90:93]
	v_mfma_f32_16x16x32_f16 v[94:97], v[160:163], v[210:213], v[94:97]
	s_nop 0
	s_barrier
	v_or_b32_e32 v173, 0x1c000, v171
	s_mov_b32 m0, s46
	v_add_u32_e32 v195, 0x1c400, v171
	ds_read_b128 v[214:217], v173
	ds_read_b128 v[218:221], v195
	v_add_u32_e32 v173, 0x1c800, v171
	v_lshl_add_u64 v[168:169], v[168:169], 0, s[94:95]
	v_add_u32_e32 v195, 0x1cc00, v171
	ds_read_b128 v[222:225], v173
	ds_read_b128 v[226:229], v195
	global_load_lds_dwordx4 v[168:169], off
	v_lshl_add_u64 v[168:169], v[230:231], 0, s[94:95]
	s_mov_b32 m0, s47
	s_nop 0
	global_load_lds_dwordx4 v[168:169], off
	s_barrier
	s_waitcnt lgkmcnt(0)
	s_nop 0
	s_waitcnt lgkmcnt(0)
	v_mfma_f32_16x16x32_f16 v[130:133], v[214:217], v[164:167], v[130:133]
	v_mfma_f32_16x16x32_f16 v[134:137], v[222:225], v[164:167], v[134:137]
	v_mfma_f32_16x16x32_f16 v[114:117], v[214:217], v[178:181], v[114:117]
	v_mfma_f32_16x16x32_f16 v[118:121], v[222:225], v[178:181], v[118:121]
	v_mfma_f32_16x16x32_f16 v[98:101], v[214:217], v[186:189], v[98:101]
	v_mfma_f32_16x16x32_f16 v[102:105], v[222:225], v[186:189], v[102:105]
	v_mfma_f32_16x16x32_f16 v[82:85], v[214:217], v[206:209], v[82:85]
	v_mfma_f32_16x16x32_f16 v[86:89], v[222:225], v[206:209], v[86:89]
	v_mfma_f32_16x16x32_f16 v[130:133], v[218:221], v[174:177], v[130:133]
	v_mfma_f32_16x16x32_f16 v[134:137], v[226:229], v[174:177], v[134:137]
	v_mfma_f32_16x16x32_f16 v[114:117], v[218:221], v[182:185], v[114:117]
	v_mfma_f32_16x16x32_f16 v[118:121], v[226:229], v[182:185], v[118:121]
	v_mfma_f32_16x16x32_f16 v[98:101], v[218:221], v[202:205], v[98:101]
	v_mfma_f32_16x16x32_f16 v[102:105], v[226:229], v[202:205], v[102:105]
	v_mfma_f32_16x16x32_f16 v[82:85], v[218:221], v[210:213], v[82:85]
	v_mfma_f32_16x16x32_f16 v[86:89], v[226:229], v[210:213], v[86:89]
	s_nop 0
	s_mov_b32 m0, s48
	v_lshl_add_u64 v[168:169], v[232:233], 0, s[94:95]
	s_barrier
	ds_read_b128 v[164:167], v170 offset:49152
	ds_read_b128 v[174:177], v170 offset:50176
	ds_read_b128 v[178:181], v170 offset:51200
	ds_read_b128 v[182:185], v170 offset:52224
	ds_read_b128 v[186:189], v170 offset:53248
	ds_read_b128 v[202:205], v170 offset:54272
	ds_read_b128 v[206:209], v170 offset:55296
	ds_read_b128 v[210:213], v170 offset:56320
	global_load_lds_dwordx4 v[168:169], off
	v_lshl_add_u64 v[168:169], v[234:235], 0, s[94:95]
	s_mov_b32 m0, s49
	s_nop 0
	global_load_lds_dwordx4 v[168:169], off
	s_barrier
	s_waitcnt lgkmcnt(0)
	s_nop 0
	s_waitcnt lgkmcnt(0)
	v_mfma_f32_16x16x32_f16 v[74:77], v[50:53], v[164:167], v[74:77]
	v_mfma_f32_16x16x32_f16 v[78:81], v[70:73], v[164:167], v[78:81]
	v_mfma_f32_16x16x32_f16 v[54:57], v[50:53], v[178:181], v[54:57]
	v_mfma_f32_16x16x32_f16 v[58:61], v[70:73], v[178:181], v[58:61]
	v_mfma_f32_16x16x32_f16 v[26:29], v[50:53], v[186:189], v[26:29]
	v_mfma_f32_16x16x32_f16 v[30:33], v[70:73], v[186:189], v[30:33]
	v_mfma_f32_16x16x32_f16 v[10:13], v[50:53], v[206:209], v[10:13]
	v_mfma_f32_16x16x32_f16 v[14:17], v[70:73], v[206:209], v[14:17]
	v_mfma_f32_16x16x32_f16 v[74:77], v[66:69], v[174:177], v[74:77]
	v_mfma_f32_16x16x32_f16 v[78:81], v[160:163], v[174:177], v[78:81]
	v_mfma_f32_16x16x32_f16 v[54:57], v[66:69], v[182:185], v[54:57]
	v_mfma_f32_16x16x32_f16 v[58:61], v[160:163], v[182:185], v[58:61]
	v_mfma_f32_16x16x32_f16 v[26:29], v[66:69], v[202:205], v[26:29]
	v_mfma_f32_16x16x32_f16 v[30:33], v[160:163], v[202:205], v[30:33]
	v_mfma_f32_16x16x32_f16 v[10:13], v[66:69], v[210:213], v[10:13]
	v_mfma_f32_16x16x32_f16 v[14:17], v[160:163], v[210:213], v[14:17]
	s_nop 0
	s_barrier
	s_add_u32 s26, s26, 0x20080
	s_addc_u32 s27, s27, 0
	s_mov_b32 m0, s50
	v_lshl_add_u64 v[50:51], s[26:27], 0, v[0:1]
	global_load_lds_dwordx4 v[50:51], off
	v_lshl_add_u64 v[50:51], s[26:27], 0, v[152:153]
	s_mov_b32 m0, s51
	s_nop 0
	global_load_lds_dwordx4 v[50:51], off
	s_waitcnt vmcnt(6)
	s_barrier
	s_nop 0
	v_mfma_f32_16x16x32_f16 v[34:37], v[214:217], v[164:167], v[34:37]
	v_mfma_f32_16x16x32_f16 v[66:69], v[218:221], v[174:177], v[34:37]
	v_mfma_f32_16x16x32_f16 v[34:37], v[222:225], v[164:167], v[46:49]
	v_mfma_f32_16x16x32_f16 v[70:73], v[226:229], v[174:177], v[34:37]
	v_mfma_f32_16x16x32_f16 v[34:37], v[214:217], v[178:181], v[38:41]
	v_mfma_f32_16x16x32_f16 v[38:41], v[218:221], v[182:185], v[34:37]
	v_mfma_f32_16x16x32_f16 v[34:37], v[222:225], v[178:181], v[42:45]
	v_mfma_f32_16x16x32_f16 v[18:21], v[214:217], v[186:189], v[18:21]
	v_mfma_f32_16x16x32_f16 v[22:25], v[222:225], v[186:189], v[22:25]
	v_mfma_f32_16x16x32_f16 v[2:5], v[214:217], v[206:209], v[2:5]
	v_mfma_f32_16x16x32_f16 v[6:9], v[222:225], v[206:209], v[6:9]
	v_mfma_f32_16x16x32_f16 v[42:45], v[226:229], v[182:185], v[34:37]
	v_mfma_f32_16x16x32_f16 v[18:21], v[218:221], v[202:205], v[18:21]
	v_mfma_f32_16x16x32_f16 v[22:25], v[226:229], v[202:205], v[22:25]
	v_mfma_f32_16x16x32_f16 v[2:5], v[218:221], v[210:213], v[2:5]
	v_mfma_f32_16x16x32_f16 v[6:9], v[226:229], v[210:213], v[6:9]
	s_nop 0
	s_add_i32 s55, s55, 2
	s_add_u32 s24, s24, 0x100
	s_addc_u32 s25, s25, 0
	s_add_u32 s53, s53, 0x100
	s_addc_u32 s54, s54, 0
	s_cmp_gt_u32 s55, 5
	s_barrier
; __device__ __forceinline__ float xor16(float v) { return __int_as_float(__builtin_amdgcn_ds_swizzle(__float_as_int(v), 0x401F)); }
; __device__ __forceinline__ float sigmoidf(float x) { return 1.f / (1.f + __expf(-x)); }
;   __device__ __forceinline__ void operator()(const f32x4 (&acc)[2][2][4][2], const g8::Unit& u, int ui, int wr, int wc, int fr, int fq) const {
;     const int ocb = 128 * u.pn + 16 * wc + 4 * fq;
;     float4 ba[2], bb[2];
; #pragma unroll
;     for (int bj = 0; bj < 2; ++bj) { ba[bj] = *(const float4*)(gb + ocb + 64 * bj); bb[bj] = *(const float4*)(gb + 512 + ocb + 64 * bj); }
; #pragma unroll
;     for (int ai = 0; ai < 2; ++ai)
; #pragma unroll
;       for (int m = 0; m < 4; ++m) {
;         const size_t row = (size_t)u.pm * 256 + 128 * ai + 64 * wr + 16 * m + fr;
;         float ss = 0.f;
; #pragma unroll
;         for (int bj = 0; bj < 2; ++bj) {
;           const f32x4 a = acc[ai][bj][m][0], b = acc[ai][bj][m][1];
;           float o0 = (a[0] + ba[bj].x) * sigmoidf(b[0] + bb[bj].x);
;           float o1 = (a[1] + ba[bj].y) * sigmoidf(b[1] + bb[bj].y);
;           float o2 = (a[2] + ba[bj].z) * sigmoidf(b[2] + bb[bj].z);
;           float o3 = (a[3] + ba[bj].w) * sigmoidf(b[3] + bb[bj].w);
;           *(h16x4*)(OB + row * 1024 + ocb + 64 * bj) = pack4(o0, o1, o2, o3);
;           ss += o0 * o0 + o1 * o1 + o2 * o2 + o3 * o3;
;         }
;         ss += xor16(ss);
;         ss += __shfl_xor(ss, 32);
;         if (fq == 0) ssqb[row * 16 + u.pn * 4 + wc] = ss;
;       }
	s_cbranch_scc0 .LBB0_2284
	s_setprio 0
	v_lshl_or_b32 v160, s2, 7, v172
	v_ashrrev_i32_e32 v161, 31, v160
	v_lshl_add_u64 v[166:167], v[160:161], 2, s[12:13]
	global_load_dwordx4 v[46:49], v[166:167], off offset:2048
	global_load_dwordx4 v[34:37], v[166:167], off offset:2304
	v_and_b32_e32 v51, 64, v199
	v_xor_b32_e32 v50, 32, v199
	v_add_u32_e32 v51, 64, v51
	v_cmp_lt_i32_e32 vcc, v50, v51
	s_ashr_i32 s23, s22, 31
	s_lshl_b64 s[22:23], s[22:23], 8
	v_cndmask_b32_e32 v50, v199, v50, vcc
	v_lshlrev_b32_e32 v173, 2, v50
	v_lshl_add_u64 v[162:163], s[22:23], 0, v[154:155]
	s_lshl_b32 s22, s2, 2
	v_lshlrev_b64 v[164:165], 11, v[162:163]
	s_ashr_i32 s23, s22, 31
	s_waitcnt vmcnt(0)
	v_add_f32_e32 v50, v138, v46
	v_mul_f32_e32 v50, 0xbfb8aa3b, v50
	v_exp_f32_e32 v138, v50
	global_load_dwordx4 v[50:53], v[166:167], off
	v_add_f32_e32 v139, v139, v47
	v_mul_f32_e32 v139, 0xbfb8aa3b, v139
	v_exp_f32_e32 v139, v139
	v_add_f32_e32 v140, v140, v48
	v_add_f32_e32 v141, v141, v49
	v_mul_f32_e32 v140, 0xbfb8aa3b, v140
	v_pk_add_f32 v[138:139], v[138:139], 1.0 op_sel_hi:[1,0]
	v_mul_f32_e32 v141, 0xbfb8aa3b, v141
	v_div_scale_f32 v168, s[2:3], v139, v139, 1.0
	v_rcp_f32_e32 v169, v168
	v_exp_f32_e32 v140, v140
	v_exp_f32_e32 v141, v141
	v_add_f32_e32 v135, v135, v35
	v_fma_f32 v174, -v168, v169, 1.0
	v_fmac_f32_e32 v169, v174, v169
	v_div_scale_f32 v174, vcc, 1.0, v139, 1.0
	v_mul_f32_e32 v175, v174, v169
	v_fma_f32 v176, -v168, v175, v174
	v_fmac_f32_e32 v175, v176, v169
	v_fma_f32 v168, -v168, v175, v174
	v_div_fmas_f32 v168, v168, v169, v175
	v_div_fixup_f32 v139, v168, v139, 1.0
	v_div_scale_f32 v168, s[2:3], v138, v138, 1.0
	v_rcp_f32_e32 v169, v168
	v_mul_f32_e32 v135, 0xbfb8aa3b, v135
	v_exp_f32_e32 v135, v135
	v_add_f32_e32 v136, v136, v36
	v_fma_f32 v174, -v168, v169, 1.0
	v_fmac_f32_e32 v169, v174, v169
	v_div_scale_f32 v174, vcc, 1.0, v138, 1.0
	v_mul_f32_e32 v175, v174, v169
	v_fma_f32 v176, -v168, v175, v174
	v_fmac_f32_e32 v175, v176, v169
	v_fma_f32 v168, -v168, v175, v174
	v_div_fmas_f32 v168, v168, v169, v175
	v_div_fixup_f32 v138, v168, v138, 1.0
	v_add_f32_e32 v137, v137, v37
	v_mul_f32_e32 v136, 0xbfb8aa3b, v136
	v_mul_f32_e32 v137, 0xbfb8aa3b, v137
	v_exp_f32_e32 v136, v136
	v_exp_f32_e32 v137, v137
	s_waitcnt vmcnt(0)
	v_pk_add_f32 v[62:63], v[62:63], v[50:51]
	s_nop 0
	v_pk_mul_f32 v[62:63], v[62:63], v[138:139]
	v_pk_add_f32 v[138:139], v[140:141], 1.0 op_sel_hi:[1,0]
	v_cvt_pk_f16_f32 v168, v62, v63
	v_div_scale_f32 v140, s[2:3], v139, v139, 1.0
	v_rcp_f32_e32 v141, v140
	v_pk_add_f32 v[64:65], v[64:65], v[52:53]
	v_pk_add_f32 v[136:137], v[136:137], 1.0 op_sel_hi:[1,0]
	v_fma_f32 v169, -v140, v141, 1.0
	v_fmac_f32_e32 v141, v169, v141
	v_div_scale_f32 v169, vcc, 1.0, v139, 1.0
	v_mul_f32_e32 v174, v169, v141
	v_fma_f32 v175, -v140, v174, v169
	v_fmac_f32_e32 v174, v175, v141
	v_fma_f32 v140, -v140, v174, v169
	v_div_fmas_f32 v140, v140, v141, v174
	v_div_fixup_f32 v139, v140, v139, 1.0
	v_div_scale_f32 v140, s[2:3], v138, v138, 1.0
	v_rcp_f32_e32 v141, v140
	s_nop 0
	v_fma_f32 v169, -v140, v141, 1.0
	v_fmac_f32_e32 v141, v169, v141
	v_div_scale_f32 v169, vcc, 1.0, v138, 1.0
	v_mul_f32_e32 v174, v169, v141
	v_fma_f32 v175, -v140, v174, v169
	v_fmac_f32_e32 v174, v175, v141
	v_fma_f32 v140, -v140, v174, v169
	v_div_fmas_f32 v140, v140, v141, v174
	v_div_fixup_f32 v138, v140, v138, 1.0
	v_pk_mul_f32 v[140:141], v[62:63], v[62:63]
	v_add_f32_e32 v62, v134, v34
	v_pk_mul_f32 v[64:65], v[64:65], v[138:139]
	v_lshl_add_u64 v[138:139], s[0:1], 0, v[164:165]
	v_mul_f32_e32 v62, 0xbfb8aa3b, v62
	v_cvt_pk_f16_f32 v169, v64, v65
	v_lshl_add_u64 v[164:165], v[160:161], 1, v[138:139]
	v_pk_mul_f32 v[138:139], v[64:65], v[64:65]
	v_exp_f32_e32 v134, v62
	global_load_dwordx4 v[62:65], v[166:167], off offset:256
	v_pk_add_f32 v[134:135], v[134:135], 1.0 op_sel_hi:[1,0]
	s_nop 0
	v_div_scale_f32 v166, s[2:3], v135, v135, 1.0
	v_rcp_f32_e32 v167, v166
	global_store_dwordx2 v[164:165], v[168:169], off
	v_fma_f32 v168, -v166, v167, 1.0
	v_fmac_f32_e32 v167, v168, v167
	v_div_scale_f32 v168, vcc, 1.0, v135, 1.0
	v_mul_f32_e32 v169, v168, v167
	v_fma_f32 v174, -v166, v169, v168
	v_fmac_f32_e32 v169, v174, v167
	v_fma_f32 v166, -v166, v169, v168
	v_div_fmas_f32 v166, v166, v167, v169
	v_div_fixup_f32 v135, v166, v135, 1.0
	v_div_scale_f32 v166, s[2:3], v134, v134, 1.0
	v_rcp_f32_e32 v167, v166
	s_waitcnt vmcnt(0)
	v_pk_add_f32 v[130:131], v[130:131], v[62:63]
	v_fma_f32 v168, -v166, v167, 1.0
	v_fmac_f32_e32 v167, v168, v167
	v_div_scale_f32 v168, vcc, 1.0, v134, 1.0
	v_mul_f32_e32 v169, v168, v167
	v_fma_f32 v174, -v166, v169, v168
	v_fmac_f32_e32 v169, v174, v167
	v_fma_f32 v166, -v166, v169, v168
	v_div_fmas_f32 v166, v166, v167, v169
	v_div_fixup_f32 v134, v166, v134, 1.0
	v_pk_mul_f32 v[130:131], v[130:131], v[134:135]
	v_div_scale_f32 v135, s[2:3], v137, v137, 1.0
	v_rcp_f32_e32 v166, v135
	v_pk_add_f32 v[132:133], v[132:133], v[64:65]
	v_cvt_pk_f16_f32 v134, v130, v131
	v_pk_mul_f32 v[130:131], v[130:131], v[130:131]
	v_fma_f32 v167, -v135, v166, 1.0
	v_fmac_f32_e32 v166, v167, v166
	v_div_scale_f32 v167, vcc, 1.0, v137, 1.0
	v_mul_f32_e32 v168, v167, v166
	v_fma_f32 v169, -v135, v168, v167
	v_fmac_f32_e32 v168, v169, v166
	v_fma_f32 v135, -v135, v168, v167
	v_div_fmas_f32 v135, v135, v166, v168
	v_div_fixup_f32 v137, v135, v137, 1.0
	v_div_scale_f32 v135, s[2:3], v136, v136, 1.0
	v_rcp_f32_e32 v166, v135
	v_add_f32_e32 v130, v130, v131
	v_add_f32_e32 v131, v140, v141
	v_add_f32_e32 v131, v138, v131
	v_fma_f32 v167, -v135, v166, 1.0
	v_fmac_f32_e32 v166, v167, v166
	v_div_scale_f32 v167, vcc, 1.0, v136, 1.0
	v_mul_f32_e32 v168, v167, v166
	v_fma_f32 v169, -v135, v168, v167
	v_fmac_f32_e32 v168, v169, v166
	v_fma_f32 v135, -v135, v168, v167
	v_div_fmas_f32 v135, v135, v166, v168
	v_div_fixup_f32 v136, v135, v136, 1.0
	v_pk_mul_f32 v[132:133], v[132:133], v[136:137]
	v_add_f32_e32 v131, v139, v131
	v_cvt_pk_f16_f32 v135, v132, v133
	v_pk_mul_f32 v[132:133], v[132:133], v[132:133]
	global_store_dwordx2 v[164:165], v[134:135], off offset:128
	v_add_f32_e32 v130, v132, v130
	v_add_f32_e32 v130, v133, v130
	v_add_f32_e32 v130, v131, v130
	v_mov_b32_e32 v131, v130
	s_nop 1
	v_permlane16_swap_b32_e32 v131, v130
	s_waitcnt lgkmcnt(0)
	v_add_f32_e32 v130, v130, v131
	v_mov_b32_e32 v131, v130
	s_nop 1
	v_permlane32_swap_b32_e32 v131, v130
	s_and_saveexec_b64 s[24:25], s[6:7]
	s_cbranch_execz .LBB0_2287
	s_waitcnt lgkmcnt(0)
	v_add_f32_e32 v132, v130, v131
	v_lshlrev_b64 v[130:131], 6, v[162:163]
	v_lshl_add_u64 v[130:131], s[10:11], 0, v[130:131]
	v_lshl_add_u64 v[130:131], s[22:23], 2, v[130:131]
	s_lshl_b32 s92, s45, 2
	v_lshl_add_u64 v[130:131], v[130:131], 0, s[92:93]
	global_store_dword v[130:131], v132, off

; #define G8_STAGE(bufoff, gbase) do { _Pragma("unroll") for (int _i = 0; _i < 2; ++_i) \
;     __builtin_amdgcn_global_load_lds((const unsigned*)((const char*)(gbase) + voffA[_i]), (LAS unsigned*)(lds + (bufoff) + ldsw + _i * 8192), 16, 0, 0); } while (0)
; #define G8_LDA(dst, b, h) do { _Pragma("unroll") for (int m = 0; m < 4; ++m) _Pragma("unroll") for (int k = 0; k < 2; ++k) dst[m][k] = *(const LAS h16x8*)(lds + G8_SA(b, h) + aoff + m * 2048 + k * 1024); } while (0)
; #define G8_LDB(dst, b, h) do { _Pragma("unroll") for (int n = 0; n < 2; ++n) _Pragma("unroll") for (int k = 0; k < 2; ++k) dst[n][k] = *(const LAS h16x8*)(lds + G8_SB(b, h) + boff + n * 2048 + k * 1024); } while (0)
; #define G8_MMA(ai, bj, At, Bt_) do { __builtin_amdgcn_s_setprio(1); _Pragma("unroll") for (int m = 0; m < 4; ++m) _Pragma("unroll") for (int n = 0; n < 2; ++n) _Pragma("unroll") for (int k = 0; k < 2; ++k) \
;     acc[ai][bj][m][n] = __builtin_amdgcn_mfma_f32_16x16x32_f16(Bt_[n][k], At[m][k], acc[ai][bj][m][n], 0, 0, 0); __builtin_amdgcn_s_setprio(0); } while (0)
; #define G8_BAR __builtin_amdgcn_s_barrier()
; template <class Epi>
; __device__ __forceinline__ void gemm_phase(LAS unsigned char* lds, const h16* A, const h16* Bt, int K, const Order& S, const Epi& E) {
;     ...
;   for (;;) {
;     const bool has_next = S.next(ui + 1, nxt);
;     const char* nA = has_next ? (const char*)A + (size_t)nxt.pm * tstep : cA;
;     const char* nB = has_next ? (const char*)Bt + (size_t)nxt.pn * tstep : cB;
;     for (int t = 0; t < nt; t += 2) {
;       const bool last = (t == nt - 2);
;       const char* a1 = cA + (size_t)(t + 1) * kstep;
;       const char* a2 = last ? nA : cA + (size_t)(t + 2) * kstep;
;       const char* b2 = last ? nB : cB + (size_t)(t + 2) * kstep;
;       const char* a3 = a2 + kstep;
;       const char* b3 = b2 + kstep;
;       if (Epi::MID_T >= 0 && t == Epi::MID_T) E.mid(acc, ui, wr, fr);
;       G8_LDB(B0, 0, 0); G8_SCHED; G8_LDA(At, 0, 0); G8_STAGE(G8_SA(1, 1), a1 + hstep);
;       G8_WAIT_L(8); G8_BAR; G8_WAIT_L(0); G8_MMA(0, 0, At, B0); G8_BAR; G8_SCHED;
;     ...
; #pragma unroll
;     for (int a = 0; a < 2; ++a)
; #pragma unroll
;       for (int b = 0; b < 2; ++b)
; #pragma unroll
;         for (int m = 0; m < 4; ++m)
; #pragma unroll
;           for (int n = 0; n < 2; ++n) acc[a][b][m][n] = (f32x4){0.f, 0.f, 0.f, 0.f};
;     cur = nxt; cA = nA; cB = nB; ++ui;
.LBB0_2377:
	s_ashr_i32 s15, s14, 31
	v_cmp_lt_i64_e32 vcc, s[16:17], v[148:149]
	s_lshl_b64 s[16:17], s[14:15], 19
	s_add_u32 s16, s31, s16
	s_addc_u32 s17, s34, s17
	s_and_b64 s[18:19], vcc, exec
	s_cselect_b32 s3, s17, s21
	s_cselect_b32 s15, s16, s20
	s_ashr_i32 s13, s12, 31
	s_lshl_b64 s[18:19], s[12:13], 19
	s_add_u32 s18, s35, s18
	s_addc_u32 s19, s36, s19
	s_and_b64 s[28:29], vcc, exec
	s_cselect_b32 s13, s19, s25
	s_cselect_b32 s23, s18, s24
	s_lshl_b32 s28, s26, 10
	s_add_u32 s26, s20, 0x40080
	s_addc_u32 s27, s21, 0
	v_mov_b32_e32 v2, v1
	v_mov_b32_e32 v3, v1
	s_add_u32 s53, s24, 0x100
	s_waitcnt lgkmcnt(0)
	v_mov_b32_e32 v0, v1
	v_mov_b64_e32 v[6:7], v[2:3]
	v_mov_b64_e32 v[10:11], v[2:3]
	v_mov_b64_e32 v[22:23], v[2:3]
	v_mov_b64_e32 v[26:27], v[2:3]
	v_mov_b64_e32 v[38:39], v[2:3]
	v_mov_b64_e32 v[42:43], v[2:3]
	v_mov_b64_e32 v[54:55], v[2:3]
	v_mov_b64_e32 v[58:59], v[2:3]
	v_mov_b64_e32 v[14:15], v[2:3]
	v_mov_b64_e32 v[18:19], v[2:3]
	v_mov_b64_e32 v[30:31], v[2:3]
	v_mov_b64_e32 v[34:35], v[2:3]
	v_mov_b64_e32 v[46:47], v[2:3]
	v_mov_b64_e32 v[50:51], v[2:3]
	v_mov_b64_e32 v[62:63], v[2:3]
	v_mov_b64_e32 v[66:67], v[2:3]
	v_mov_b64_e32 v[70:71], v[2:3]
	v_mov_b64_e32 v[74:75], v[2:3]
	v_mov_b64_e32 v[86:87], v[2:3]
	v_mov_b64_e32 v[90:91], v[2:3]
	v_mov_b64_e32 v[102:103], v[2:3]
	v_mov_b64_e32 v[106:107], v[2:3]
	v_mov_b64_e32 v[118:119], v[2:3]
	v_mov_b64_e32 v[122:123], v[2:3]
	v_mov_b64_e32 v[78:79], v[2:3]
	v_mov_b64_e32 v[82:83], v[2:3]
	v_mov_b64_e32 v[94:95], v[2:3]
	v_mov_b64_e32 v[98:99], v[2:3]
	v_mov_b64_e32 v[110:111], v[2:3]
	v_mov_b64_e32 v[114:115], v[2:3]
	v_mov_b64_e32 v[126:127], v[2:3]
	v_mov_b64_e32 v[130:131], v[2:3]
	v_lshl_add_u64 v[154:155], s[26:27], 0, v[140:141]
	v_lshl_add_u64 v[156:157], s[26:27], 0, v[152:153]
	s_addc_u32 s54, s25, 0
	s_mov_b32 s55, -2
	s_mov_b64 s[24:25], 0
	v_add_u32_e32 v160, s28, v159
	v_mov_b64_e32 v[4:5], v[0:1]
	v_mov_b64_e32 v[8:9], v[0:1]
	v_mov_b64_e32 v[20:21], v[0:1]
	v_mov_b64_e32 v[24:25], v[0:1]
	v_mov_b64_e32 v[36:37], v[0:1]
	v_mov_b64_e32 v[40:41], v[0:1]
	v_mov_b64_e32 v[52:53], v[0:1]
	v_mov_b64_e32 v[56:57], v[0:1]
	v_mov_b64_e32 v[12:13], v[0:1]
	v_mov_b64_e32 v[16:17], v[0:1]
	v_mov_b64_e32 v[28:29], v[0:1]
	v_mov_b64_e32 v[32:33], v[0:1]
	v_mov_b64_e32 v[44:45], v[0:1]
	v_mov_b64_e32 v[48:49], v[0:1]
	v_mov_b64_e32 v[60:61], v[0:1]
	v_mov_b64_e32 v[64:65], v[0:1]
	v_mov_b64_e32 v[68:69], v[0:1]
	v_mov_b64_e32 v[72:73], v[0:1]
	v_mov_b64_e32 v[84:85], v[0:1]
	v_mov_b64_e32 v[88:89], v[0:1]
	v_mov_b64_e32 v[100:101], v[0:1]
	v_mov_b64_e32 v[104:105], v[0:1]
	v_mov_b64_e32 v[116:117], v[0:1]
	v_mov_b64_e32 v[120:121], v[0:1]
	v_mov_b64_e32 v[76:77], v[0:1]
	v_mov_b64_e32 v[80:81], v[0:1]
	v_mov_b64_e32 v[92:93], v[0:1]
	v_mov_b64_e32 v[96:97], v[0:1]
	v_mov_b64_e32 v[108:109], v[0:1]
	v_mov_b64_e32 v[112:113], v[0:1]
	v_mov_b64_e32 v[124:125], v[0:1]
	v_mov_b64_e32 v[128:129], v[0:1]
	v_readfirstlane_b32 vcc_lo, v145
	s_cmp_lt_u32 vcc_lo, 0x100
	s_cbranch_scc1 .Lgprio_wo
	s_setprio 1
.Lgprio_wo:
	s_branch .LBB0_2379
.LBB0_2378:
	s_add_u32 s26, s20, s24
	v_or_b32_e32 v0, 0x10000, v158
	s_addc_u32 s27, s21, s25
	v_add_u32_e32 v2, 0x10400, v158
	ds_read_b128 v[162:165], v0
	ds_read_b128 v[166:169], v2
	v_add_u32_e32 v0, 0x10800, v158
	s_add_u32 s26, s26, 0x100
	v_add_u32_e32 v2, 0x10c00, v158
	ds_read_b128 v[170:173], v0
	ds_read_b128 v[174:177], v2
	s_addc_u32 s27, s27, 0
	s_add_u32 s56, s53, s24
	s_addc_u32 s57, s54, s25
	s_cmpk_eq_i32 s24, 0x700
	s_cselect_b32 s29, s3, s27
	s_cselect_b32 s28, s15, s26
	s_cselect_b32 s27, s13, s57
	s_cselect_b32 s26, s23, s56
	v_lshl_add_u64 v[2:3], v[154:155], 0, s[24:25]
	s_add_i32 m0, s37, 0xc000
	ds_read_b128 v[178:181], v139
	ds_read_b128 v[182:185], v139 offset:1024
	ds_read_b128 v[186:189], v139 offset:2048
	ds_read_b128 v[202:205], v139 offset:3072
	ds_read_b128 v[206:209], v139 offset:4096
	ds_read_b128 v[210:213], v139 offset:5120
	ds_read_b128 v[214:217], v139 offset:6144
	ds_read_b128 v[218:221], v139 offset:7168
	global_load_lds_dwordx4 v[2:3], off
	v_lshl_add_u64 v[2:3], v[156:157], 0, s[24:25]
	s_add_i32 m0, s37, 0xe000
	s_nop 0
	global_load_lds_dwordx4 v[2:3], off
	s_waitcnt lgkmcnt(8)
	s_barrier
	s_waitcnt lgkmcnt(0)
	s_nop 0
	s_waitcnt lgkmcnt(0)
	v_mfma_f32_16x16x32_f16 v[128:131], v[162:165], v[178:181], v[128:131]
	v_mfma_f32_16x16x32_f16 v[124:127], v[170:173], v[178:181], v[124:127]
	v_mfma_f32_16x16x32_f16 v[112:115], v[162:165], v[186:189], v[112:115]
	v_mfma_f32_16x16x32_f16 v[108:111], v[170:173], v[186:189], v[108:111]
	v_mfma_f32_16x16x32_f16 v[96:99], v[162:165], v[206:209], v[96:99]
	v_mfma_f32_16x16x32_f16 v[92:95], v[170:173], v[206:209], v[92:95]
	v_mfma_f32_16x16x32_f16 v[80:83], v[162:165], v[214:217], v[80:83]
	v_mfma_f32_16x16x32_f16 v[76:79], v[170:173], v[214:217], v[76:79]
	v_mfma_f32_16x16x32_f16 v[128:131], v[166:169], v[182:185], v[128:131]
	v_mfma_f32_16x16x32_f16 v[124:127], v[174:177], v[182:185], v[124:127]
	v_mfma_f32_16x16x32_f16 v[112:115], v[166:169], v[202:205], v[112:115]
	v_mfma_f32_16x16x32_f16 v[108:111], v[174:177], v[202:205], v[108:111]
	v_mfma_f32_16x16x32_f16 v[96:99], v[166:169], v[210:213], v[96:99]
	v_mfma_f32_16x16x32_f16 v[92:95], v[174:177], v[210:213], v[92:95]
	v_mfma_f32_16x16x32_f16 v[80:83], v[166:169], v[218:221], v[80:83]
	v_mfma_f32_16x16x32_f16 v[76:79], v[174:177], v[218:221], v[76:79]
	s_nop 0
	s_barrier
; #define G8_STAGE(bufoff, gbase) do { _Pragma("unroll") for (int _i = 0; _i < 2; ++_i) \
;     __builtin_amdgcn_global_load_lds((const unsigned*)((const char*)(gbase) + voffA[_i]), (LAS unsigned*)(lds + (bufoff) + ldsw + _i * 8192), 16, 0, 0); } while (0)
; #define G8_LDA(dst, b, h) do { _Pragma("unroll") for (int m = 0; m < 4; ++m) _Pragma("unroll") for (int k = 0; k < 2; ++k) dst[m][k] = *(const LAS h16x8*)(lds + G8_SA(b, h) + aoff + m * 2048 + k * 1024); } while (0)
; #define G8_LDB(dst, b, h) do { _Pragma("unroll") for (int n = 0; n < 2; ++n) _Pragma("unroll") for (int k = 0; k < 2; ++k) dst[n][k] = *(const LAS h16x8*)(lds + G8_SB(b, h) + boff + n * 2048 + k * 1024); } while (0)
; #define G8_MMA(ai, bj, At, Bt_) do { __builtin_amdgcn_s_setprio(1); _Pragma("unroll") for (int m = 0; m < 4; ++m) _Pragma("unroll") for (int n = 0; n < 2; ++n) _Pragma("unroll") for (int k = 0; k < 2; ++k) \
;     acc[ai][bj][m][n] = __builtin_amdgcn_mfma_f32_16x16x32_f16(Bt_[n][k], At[m][k], acc[ai][bj][m][n], 0, 0, 0); __builtin_amdgcn_s_setprio(0); } while (0)
; #define G8_WAIT_V(n) asm volatile("s_waitcnt vmcnt(" #n ")" ::: "memory")
; #define G8_WAIT_L(n) asm volatile("s_waitcnt lgkmcnt(" #n ")" ::: "memory")
; #define G8_BAR __builtin_amdgcn_s_barrier()
; #define G8_SCHED __builtin_amdgcn_sched_barrier(0)
; template <class Epi>
; __device__ __forceinline__ void gemm_phase(LAS unsigned char* lds, const h16* A, const h16* Bt, int K, const Order& S, const Epi& E) {
;     ...
;       G8_LDB(B1, 0, 1); G8_STAGE(G8_SB(0, 0), b2);
;       G8_BAR; G8_WAIT_L(0); G8_MMA(0, 1, At, B1); G8_BAR;
;       G8_LDA(At, 0, 1); G8_STAGE(G8_SA(0, 0), a2);
;       G8_BAR; G8_WAIT_L(0); G8_MMA(1, 0, At, B0); G8_BAR; G8_SCHED;
;       G8_STAGE(G8_SB(0, 1), b2 + hstep);
;       G8_WAIT_V(6); G8_BAR; G8_MMA(1, 1, At, B1); G8_BAR;
;       G8_LDB(B0, 1, 0); G8_SCHED; G8_LDA(At, 1, 0); G8_STAGE(G8_SA(0, 1), a2 + hstep);
;       G8_WAIT_L(8); G8_BAR; G8_WAIT_L(0); G8_MMA(0, 0, At, B0); G8_BAR; G8_SCHED;
	v_or_b32_e32 v0, 0x14000, v158
	s_mov_b32 m0, s38
	v_add_u32_e32 v2, 0x14400, v158
	ds_read_b128 v[222:225], v0
	ds_read_b128 v[226:229], v2
	v_add_u32_e32 v0, 0x14800, v158
	v_lshl_add_u64 v[238:239], s[26:27], 0, v[134:135]
	v_add_u32_e32 v2, 0x14c00, v158
	ds_read_b128 v[230:233], v0
	ds_read_b128 v[234:237], v2
	global_load_lds_dwordx4 v[238:239], off
	v_lshl_add_u64 v[240:241], s[26:27], 0, v[132:133]
	s_mov_b32 m0, s39
	s_nop 0
	global_load_lds_dwordx4 v[240:241], off
	s_barrier
	s_waitcnt lgkmcnt(0)
	s_nop 0
	s_waitcnt lgkmcnt(0)
	v_mfma_f32_16x16x32_f16 v[120:123], v[222:225], v[178:181], v[120:123]
	v_mfma_f32_16x16x32_f16 v[116:119], v[230:233], v[178:181], v[116:119]
	v_mfma_f32_16x16x32_f16 v[104:107], v[222:225], v[186:189], v[104:107]
	v_mfma_f32_16x16x32_f16 v[100:103], v[230:233], v[186:189], v[100:103]
	v_mfma_f32_16x16x32_f16 v[88:91], v[222:225], v[206:209], v[88:91]
	v_mfma_f32_16x16x32_f16 v[84:87], v[230:233], v[206:209], v[84:87]
	v_mfma_f32_16x16x32_f16 v[72:75], v[222:225], v[214:217], v[72:75]
	v_mfma_f32_16x16x32_f16 v[68:71], v[230:233], v[214:217], v[68:71]
	v_mfma_f32_16x16x32_f16 v[120:123], v[226:229], v[182:185], v[120:123]
	v_mfma_f32_16x16x32_f16 v[116:119], v[234:237], v[182:185], v[116:119]
	v_mfma_f32_16x16x32_f16 v[104:107], v[226:229], v[202:205], v[104:107]
	v_mfma_f32_16x16x32_f16 v[100:103], v[234:237], v[202:205], v[100:103]
	v_mfma_f32_16x16x32_f16 v[88:91], v[226:229], v[210:213], v[88:91]
	v_mfma_f32_16x16x32_f16 v[84:87], v[234:237], v[210:213], v[84:87]
	v_mfma_f32_16x16x32_f16 v[72:75], v[226:229], v[218:221], v[72:75]
	v_mfma_f32_16x16x32_f16 v[68:71], v[234:237], v[218:221], v[68:71]
	s_nop 0
	s_mov_b32 m0, s37
	v_lshl_add_u64 v[242:243], s[28:29], 0, v[134:135]
	s_barrier
	ds_read_b128 v[178:181], v139 offset:16384
	ds_read_b128 v[182:185], v139 offset:17408
	ds_read_b128 v[186:189], v139 offset:18432
	ds_read_b128 v[202:205], v139 offset:19456
	ds_read_b128 v[206:209], v139 offset:20480
	ds_read_b128 v[210:213], v139 offset:21504
	ds_read_b128 v[214:217], v139 offset:22528
	ds_read_b128 v[218:221], v139 offset:23552
	global_load_lds_dwordx4 v[242:243], off
	v_lshl_add_u64 v[244:245], s[28:29], 0, v[132:133]
	s_mov_b32 m0, s40
	s_nop 0
	global_load_lds_dwordx4 v[244:245], off
	s_barrier
	s_waitcnt lgkmcnt(0)
	s_nop 0
	s_waitcnt lgkmcnt(0)
	v_mfma_f32_16x16x32_f16 v[64:67], v[162:165], v[178:181], v[64:67]
	v_mfma_f32_16x16x32_f16 v[60:63], v[170:173], v[178:181], v[60:63]
	v_mfma_f32_16x16x32_f16 v[48:51], v[162:165], v[186:189], v[48:51]
	v_mfma_f32_16x16x32_f16 v[44:47], v[170:173], v[186:189], v[44:47]
	v_mfma_f32_16x16x32_f16 v[32:35], v[162:165], v[206:209], v[32:35]
	v_mfma_f32_16x16x32_f16 v[28:31], v[170:173], v[206:209], v[28:31]
	v_mfma_f32_16x16x32_f16 v[16:19], v[162:165], v[214:217], v[16:19]
	v_mfma_f32_16x16x32_f16 v[12:15], v[170:173], v[214:217], v[12:15]
	v_mfma_f32_16x16x32_f16 v[64:67], v[166:169], v[182:185], v[64:67]
	v_mfma_f32_16x16x32_f16 v[60:63], v[174:177], v[182:185], v[60:63]
	v_mfma_f32_16x16x32_f16 v[48:51], v[166:169], v[202:205], v[48:51]
	v_mfma_f32_16x16x32_f16 v[44:47], v[174:177], v[202:205], v[44:47]
	v_mfma_f32_16x16x32_f16 v[32:35], v[166:169], v[210:213], v[32:35]
	v_mfma_f32_16x16x32_f16 v[28:31], v[174:177], v[210:213], v[28:31]
	v_mfma_f32_16x16x32_f16 v[16:19], v[166:169], v[218:221], v[16:19]
	v_mfma_f32_16x16x32_f16 v[12:15], v[174:177], v[218:221], v[12:15]
	s_nop 0
	s_barrier
	s_add_u32 s56, s26, 0x40000
	s_addc_u32 s57, s27, 0
	s_mov_b32 m0, s41
	v_lshl_add_u64 v[2:3], s[56:57], 0, v[134:135]
	global_load_lds_dwordx4 v[2:3], off
	v_lshl_add_u64 v[2:3], s[56:57], 0, v[132:133]
	s_mov_b32 m0, s42
	s_nop 0
	global_load_lds_dwordx4 v[2:3], off
	s_waitcnt vmcnt(6)
	s_barrier
	s_nop 0
	v_mfma_f32_16x16x32_f16 v[56:59], v[222:225], v[178:181], v[56:59]
	v_mfma_f32_16x16x32_f16 v[52:55], v[230:233], v[178:181], v[52:55]
	v_mfma_f32_16x16x32_f16 v[40:43], v[222:225], v[186:189], v[40:43]
	v_mfma_f32_16x16x32_f16 v[36:39], v[230:233], v[186:189], v[36:39]
	v_mfma_f32_16x16x32_f16 v[24:27], v[222:225], v[206:209], v[24:27]
	v_mfma_f32_16x16x32_f16 v[20:23], v[230:233], v[206:209], v[20:23]
	v_mfma_f32_16x16x32_f16 v[8:11], v[222:225], v[214:217], v[8:11]
	v_mfma_f32_16x16x32_f16 v[2:5], v[230:233], v[214:217], v[4:7]
	v_mfma_f32_16x16x32_f16 v[56:59], v[226:229], v[182:185], v[56:59]
	v_mfma_f32_16x16x32_f16 v[52:55], v[234:237], v[182:185], v[52:55]
	v_mfma_f32_16x16x32_f16 v[40:43], v[226:229], v[202:205], v[40:43]
	v_mfma_f32_16x16x32_f16 v[36:39], v[234:237], v[202:205], v[36:39]
	v_mfma_f32_16x16x32_f16 v[24:27], v[226:229], v[210:213], v[24:27]
	v_mfma_f32_16x16x32_f16 v[20:23], v[234:237], v[210:213], v[20:23]
	v_mfma_f32_16x16x32_f16 v[8:11], v[226:229], v[218:221], v[8:11]
	v_mfma_f32_16x16x32_f16 v[2:5], v[234:237], v[218:221], v[2:5]
	s_nop 0
	v_or_b32_e32 v0, 0x18000, v158
	s_barrier
	v_add_u32_e32 v6, 0x18400, v158
	ds_read_b128 v[162:165], v0
	ds_read_b128 v[166:169], v6
	v_add_u32_e32 v0, 0x18800, v158
	v_add_u32_e32 v6, 0x18c00, v158
	ds_read_b128 v[170:173], v0
	ds_read_b128 v[174:177], v6
	s_add_u32 s28, s28, 0x40000
	s_addc_u32 s29, s29, 0
	s_mov_b32 m0, s43
	v_lshl_add_u64 v[6:7], s[28:29], 0, v[134:135]
	ds_read_b128 v[178:181], v139 offset:32768
	ds_read_b128 v[182:185], v139 offset:33792
	ds_read_b128 v[186:189], v139 offset:34816
	ds_read_b128 v[202:205], v139 offset:35840
	ds_read_b128 v[206:209], v139 offset:36864
	ds_read_b128 v[210:213], v139 offset:37888
	ds_read_b128 v[214:217], v139 offset:38912
	ds_read_b128 v[218:221], v139 offset:39936
	global_load_lds_dwordx4 v[6:7], off
	v_lshl_add_u64 v[6:7], s[28:29], 0, v[132:133]
	s_mov_b32 m0, s44
	s_nop 0
	global_load_lds_dwordx4 v[6:7], off
	s_waitcnt lgkmcnt(8)
	s_barrier
; #define G8_STAGE(bufoff, gbase) do { _Pragma("unroll") for (int _i = 0; _i < 2; ++_i) \
;     __builtin_amdgcn_global_load_lds((const unsigned*)((const char*)(gbase) + voffA[_i]), (LAS unsigned*)(lds + (bufoff) + ldsw + _i * 8192), 16, 0, 0); } while (0)
; #define G8_LDA(dst, b, h) do { _Pragma("unroll") for (int m = 0; m < 4; ++m) _Pragma("unroll") for (int k = 0; k < 2; ++k) dst[m][k] = *(const LAS h16x8*)(lds + G8_SA(b, h) + aoff + m * 2048 + k * 1024); } while (0)
; #define G8_LDB(dst, b, h) do { _Pragma("unroll") for (int n = 0; n < 2; ++n) _Pragma("unroll") for (int k = 0; k < 2; ++k) dst[n][k] = *(const LAS h16x8*)(lds + G8_SB(b, h) + boff + n * 2048 + k * 1024); } while (0)
; #define G8_MMA(ai, bj, At, Bt_) do { __builtin_amdgcn_s_setprio(1); _Pragma("unroll") for (int m = 0; m < 4; ++m) _Pragma("unroll") for (int n = 0; n < 2; ++n) _Pragma("unroll") for (int k = 0; k < 2; ++k) \
;     acc[ai][bj][m][n] = __builtin_amdgcn_mfma_f32_16x16x32_f16(Bt_[n][k], At[m][k], acc[ai][bj][m][n], 0, 0, 0); __builtin_amdgcn_s_setprio(0); } while (0)
; #define G8_WAIT_V(n) asm volatile("s_waitcnt vmcnt(" #n ")" ::: "memory")
; #define G8_WAIT_L(n) asm volatile("s_waitcnt lgkmcnt(" #n ")" ::: "memory")
; #define G8_BAR __builtin_amdgcn_s_barrier()
; #define G8_SCHED __builtin_amdgcn_sched_barrier(0)
; template <class Epi>
; __device__ __forceinline__ void gemm_phase(LAS unsigned char* lds, const h16* A, const h16* Bt, int K, const Order& S, const Epi& E) {
;     ...
;       G8_WAIT_L(8); G8_BAR; G8_WAIT_L(0); G8_MMA(0, 0, At, B0); G8_BAR; G8_SCHED;
;       G8_LDB(B1, 1, 1); G8_STAGE(G8_SB(1, 0), b3);
;       G8_BAR; G8_WAIT_L(0); G8_MMA(0, 1, At, B1); G8_BAR;
;       G8_LDA(At, 1, 1); G8_STAGE(G8_SA(1, 0), a3);
;       G8_BAR; G8_WAIT_L(0); G8_MMA(1, 0, At, B0); G8_BAR; G8_SCHED;
;       G8_STAGE(G8_SB(1, 1), b3 + hstep);
;       G8_WAIT_V(6); G8_BAR; G8_MMA(1, 1, At, B1); G8_BAR;
;     }
	s_waitcnt lgkmcnt(0)
	s_nop 0
	s_waitcnt lgkmcnt(0)
	v_mfma_f32_16x16x32_f16 v[128:131], v[162:165], v[178:181], v[128:131]
	v_mfma_f32_16x16x32_f16 v[124:127], v[170:173], v[178:181], v[124:127]
	v_mfma_f32_16x16x32_f16 v[112:115], v[162:165], v[186:189], v[112:115]
	v_mfma_f32_16x16x32_f16 v[108:111], v[170:173], v[186:189], v[108:111]
	v_mfma_f32_16x16x32_f16 v[96:99], v[162:165], v[206:209], v[96:99]
	v_mfma_f32_16x16x32_f16 v[92:95], v[170:173], v[206:209], v[92:95]
	v_mfma_f32_16x16x32_f16 v[80:83], v[162:165], v[214:217], v[80:83]
	v_mfma_f32_16x16x32_f16 v[76:79], v[170:173], v[214:217], v[76:79]
	v_mfma_f32_16x16x32_f16 v[128:131], v[166:169], v[182:185], v[128:131]
	v_mfma_f32_16x16x32_f16 v[124:127], v[174:177], v[182:185], v[124:127]
	v_mfma_f32_16x16x32_f16 v[112:115], v[166:169], v[202:205], v[112:115]
	v_mfma_f32_16x16x32_f16 v[108:111], v[174:177], v[202:205], v[108:111]
	v_mfma_f32_16x16x32_f16 v[96:99], v[166:169], v[210:213], v[96:99]
	v_mfma_f32_16x16x32_f16 v[92:95], v[174:177], v[210:213], v[92:95]
	v_mfma_f32_16x16x32_f16 v[80:83], v[166:169], v[218:221], v[80:83]
	v_mfma_f32_16x16x32_f16 v[76:79], v[174:177], v[218:221], v[76:79]
	s_nop 0
	s_barrier
	v_or_b32_e32 v0, 0x1c000, v158
	v_add_u32_e32 v6, 0x1c400, v158
	ds_read_b128 v[222:225], v0
	ds_read_b128 v[226:229], v6
	v_add_u32_e32 v0, 0x1c800, v158
	v_add_u32_e32 v6, 0x1cc00, v158
	s_mov_b32 m0, s46
	ds_read_b128 v[230:233], v0
	ds_read_b128 v[234:237], v6
	v_lshl_add_u64 v[6:7], v[238:239], 0, s[94:95]
	global_load_lds_dwordx4 v[6:7], off
	v_lshl_add_u64 v[6:7], v[240:241], 0, s[94:95]
	s_mov_b32 m0, s47
	s_nop 0
	global_load_lds_dwordx4 v[6:7], off
	s_barrier
	s_waitcnt lgkmcnt(0)
	s_nop 0
	s_waitcnt lgkmcnt(0)
	v_mfma_f32_16x16x32_f16 v[120:123], v[222:225], v[178:181], v[120:123]
	v_mfma_f32_16x16x32_f16 v[116:119], v[230:233], v[178:181], v[116:119]
	v_mfma_f32_16x16x32_f16 v[104:107], v[222:225], v[186:189], v[104:107]
	v_mfma_f32_16x16x32_f16 v[100:103], v[230:233], v[186:189], v[100:103]
	v_mfma_f32_16x16x32_f16 v[88:91], v[222:225], v[206:209], v[88:91]
	v_mfma_f32_16x16x32_f16 v[84:87], v[230:233], v[206:209], v[84:87]
	v_mfma_f32_16x16x32_f16 v[72:75], v[222:225], v[214:217], v[72:75]
	v_mfma_f32_16x16x32_f16 v[68:71], v[230:233], v[214:217], v[68:71]
	v_mfma_f32_16x16x32_f16 v[120:123], v[226:229], v[182:185], v[120:123]
	v_mfma_f32_16x16x32_f16 v[116:119], v[234:237], v[182:185], v[116:119]
	v_mfma_f32_16x16x32_f16 v[104:107], v[226:229], v[202:205], v[104:107]
	v_mfma_f32_16x16x32_f16 v[100:103], v[234:237], v[202:205], v[100:103]
	v_mfma_f32_16x16x32_f16 v[88:91], v[226:229], v[210:213], v[88:91]
	v_mfma_f32_16x16x32_f16 v[84:87], v[234:237], v[210:213], v[84:87]
	v_mfma_f32_16x16x32_f16 v[72:75], v[226:229], v[218:221], v[72:75]
	v_mfma_f32_16x16x32_f16 v[68:71], v[234:237], v[218:221], v[68:71]
	s_nop 0
	s_mov_b32 m0, s48
	v_lshl_add_u64 v[6:7], v[242:243], 0, s[94:95]
	s_barrier
	ds_read_b128 v[178:181], v139 offset:49152
	ds_read_b128 v[182:185], v139 offset:50176
	ds_read_b128 v[186:189], v139 offset:51200
	ds_read_b128 v[202:205], v139 offset:52224
	ds_read_b128 v[206:209], v139 offset:53248
	ds_read_b128 v[210:213], v139 offset:54272
	ds_read_b128 v[214:217], v139 offset:55296
	ds_read_b128 v[218:221], v139 offset:56320
	global_load_lds_dwordx4 v[6:7], off
	v_lshl_add_u64 v[6:7], v[244:245], 0, s[94:95]
	s_mov_b32 m0, s49
	s_nop 0
	global_load_lds_dwordx4 v[6:7], off
	s_barrier
	s_waitcnt lgkmcnt(0)
	s_nop 0
	s_waitcnt lgkmcnt(0)
	v_mfma_f32_16x16x32_f16 v[64:67], v[162:165], v[178:181], v[64:67]
	v_mfma_f32_16x16x32_f16 v[60:63], v[170:173], v[178:181], v[60:63]
	v_mfma_f32_16x16x32_f16 v[48:51], v[162:165], v[186:189], v[48:51]
	v_mfma_f32_16x16x32_f16 v[44:47], v[170:173], v[186:189], v[44:47]
	v_mfma_f32_16x16x32_f16 v[32:35], v[162:165], v[206:209], v[32:35]
	v_mfma_f32_16x16x32_f16 v[28:31], v[170:173], v[206:209], v[28:31]
	v_mfma_f32_16x16x32_f16 v[16:19], v[162:165], v[214:217], v[16:19]
	v_mfma_f32_16x16x32_f16 v[12:15], v[170:173], v[214:217], v[12:15]
	v_mfma_f32_16x16x32_f16 v[64:67], v[166:169], v[182:185], v[64:67]
	v_mfma_f32_16x16x32_f16 v[60:63], v[174:177], v[182:185], v[60:63]
	v_mfma_f32_16x16x32_f16 v[48:51], v[166:169], v[202:205], v[48:51]
	v_mfma_f32_16x16x32_f16 v[44:47], v[174:177], v[202:205], v[44:47]
	v_mfma_f32_16x16x32_f16 v[32:35], v[166:169], v[210:213], v[32:35]
	v_mfma_f32_16x16x32_f16 v[28:31], v[174:177], v[210:213], v[28:31]
	v_mfma_f32_16x16x32_f16 v[16:19], v[166:169], v[218:221], v[16:19]
	v_mfma_f32_16x16x32_f16 v[12:15], v[174:177], v[218:221], v[12:15]
	s_nop 0
	s_barrier
	s_add_u32 s26, s26, 0x40080
	s_addc_u32 s27, s27, 0
	s_mov_b32 m0, s50
	v_lshl_add_u64 v[6:7], s[26:27], 0, v[134:135]
	global_load_lds_dwordx4 v[6:7], off
	v_lshl_add_u64 v[6:7], s[26:27], 0, v[132:133]
	s_mov_b32 m0, s51
	s_nop 0
	global_load_lds_dwordx4 v[6:7], off
	s_waitcnt vmcnt(6)
	s_barrier
	s_nop 0
	v_mfma_f32_16x16x32_f16 v[56:59], v[222:225], v[178:181], v[56:59]
	v_mfma_f32_16x16x32_f16 v[52:55], v[230:233], v[178:181], v[52:55]
	v_mfma_f32_16x16x32_f16 v[40:43], v[222:225], v[186:189], v[40:43]
	v_mfma_f32_16x16x32_f16 v[36:39], v[230:233], v[186:189], v[36:39]
	v_mfma_f32_16x16x32_f16 v[24:27], v[222:225], v[206:209], v[24:27]
	v_mfma_f32_16x16x32_f16 v[20:23], v[230:233], v[206:209], v[20:23]
	v_mfma_f32_16x16x32_f16 v[6:9], v[222:225], v[214:217], v[8:11]
	v_mfma_f32_16x16x32_f16 v[2:5], v[230:233], v[214:217], v[2:5]
	v_mfma_f32_16x16x32_f16 v[56:59], v[226:229], v[182:185], v[56:59]
	v_mfma_f32_16x16x32_f16 v[52:55], v[234:237], v[182:185], v[52:55]
	v_mfma_f32_16x16x32_f16 v[40:43], v[226:229], v[202:205], v[40:43]
	v_mfma_f32_16x16x32_f16 v[36:39], v[234:237], v[202:205], v[36:39]
	v_mfma_f32_16x16x32_f16 v[24:27], v[226:229], v[210:213], v[24:27]
	v_mfma_f32_16x16x32_f16 v[20:23], v[234:237], v[210:213], v[20:23]
	v_mfma_f32_16x16x32_f16 v[8:11], v[226:229], v[218:221], v[6:9]
	v_mfma_f32_16x16x32_f16 v[4:7], v[234:237], v[218:221], v[2:5]
	s_nop 0
	s_add_i32 s55, s55, 2
	s_add_u32 s24, s24, 0x100
	s_addc_u32 s25, s25, 0
	s_cmp_gt_u32 s55, 13
	s_barrier
	s_cbranch_scc1 .LBB0_2381

; __device__ __forceinline__ float xor16(float v) { return __int_as_float(__builtin_amdgcn_ds_swizzle(__float_as_int(v), 0x401F)); }
;   __device__ __forceinline__ void operator()(const f32x4 (&acc)[2][2][4][2], const g8::Unit& u, int ui, int wr, int wc, int fr, int fq) const {
; #pragma unroll
;     for (int ai = 0; ai < 2; ++ai)
; #pragma unroll
;       for (int m = 0; m < 4; ++m) {
;         const size_t row = (size_t)u.pm * 256 + 128 * ai + 64 * wr + 16 * m + fr;
;         const size_t base = row * DM + 256 * u.pn + 32 * wc + 8 * fq;
;         float ss = 0.f;
; #pragma unroll
;         for (int bj = 0; bj < 2; ++bj) {
;           const size_t idx = base + 128 * bj;
;           const h16x8 xv = *(const h16x8*)(xb + idx);
;           f32x4 x0 = acc[ai][bj][m][0], x1 = acc[ai][bj][m][1];
; #pragma unroll
;           for (int j = 0; j < 4; ++j) { x0[j] += (float)xv[j]; x1[j] += (float)xv[4 + j]; ss += x0[j] * x0[j] + x1[j] * x1[j]; }
;           if (final_out) {
;             __builtin_nontemporal_store(x0, (f32x4*)(xo + idx));
;             __builtin_nontemporal_store(x1, (f32x4*)(xo + idx + 4));
;           } else {
;             *(h16x8*)(xb + idx) = pack8(x0, x1);
;           }
;         }
;         ss += xor16(ss);
;         ss += __shfl_xor(ss, 32);
;         if (fq == 0) ssq[row * 16 + u.pn * 4 + wc] = ss;
;       }
.LBB0_2381:
	s_setprio 0
	s_ashr_i32 s23, s22, 31
	s_lshl_b64 s[20:21], s[22:23], 8
	v_and_b32_e32 v156, 64, v199
	v_lshl_add_u64 v[2:3], s[20:21], 0, v[136:137]
	s_lshl_b32 s3, s2, 8
	v_xor_b32_e32 v0, 32, v199
	v_add_u32_e32 v156, 64, v156
	s_ashr_i32 s13, s3, 31
	v_cmp_lt_i32_e32 vcc, v0, v156
	v_lshlrev_b64 v[156:157], 11, v[2:3]
	v_mov_b32_e32 v155, s13
	v_or_b32_e32 v154, s3, v138
	v_lshl_add_u64 v[156:157], s[0:1], 0, v[156:157]
	v_lshl_add_u64 v[156:157], v[154:155], 1, v[156:157]
	v_cndmask_b32_e32 v0, v199, v0, vcc
	v_lshlrev_b32_e32 v0, 2, v0
	s_lshl_b32 s20, s2, 2
	s_ashr_i32 s21, s20, 31
	global_load_dwordx4 v[166:169], v[156:157], off
	global_load_dwordx4 v[170:173], v[156:157], off offset:256
	s_mov_b32 s3, 0
	s_mov_b32 s2, 0x8000
	v_lshl_add_u64 v[242:243], v[156:157], 0, s[2:3]
	global_load_dwordx4 v[174:177], v[242:243], off
	global_load_dwordx4 v[178:181], v[242:243], off offset:256
	s_mov_b32 s2, 0x10000
	v_lshl_add_u64 v[244:245], v[156:157], 0, s[2:3]
	global_load_dwordx4 v[182:185], v[244:245], off
	global_load_dwordx4 v[186:189], v[244:245], off offset:256
	s_mov_b32 s2, 0x18000
	v_lshl_add_u64 v[242:243], v[156:157], 0, s[2:3]
	global_load_dwordx4 v[202:205], v[242:243], off
	global_load_dwordx4 v[206:209], v[242:243], off offset:256
	s_mov_b32 s2, 0x40000
	v_lshl_add_u64 v[244:245], v[156:157], 0, s[2:3]
	global_load_dwordx4 v[210:213], v[244:245], off
	global_load_dwordx4 v[214:217], v[244:245], off offset:256
	s_mov_b32 s2, 0x48000
	v_lshl_add_u64 v[242:243], v[156:157], 0, s[2:3]
	global_load_dwordx4 v[218:221], v[242:243], off
	global_load_dwordx4 v[222:225], v[242:243], off offset:256
	s_mov_b32 s2, 0x50000
	v_lshl_add_u64 v[244:245], v[156:157], 0, s[2:3]
	global_load_dwordx4 v[226:229], v[244:245], off
	global_load_dwordx4 v[230:233], v[244:245], off offset:256
	s_mov_b32 s2, 0x58000
	v_lshl_add_u64 v[242:243], v[156:157], 0, s[2:3]
	global_load_dwordx4 v[234:237], v[242:243], off
	global_load_dwordx4 v[238:241], v[242:243], off offset:256
	s_waitcnt vmcnt(15)
	v_cvt_f32_f16_e32 v164, v166
	v_cvt_f32_f16_sdwa v165, v166 dst_sel:DWORD dst_unused:UNUSED_PAD src0_sel:WORD_1
	v_cvt_f32_f16_e32 v160, v167
	v_cvt_f32_f16_sdwa v161, v167 dst_sel:DWORD dst_unused:UNUSED_PAD src0_sel:WORD_1
	v_pk_add_f32 v[164:165], v[128:129], v[164:165]
	s_nop 0
	v_cvt_pk_f16_f32 v128, v164, v165
	v_pk_add_f32 v[160:161], v[130:131], v[160:161]
	v_cvt_f32_f16_e32 v130, v168
	v_cvt_f32_f16_sdwa v131, v168 dst_sel:DWORD dst_unused:UNUSED_PAD src0_sel:WORD_1
	v_cvt_f32_f16_e32 v162, v169
	v_cvt_f32_f16_sdwa v163, v169 dst_sel:DWORD dst_unused:UNUSED_PAD src0_sel:WORD_1
	v_cvt_pk_f16_f32 v129, v160, v161
	v_pk_add_f32 v[130:131], v[124:125], v[130:131]
	v_pk_add_f32 v[162:163], v[126:127], v[162:163]
	v_pk_mul_f32 v[124:125], v[130:131], v[130:131]
	v_cvt_pk_f16_f32 v130, v130, v131
	v_cvt_pk_f16_f32 v131, v162, v163
	global_store_dwordx4 v[156:157], v[128:131], off
	s_nop 0
	v_pk_mul_f32 v[126:127], v[162:163], v[162:163]
	v_pk_fma_f32 v[124:125], v[164:165], v[164:165], v[124:125]
	v_pk_fma_f32 v[126:127], v[160:161], v[160:161], v[126:127]
	s_waitcnt vmcnt(15)
	v_cvt_f32_f16_e32 v160, v170
	v_cvt_f32_f16_sdwa v161, v170 dst_sel:DWORD dst_unused:UNUSED_PAD src0_sel:WORD_1
	v_cvt_f32_f16_e32 v128, v171
	v_cvt_f32_f16_sdwa v129, v171 dst_sel:DWORD dst_unused:UNUSED_PAD src0_sel:WORD_1
	v_pk_add_f32 v[160:161], v[120:121], v[160:161]
	s_nop 0
	v_cvt_pk_f16_f32 v120, v160, v161
	v_pk_add_f32 v[128:129], v[122:123], v[128:129]
	v_cvt_f32_f16_e32 v122, v172
	v_cvt_f32_f16_sdwa v123, v172 dst_sel:DWORD dst_unused:UNUSED_PAD src0_sel:WORD_1
	v_cvt_pk_f16_f32 v121, v128, v129
	v_pk_add_f32 v[116:117], v[116:117], v[122:123]
	s_nop 0
	v_pk_mul_f32 v[122:123], v[116:117], v[116:117]
	s_nop 0
	v_pk_fma_f32 v[160:161], v[160:161], v[160:161], v[122:123]
	v_cvt_pk_f16_f32 v122, v116, v117
	v_cvt_f32_f16_e32 v116, v173
	v_cvt_f32_f16_sdwa v117, v173 dst_sel:DWORD dst_unused:UNUSED_PAD src0_sel:WORD_1
	v_add_f32_e32 v123, v124, v125
	v_add_f32_e32 v123, v126, v123
	v_add_f32_e32 v123, v127, v123
	v_pk_add_f32 v[116:117], v[118:119], v[116:117]
	v_add_f32_e32 v123, v160, v123
	v_pk_mul_f32 v[118:119], v[116:117], v[116:117]
	v_add_f32_e32 v123, v161, v123
	v_pk_fma_f32 v[118:119], v[128:129], v[128:129], v[118:119]
	s_nop 0
	v_add_f32_e32 v118, v118, v123
	v_add_f32_e32 v118, v119, v118
	v_cvt_pk_f16_f32 v123, v116, v117
	v_mov_b32_e32 v116, v118
	s_nop 1
	v_permlane16_swap_b32_e32 v116, v118
	global_store_dwordx4 v[156:157], v[120:123], off offset:256
	s_waitcnt lgkmcnt(0)
	v_add_f32_e32 v116, v118, v116
	v_mov_b32_e32 v117, v116
	s_nop 1
	v_permlane32_swap_b32_e32 v117, v116
	s_and_saveexec_b64 s[22:23], s[6:7]
	s_cbranch_execz .LBB0_2383
	s_waitcnt lgkmcnt(0)
	v_add_f32_e32 v118, v116, v117
	v_lshlrev_b64 v[116:117], 6, v[2:3]
	v_lshl_add_u64 v[116:117], s[10:11], 0, v[116:117]
	v_lshl_add_u64 v[116:117], s[20:21], 2, v[116:117]
	s_lshl_b32 s92, s45, 2
	v_lshl_add_u64 v[116:117], v[116:117], 0, s[92:93]
	global_store_dword v[116:117], v118, off

; #define G8_STAGE(bufoff, gbase) do { _Pragma("unroll") for (int _i = 0; _i < 2; ++_i) \
;     __builtin_amdgcn_global_load_lds((const unsigned*)((const char*)(gbase) + voffA[_i]), (LAS unsigned*)(lds + (bufoff) + ldsw + _i * 8192), 16, 0, 0); } while (0)
; #define G8_LDA(dst, b, h) do { _Pragma("unroll") for (int m = 0; m < 4; ++m) _Pragma("unroll") for (int k = 0; k < 2; ++k) dst[m][k] = *(const LAS h16x8*)(lds + G8_SA(b, h) + aoff + m * 2048 + k * 1024); } while (0)
; #define G8_LDB(dst, b, h) do { _Pragma("unroll") for (int n = 0; n < 2; ++n) _Pragma("unroll") for (int k = 0; k < 2; ++k) dst[n][k] = *(const LAS h16x8*)(lds + G8_SB(b, h) + boff + n * 2048 + k * 1024); } while (0)
; #define G8_MMA(ai, bj, At, Bt_) do { __builtin_amdgcn_s_setprio(1); _Pragma("unroll") for (int m = 0; m < 4; ++m) _Pragma("unroll") for (int n = 0; n < 2; ++n) _Pragma("unroll") for (int k = 0; k < 2; ++k) \
;     acc[ai][bj][m][n] = __builtin_amdgcn_mfma_f32_16x16x32_f16(Bt_[n][k], At[m][k], acc[ai][bj][m][n], 0, 0, 0); __builtin_amdgcn_s_setprio(0); } while (0)
; #define G8_BAR __builtin_amdgcn_s_barrier()
; template <class Epi>
; __device__ __forceinline__ void gemm_phase(LAS unsigned char* lds, const h16* A, const h16* Bt, int K, const Order& S, const Epi& E) {
;     ...
;   for (;;) {
;     const bool has_next = S.next(ui + 1, nxt);
;     const char* nA = has_next ? (const char*)A + (size_t)nxt.pm * tstep : cA;
;     const char* nB = has_next ? (const char*)Bt + (size_t)nxt.pn * tstep : cB;
;     for (int t = 0; t < nt; t += 2) {
;       const bool last = (t == nt - 2);
;       const char* a1 = cA + (size_t)(t + 1) * kstep;
;       const char* a2 = last ? nA : cA + (size_t)(t + 2) * kstep;
;       const char* b2 = last ? nB : cB + (size_t)(t + 2) * kstep;
;       const char* a3 = a2 + kstep;
;       const char* b3 = b2 + kstep;
;       if (Epi::MID_T >= 0 && t == Epi::MID_T) E.mid(acc, ui, wr, fr);
;       G8_LDB(B0, 0, 0); G8_SCHED; G8_LDA(At, 0, 0); G8_STAGE(G8_SA(1, 1), a1 + hstep);
;       G8_WAIT_L(8); G8_BAR; G8_WAIT_L(0); G8_MMA(0, 0, At, B0); G8_BAR; G8_SCHED;
;     ...
; #pragma unroll
;     for (int a = 0; a < 2; ++a)
; #pragma unroll
;       for (int b = 0; b < 2; ++b)
; #pragma unroll
;         for (int m = 0; m < 4; ++m)
; #pragma unroll
;           for (int n = 0; n < 2; ++n) acc[a][b][m][n] = (f32x4){0.f, 0.f, 0.f, 0.f};
;     cur = nxt; cA = nA; cB = nB; ++ui;
.LBB0_2472:
	v_mov_b64_e32 v[2:3], 0x800
	s_ashr_i32 s13, s12, 31
	v_cmp_lt_i64_e32 vcc, s[14:15], v[2:3]
	s_lshl_b64 s[14:15], s[12:13], 19
	s_add_u32 s14, s3, s14
	s_addc_u32 s15, s24, s15
	s_and_b64 s[16:17], vcc, exec
	s_cselect_b32 s13, s15, s19
	s_cselect_b32 s47, s14, s18
	s_ashr_i32 s11, s10, 31
	s_lshl_b64 s[16:17], s[10:11], 19
	s_add_u32 s16, s25, s16
	s_addc_u32 s17, s26, s17
	s_and_b64 s[22:23], vcc, exec
	s_cselect_b32 s11, s17, s21
	s_cselect_b32 s48, s16, s20
	s_add_u32 s18, s18, 0x40080
	s_addc_u32 s19, s19, 0
	s_add_u32 s49, s20, 0x100
	v_mov_b32_e32 v2, 0
	s_addc_u32 s50, s21, 0
	s_mov_b32 s51, -2
	v_mov_b32_e32 v3, v2
	v_mov_b32_e32 v4, v2
	v_mov_b32_e32 v5, v2
	v_mov_b32_e32 v6, v2
	v_mov_b32_e32 v7, v2
	v_mov_b32_e32 v8, v2
	v_mov_b32_e32 v9, v2
	v_mov_b32_e32 v18, v2
	v_mov_b32_e32 v19, v2
	v_mov_b32_e32 v20, v2
	v_mov_b32_e32 v21, v2
	v_mov_b32_e32 v22, v2
	v_mov_b32_e32 v23, v2
	v_mov_b32_e32 v24, v2
	v_mov_b32_e32 v25, v2
	v_mov_b32_e32 v34, v2
	v_mov_b32_e32 v35, v2
	v_mov_b32_e32 v36, v2
	v_mov_b32_e32 v37, v2
	v_mov_b32_e32 v38, v2
	v_mov_b32_e32 v39, v2
	v_mov_b32_e32 v40, v2
	v_mov_b32_e32 v41, v2
	v_mov_b32_e32 v50, v2
	v_mov_b32_e32 v51, v2
	v_mov_b32_e32 v52, v2
	v_mov_b32_e32 v53, v2
	v_mov_b32_e32 v54, v2
	v_mov_b32_e32 v55, v2
	v_mov_b32_e32 v56, v2
	v_mov_b32_e32 v57, v2
	v_mov_b32_e32 v10, v2
	v_mov_b32_e32 v11, v2
	v_mov_b32_e32 v12, v2
	v_mov_b32_e32 v13, v2
	v_mov_b32_e32 v14, v2
	v_mov_b32_e32 v15, v2
	v_mov_b32_e32 v16, v2
	v_mov_b32_e32 v17, v2
	v_mov_b32_e32 v26, v2
	v_mov_b32_e32 v27, v2
	v_mov_b32_e32 v28, v2
	v_mov_b32_e32 v29, v2
	v_mov_b32_e32 v30, v2
	v_mov_b32_e32 v31, v2
	v_mov_b32_e32 v32, v2
	v_mov_b32_e32 v33, v2
	v_mov_b32_e32 v42, v2
	v_mov_b32_e32 v43, v2
	v_mov_b32_e32 v44, v2
	v_mov_b32_e32 v45, v2
	v_mov_b32_e32 v46, v2
	v_mov_b32_e32 v47, v2
	v_mov_b32_e32 v48, v2
	v_mov_b32_e32 v49, v2
	v_mov_b32_e32 v58, v2
	v_mov_b32_e32 v59, v2
	v_mov_b32_e32 v60, v2
	v_mov_b32_e32 v61, v2
	v_mov_b32_e32 v62, v2
	v_mov_b32_e32 v63, v2
	v_mov_b32_e32 v64, v2
	v_mov_b32_e32 v65, v2
	v_mov_b32_e32 v66, v2
	v_mov_b32_e32 v67, v2
	v_mov_b32_e32 v68, v2
	v_mov_b32_e32 v69, v2
	v_mov_b32_e32 v70, v2
	v_mov_b32_e32 v71, v2
	v_mov_b32_e32 v72, v2
	v_mov_b32_e32 v73, v2
	v_mov_b32_e32 v82, v2
	v_mov_b32_e32 v83, v2
	v_mov_b32_e32 v84, v2
	v_mov_b32_e32 v85, v2
	v_mov_b32_e32 v86, v2
	v_mov_b32_e32 v87, v2
	v_mov_b32_e32 v88, v2
	v_mov_b32_e32 v89, v2
	v_mov_b32_e32 v98, v2
	v_mov_b32_e32 v99, v2
	v_mov_b32_e32 v100, v2
	v_mov_b32_e32 v101, v2
	v_mov_b32_e32 v102, v2
	v_mov_b32_e32 v103, v2
	v_mov_b32_e32 v104, v2
	v_mov_b32_e32 v105, v2
	v_mov_b32_e32 v114, v2
	v_mov_b32_e32 v115, v2
	v_mov_b32_e32 v116, v2
	v_mov_b32_e32 v117, v2
	v_mov_b32_e32 v118, v2
	v_mov_b32_e32 v119, v2
	v_mov_b32_e32 v120, v2
	v_mov_b32_e32 v121, v2
	v_mov_b32_e32 v74, v2
	v_mov_b32_e32 v75, v2
	v_mov_b32_e32 v76, v2
	v_mov_b32_e32 v77, v2
	v_mov_b32_e32 v78, v2
	v_mov_b32_e32 v79, v2
	v_mov_b32_e32 v80, v2
	v_mov_b32_e32 v81, v2
	v_mov_b32_e32 v90, v2
	v_mov_b32_e32 v91, v2
	v_mov_b32_e32 v92, v2
	v_mov_b32_e32 v93, v2
	v_mov_b32_e32 v94, v2
	v_mov_b32_e32 v95, v2
	v_mov_b32_e32 v96, v2
	v_mov_b32_e32 v97, v2
	v_mov_b32_e32 v106, v2
	v_mov_b32_e32 v107, v2
	v_mov_b32_e32 v108, v2
	v_mov_b32_e32 v109, v2
	v_mov_b32_e32 v110, v2
	v_mov_b32_e32 v111, v2
	v_mov_b32_e32 v112, v2
	v_mov_b32_e32 v113, v2
	v_mov_b32_e32 v122, v2
	v_mov_b32_e32 v123, v2
	v_mov_b32_e32 v124, v2
	v_mov_b32_e32 v125, v2
	v_mov_b32_e32 v126, v2
	v_mov_b32_e32 v127, v2
	v_mov_b32_e32 v128, v2
	v_mov_b32_e32 v129, v2
	v_readfirstlane_b32 vcc_lo, v145
	s_cmp_lt_u32 vcc_lo, 0x100
	s_cbranch_scc1 .Lgprio_up
	s_setprio 1
.Lgprio_up:
	v_or_b32_e32 v159, 0x10000, v140
	v_add_u32_e32 v164, 0x10400, v140
	ds_read_b128 v[160:163], v159
	ds_read_b128 v[164:167], v164
	v_add_u32_e32 v159, 0x10800, v140
	v_add_u32_e32 v172, 0x10c00, v140
	ds_read_b128 v[168:171], v159
	ds_read_b128 v[172:175], v172
.LBB0_2473:
	s_add_u32 s20, s18, 0xfffc0080
	s_addc_u32 s21, s19, -1
	s_cmp_eq_u32 s51, 12
	s_cselect_b32 s23, s13, s21
	s_cselect_b32 s22, s47, s20
	s_cselect_b32 s21, s11, s50
	s_cselect_b32 s20, s48, s49
	v_lshl_add_u64 v[188:189], s[18:19], 0, v[134:135]
	s_add_i32 m0, s27, 0xc000
	ds_read_b128 v[176:179], v139
	ds_read_b128 v[180:183], v139 offset:1024
	ds_read_b128 v[184:187], v139 offset:2048
	ds_read_b128 v[202:205], v139 offset:3072
	ds_read_b128 v[206:209], v139 offset:4096
	ds_read_b128 v[210:213], v139 offset:5120
	ds_read_b128 v[214:217], v139 offset:6144
	ds_read_b128 v[218:221], v139 offset:7168
	global_load_lds_dwordx4 v[188:189], off
	v_lshl_add_u64 v[188:189], s[18:19], 0, v[136:137]
	s_add_i32 m0, s27, 0xe000
	s_nop 0
	global_load_lds_dwordx4 v[188:189], off
	s_waitcnt lgkmcnt(8)
	s_barrier
	s_waitcnt lgkmcnt(0)
	s_nop 0
	s_waitcnt lgkmcnt(0)
	v_mfma_f32_16x16x32_f16 v[126:129], v[160:163], v[176:179], v[126:129]
	v_mfma_f32_16x16x32_f16 v[122:125], v[168:171], v[176:179], v[122:125]
	v_mfma_f32_16x16x32_f16 v[110:113], v[160:163], v[184:187], v[110:113]
	v_mfma_f32_16x16x32_f16 v[106:109], v[168:171], v[184:187], v[106:109]
	v_mfma_f32_16x16x32_f16 v[94:97], v[160:163], v[206:209], v[94:97]
	v_mfma_f32_16x16x32_f16 v[90:93], v[168:171], v[206:209], v[90:93]
	v_mfma_f32_16x16x32_f16 v[78:81], v[160:163], v[214:217], v[78:81]
	v_mfma_f32_16x16x32_f16 v[74:77], v[168:171], v[214:217], v[74:77]
	v_mfma_f32_16x16x32_f16 v[126:129], v[164:167], v[180:183], v[126:129]
	v_mfma_f32_16x16x32_f16 v[122:125], v[172:175], v[180:183], v[122:125]
	v_mfma_f32_16x16x32_f16 v[110:113], v[164:167], v[202:205], v[110:113]
	v_mfma_f32_16x16x32_f16 v[106:109], v[172:175], v[202:205], v[106:109]
	v_mfma_f32_16x16x32_f16 v[94:97], v[164:167], v[210:213], v[94:97]
	v_mfma_f32_16x16x32_f16 v[90:93], v[172:175], v[210:213], v[90:93]
	v_mfma_f32_16x16x32_f16 v[78:81], v[164:167], v[218:221], v[78:81]
	v_mfma_f32_16x16x32_f16 v[74:77], v[172:175], v[218:221], v[74:77]
	s_nop 0
	s_barrier
; #define G8_STAGE(bufoff, gbase) do { _Pragma("unroll") for (int _i = 0; _i < 2; ++_i) \
;     __builtin_amdgcn_global_load_lds((const unsigned*)((const char*)(gbase) + voffA[_i]), (LAS unsigned*)(lds + (bufoff) + ldsw + _i * 8192), 16, 0, 0); } while (0)
; #define G8_LDA(dst, b, h) do { _Pragma("unroll") for (int m = 0; m < 4; ++m) _Pragma("unroll") for (int k = 0; k < 2; ++k) dst[m][k] = *(const LAS h16x8*)(lds + G8_SA(b, h) + aoff + m * 2048 + k * 1024); } while (0)
; #define G8_LDB(dst, b, h) do { _Pragma("unroll") for (int n = 0; n < 2; ++n) _Pragma("unroll") for (int k = 0; k < 2; ++k) dst[n][k] = *(const LAS h16x8*)(lds + G8_SB(b, h) + boff + n * 2048 + k * 1024); } while (0)
; #define G8_MMA(ai, bj, At, Bt_) do { __builtin_amdgcn_s_setprio(1); _Pragma("unroll") for (int m = 0; m < 4; ++m) _Pragma("unroll") for (int n = 0; n < 2; ++n) _Pragma("unroll") for (int k = 0; k < 2; ++k) \
;     acc[ai][bj][m][n] = __builtin_amdgcn_mfma_f32_16x16x32_f16(Bt_[n][k], At[m][k], acc[ai][bj][m][n], 0, 0, 0); __builtin_amdgcn_s_setprio(0); } while (0)
; #define G8_WAIT_V(n) asm volatile("s_waitcnt vmcnt(" #n ")" ::: "memory")
; #define G8_WAIT_L(n) asm volatile("s_waitcnt lgkmcnt(" #n ")" ::: "memory")
; #define G8_BAR __builtin_amdgcn_s_barrier()
; #define G8_SCHED __builtin_amdgcn_sched_barrier(0)
; template <class Epi>
; __device__ __forceinline__ void gemm_phase(LAS unsigned char* lds, const h16* A, const h16* Bt, int K, const Order& S, const Epi& E) {
;     ...
;       G8_LDB(B1, 0, 1); G8_STAGE(G8_SB(0, 0), b2);
;       G8_BAR; G8_WAIT_L(0); G8_MMA(0, 1, At, B1); G8_BAR;
;       G8_LDA(At, 0, 1); G8_STAGE(G8_SA(0, 0), a2);
;       G8_BAR; G8_WAIT_L(0); G8_MMA(1, 0, At, B0); G8_BAR; G8_SCHED;
;       G8_STAGE(G8_SB(0, 1), b2 + hstep);
;       G8_WAIT_V(6); G8_BAR; G8_MMA(1, 1, At, B1); G8_BAR;
;       G8_LDB(B0, 1, 0); G8_SCHED; G8_LDA(At, 1, 0); G8_STAGE(G8_SA(0, 1), a2 + hstep);
;       G8_WAIT_L(8); G8_BAR; G8_WAIT_L(0); G8_MMA(0, 0, At, B0); G8_BAR; G8_SCHED;
	v_or_b32_e32 v159, 0x14000, v140
	v_add_u32_e32 v188, 0x14400, v140
	ds_read_b128 v[222:225], v159
	ds_read_b128 v[226:229], v188
	v_add_u32_e32 v159, 0x14800, v140
	v_add_u32_e32 v188, 0x14c00, v140
	s_mov_b32 m0, s28
	ds_read_b128 v[230:233], v159
	ds_read_b128 v[234:237], v188
	v_lshl_add_u64 v[188:189], s[20:21], 0, v[132:133]
	global_load_lds_dwordx4 v[188:189], off
	v_lshl_add_u64 v[238:239], s[20:21], 0, v[130:131]
	s_mov_b32 m0, s29
	s_nop 0
	global_load_lds_dwordx4 v[238:239], off
	s_barrier
	s_waitcnt lgkmcnt(0)
	s_nop 0
	s_waitcnt lgkmcnt(0)
	v_mfma_f32_16x16x32_f16 v[118:121], v[222:225], v[176:179], v[118:121]
	v_mfma_f32_16x16x32_f16 v[114:117], v[230:233], v[176:179], v[114:117]
	v_mfma_f32_16x16x32_f16 v[102:105], v[222:225], v[184:187], v[102:105]
	v_mfma_f32_16x16x32_f16 v[98:101], v[230:233], v[184:187], v[98:101]
	v_mfma_f32_16x16x32_f16 v[86:89], v[222:225], v[206:209], v[86:89]
	v_mfma_f32_16x16x32_f16 v[82:85], v[230:233], v[206:209], v[82:85]
	v_mfma_f32_16x16x32_f16 v[70:73], v[222:225], v[214:217], v[70:73]
	v_mfma_f32_16x16x32_f16 v[66:69], v[230:233], v[214:217], v[66:69]
	v_mfma_f32_16x16x32_f16 v[118:121], v[226:229], v[180:183], v[118:121]
	v_mfma_f32_16x16x32_f16 v[114:117], v[234:237], v[180:183], v[114:117]
	v_mfma_f32_16x16x32_f16 v[102:105], v[226:229], v[202:205], v[102:105]
	v_mfma_f32_16x16x32_f16 v[98:101], v[234:237], v[202:205], v[98:101]
	v_mfma_f32_16x16x32_f16 v[86:89], v[226:229], v[210:213], v[86:89]
	v_mfma_f32_16x16x32_f16 v[82:85], v[234:237], v[210:213], v[82:85]
	v_mfma_f32_16x16x32_f16 v[70:73], v[226:229], v[218:221], v[70:73]
	v_mfma_f32_16x16x32_f16 v[66:69], v[234:237], v[218:221], v[66:69]
	s_nop 0
	s_mov_b32 m0, s27
	v_lshl_add_u64 v[240:241], s[22:23], 0, v[132:133]
	s_barrier
	ds_read_b128 v[176:179], v139 offset:16384
	ds_read_b128 v[180:183], v139 offset:17408
	ds_read_b128 v[184:187], v139 offset:18432
	ds_read_b128 v[202:205], v139 offset:19456
	ds_read_b128 v[206:209], v139 offset:20480
	ds_read_b128 v[210:213], v139 offset:21504
	ds_read_b128 v[214:217], v139 offset:22528
	ds_read_b128 v[218:221], v139 offset:23552
	global_load_lds_dwordx4 v[240:241], off
	v_lshl_add_u64 v[242:243], s[22:23], 0, v[130:131]
	s_mov_b32 m0, s30
	s_nop 0
	global_load_lds_dwordx4 v[242:243], off
	s_waitcnt vmcnt(10)
	s_barrier
	s_waitcnt lgkmcnt(0)
	s_nop 0
	s_waitcnt lgkmcnt(0)
	v_mfma_f32_16x16x32_f16 v[62:65], v[160:163], v[176:179], v[62:65]
	v_mfma_f32_16x16x32_f16 v[58:61], v[168:171], v[176:179], v[58:61]
	v_mfma_f32_16x16x32_f16 v[46:49], v[160:163], v[184:187], v[46:49]
	v_mfma_f32_16x16x32_f16 v[42:45], v[168:171], v[184:187], v[42:45]
	v_mfma_f32_16x16x32_f16 v[30:33], v[160:163], v[206:209], v[30:33]
	v_mfma_f32_16x16x32_f16 v[26:29], v[168:171], v[206:209], v[26:29]
	v_mfma_f32_16x16x32_f16 v[14:17], v[160:163], v[214:217], v[14:17]
	v_mfma_f32_16x16x32_f16 v[10:13], v[168:171], v[214:217], v[10:13]
	v_mfma_f32_16x16x32_f16 v[62:65], v[164:167], v[180:183], v[62:65]
	v_mfma_f32_16x16x32_f16 v[58:61], v[172:175], v[180:183], v[58:61]
	v_mfma_f32_16x16x32_f16 v[46:49], v[164:167], v[202:205], v[46:49]
	v_mfma_f32_16x16x32_f16 v[42:45], v[172:175], v[202:205], v[42:45]
	v_mfma_f32_16x16x32_f16 v[30:33], v[164:167], v[210:213], v[30:33]
	v_mfma_f32_16x16x32_f16 v[26:29], v[172:175], v[210:213], v[26:29]
	v_mfma_f32_16x16x32_f16 v[14:17], v[164:167], v[218:221], v[14:17]
	v_mfma_f32_16x16x32_f16 v[10:13], v[172:175], v[218:221], v[10:13]
	s_nop 0
	s_barrier
	s_add_u32 s52, s20, 0x40000
	s_addc_u32 s53, s21, 0
	s_mov_b32 m0, s31
	v_lshl_add_u64 v[160:161], s[52:53], 0, v[132:133]
	global_load_lds_dwordx4 v[160:161], off
	v_lshl_add_u64 v[160:161], s[52:53], 0, v[130:131]
	s_mov_b32 m0, s34
	s_nop 0
	global_load_lds_dwordx4 v[160:161], off
	v_or_b32_e32 v159, 0x18000, v140
	v_add_u32_e32 v164, 0x18400, v140
	ds_read_b128 v[160:163], v159
	ds_read_b128 v[164:167], v164
	v_add_u32_e32 v159, 0x18800, v140
	v_add_u32_e32 v172, 0x18c00, v140
	ds_read_b128 v[168:171], v159
	ds_read_b128 v[172:175], v172
	s_waitcnt vmcnt(6)
	s_barrier
	s_nop 0
	v_mfma_f32_16x16x32_f16 v[54:57], v[222:225], v[176:179], v[54:57]
	v_mfma_f32_16x16x32_f16 v[50:53], v[230:233], v[176:179], v[50:53]
	v_mfma_f32_16x16x32_f16 v[38:41], v[222:225], v[184:187], v[38:41]
	v_mfma_f32_16x16x32_f16 v[34:37], v[230:233], v[184:187], v[34:37]
	v_mfma_f32_16x16x32_f16 v[22:25], v[222:225], v[206:209], v[22:25]
	v_mfma_f32_16x16x32_f16 v[18:21], v[230:233], v[206:209], v[18:21]
	v_mfma_f32_16x16x32_f16 v[6:9], v[222:225], v[214:217], v[6:9]
	v_mfma_f32_16x16x32_f16 v[2:5], v[230:233], v[214:217], v[2:5]
	v_mfma_f32_16x16x32_f16 v[54:57], v[226:229], v[180:183], v[54:57]
	v_mfma_f32_16x16x32_f16 v[50:53], v[234:237], v[180:183], v[50:53]
	v_mfma_f32_16x16x32_f16 v[38:41], v[226:229], v[202:205], v[38:41]
	v_mfma_f32_16x16x32_f16 v[34:37], v[234:237], v[202:205], v[34:37]
	v_mfma_f32_16x16x32_f16 v[22:25], v[226:229], v[210:213], v[22:25]
	v_mfma_f32_16x16x32_f16 v[18:21], v[234:237], v[210:213], v[18:21]
	v_mfma_f32_16x16x32_f16 v[6:9], v[226:229], v[218:221], v[6:9]
	v_mfma_f32_16x16x32_f16 v[2:5], v[234:237], v[218:221], v[2:5]
	s_nop 0
	s_barrier
	s_add_u32 s22, s22, 0x40000
	s_addc_u32 s23, s23, 0
	s_mov_b32 m0, s35
	v_lshl_add_u64 v[222:223], s[22:23], 0, v[132:133]
	ds_read_b128 v[176:179], v139 offset:32768
	ds_read_b128 v[180:183], v139 offset:33792
	ds_read_b128 v[184:187], v139 offset:34816
	ds_read_b128 v[202:205], v139 offset:35840
	ds_read_b128 v[206:209], v139 offset:36864
	ds_read_b128 v[210:213], v139 offset:37888
	ds_read_b128 v[214:217], v139 offset:38912
	ds_read_b128 v[218:221], v139 offset:39936
	global_load_lds_dwordx4 v[222:223], off
	v_lshl_add_u64 v[222:223], s[22:23], 0, v[130:131]
	s_mov_b32 m0, s36
	s_nop 0
	global_load_lds_dwordx4 v[222:223], off
	s_waitcnt lgkmcnt(8)
	s_barrier
; #define G8_STAGE(bufoff, gbase) do { _Pragma("unroll") for (int _i = 0; _i < 2; ++_i) \
;     __builtin_amdgcn_global_load_lds((const unsigned*)((const char*)(gbase) + voffA[_i]), (LAS unsigned*)(lds + (bufoff) + ldsw + _i * 8192), 16, 0, 0); } while (0)
; #define G8_LDA(dst, b, h) do { _Pragma("unroll") for (int m = 0; m < 4; ++m) _Pragma("unroll") for (int k = 0; k < 2; ++k) dst[m][k] = *(const LAS h16x8*)(lds + G8_SA(b, h) + aoff + m * 2048 + k * 1024); } while (0)
; #define G8_LDB(dst, b, h) do { _Pragma("unroll") for (int n = 0; n < 2; ++n) _Pragma("unroll") for (int k = 0; k < 2; ++k) dst[n][k] = *(const LAS h16x8*)(lds + G8_SB(b, h) + boff + n * 2048 + k * 1024); } while (0)
; #define G8_MMA(ai, bj, At, Bt_) do { __builtin_amdgcn_s_setprio(1); _Pragma("unroll") for (int m = 0; m < 4; ++m) _Pragma("unroll") for (int n = 0; n < 2; ++n) _Pragma("unroll") for (int k = 0; k < 2; ++k) \
;     acc[ai][bj][m][n] = __builtin_amdgcn_mfma_f32_16x16x32_f16(Bt_[n][k], At[m][k], acc[ai][bj][m][n], 0, 0, 0); __builtin_amdgcn_s_setprio(0); } while (0)
; #define G8_WAIT_L(n) asm volatile("s_waitcnt lgkmcnt(" #n ")" ::: "memory")
; #define G8_BAR __builtin_amdgcn_s_barrier()
; #define G8_SCHED __builtin_amdgcn_sched_barrier(0)
; template <class Epi>
; __device__ __forceinline__ void gemm_phase(LAS unsigned char* lds, const h16* A, const h16* Bt, int K, const Order& S, const Epi& E) {
;     ...
;       G8_WAIT_L(8); G8_BAR; G8_WAIT_L(0); G8_MMA(0, 0, At, B0); G8_BAR; G8_SCHED;
;       G8_LDB(B1, 1, 1); G8_STAGE(G8_SB(1, 0), b3);
;       G8_BAR; G8_WAIT_L(0); G8_MMA(0, 1, At, B1); G8_BAR;
;       G8_LDA(At, 1, 1); G8_STAGE(G8_SA(1, 0), a3);
;       G8_BAR; G8_WAIT_L(0); G8_MMA(1, 0, At, B0); G8_BAR; G8_SCHED;
	s_waitcnt lgkmcnt(0)
	s_nop 0
	s_waitcnt lgkmcnt(0)
	v_mfma_f32_16x16x32_f16 v[126:129], v[160:163], v[176:179], v[126:129]
	v_mfma_f32_16x16x32_f16 v[122:125], v[168:171], v[176:179], v[122:125]
	v_mfma_f32_16x16x32_f16 v[110:113], v[160:163], v[184:187], v[110:113]
	v_mfma_f32_16x16x32_f16 v[106:109], v[168:171], v[184:187], v[106:109]
	v_mfma_f32_16x16x32_f16 v[94:97], v[160:163], v[206:209], v[94:97]
	v_mfma_f32_16x16x32_f16 v[90:93], v[168:171], v[206:209], v[90:93]
	v_mfma_f32_16x16x32_f16 v[78:81], v[160:163], v[214:217], v[78:81]
	v_mfma_f32_16x16x32_f16 v[74:77], v[168:171], v[214:217], v[74:77]
	v_mfma_f32_16x16x32_f16 v[126:129], v[164:167], v[180:183], v[126:129]
	v_mfma_f32_16x16x32_f16 v[122:125], v[172:175], v[180:183], v[122:125]
	v_mfma_f32_16x16x32_f16 v[110:113], v[164:167], v[202:205], v[110:113]
	v_mfma_f32_16x16x32_f16 v[106:109], v[172:175], v[202:205], v[106:109]
	v_mfma_f32_16x16x32_f16 v[94:97], v[164:167], v[210:213], v[94:97]
	v_mfma_f32_16x16x32_f16 v[90:93], v[172:175], v[210:213], v[90:93]
	v_mfma_f32_16x16x32_f16 v[78:81], v[164:167], v[218:221], v[78:81]
	v_mfma_f32_16x16x32_f16 v[74:77], v[172:175], v[218:221], v[74:77]
	s_nop 0
	s_barrier
	v_or_b32_e32 v159, 0x1c000, v140
	s_mov_b32 m0, s37
	v_add_u32_e32 v195, 0x1c400, v140
	ds_read_b128 v[222:225], v159
	ds_read_b128 v[226:229], v195
	v_add_u32_e32 v159, 0x1c800, v140
	v_lshl_add_u64 v[188:189], v[188:189], 0, s[94:95]
	v_add_u32_e32 v195, 0x1cc00, v140
	ds_read_b128 v[230:233], v159
	ds_read_b128 v[234:237], v195
	global_load_lds_dwordx4 v[188:189], off
	v_lshl_add_u64 v[188:189], v[238:239], 0, s[94:95]
	s_mov_b32 m0, s38
	s_nop 0
	global_load_lds_dwordx4 v[188:189], off
	s_barrier
	s_waitcnt lgkmcnt(0)
	s_nop 0
	s_waitcnt lgkmcnt(0)
	v_mfma_f32_16x16x32_f16 v[118:121], v[222:225], v[176:179], v[118:121]
	v_mfma_f32_16x16x32_f16 v[114:117], v[230:233], v[176:179], v[114:117]
	v_mfma_f32_16x16x32_f16 v[102:105], v[222:225], v[184:187], v[102:105]
	v_mfma_f32_16x16x32_f16 v[98:101], v[230:233], v[184:187], v[98:101]
	v_mfma_f32_16x16x32_f16 v[86:89], v[222:225], v[206:209], v[86:89]
	v_mfma_f32_16x16x32_f16 v[82:85], v[230:233], v[206:209], v[82:85]
	v_mfma_f32_16x16x32_f16 v[70:73], v[222:225], v[214:217], v[70:73]
	v_mfma_f32_16x16x32_f16 v[66:69], v[230:233], v[214:217], v[66:69]
	v_mfma_f32_16x16x32_f16 v[118:121], v[226:229], v[180:183], v[118:121]
	v_mfma_f32_16x16x32_f16 v[114:117], v[234:237], v[180:183], v[114:117]
	v_mfma_f32_16x16x32_f16 v[102:105], v[226:229], v[202:205], v[102:105]
	v_mfma_f32_16x16x32_f16 v[98:101], v[234:237], v[202:205], v[98:101]
	v_mfma_f32_16x16x32_f16 v[86:89], v[226:229], v[210:213], v[86:89]
	v_mfma_f32_16x16x32_f16 v[82:85], v[234:237], v[210:213], v[82:85]
	v_mfma_f32_16x16x32_f16 v[70:73], v[226:229], v[218:221], v[70:73]
	v_mfma_f32_16x16x32_f16 v[66:69], v[234:237], v[218:221], v[66:69]
	s_nop 0
	s_mov_b32 m0, s39
	v_lshl_add_u64 v[188:189], v[240:241], 0, s[94:95]
	s_barrier
	ds_read_b128 v[176:179], v139 offset:49152
	ds_read_b128 v[180:183], v139 offset:50176
	ds_read_b128 v[184:187], v139 offset:51200
	ds_read_b128 v[202:205], v139 offset:52224
	ds_read_b128 v[206:209], v139 offset:53248
	ds_read_b128 v[210:213], v139 offset:54272
	ds_read_b128 v[214:217], v139 offset:55296
	ds_read_b128 v[218:221], v139 offset:56320
	global_load_lds_dwordx4 v[188:189], off
	v_lshl_add_u64 v[188:189], v[242:243], 0, s[94:95]
	s_mov_b32 m0, s40
	s_nop 0
	global_load_lds_dwordx4 v[188:189], off
	s_waitcnt vmcnt(10)
	s_barrier
	s_waitcnt lgkmcnt(0)
	s_nop 0
	s_waitcnt lgkmcnt(0)
	v_mfma_f32_16x16x32_f16 v[62:65], v[160:163], v[176:179], v[62:65]
	v_mfma_f32_16x16x32_f16 v[58:61], v[168:171], v[176:179], v[58:61]
	v_mfma_f32_16x16x32_f16 v[46:49], v[160:163], v[184:187], v[46:49]
	v_mfma_f32_16x16x32_f16 v[42:45], v[168:171], v[184:187], v[42:45]
	v_mfma_f32_16x16x32_f16 v[30:33], v[160:163], v[206:209], v[30:33]
	v_mfma_f32_16x16x32_f16 v[26:29], v[168:171], v[206:209], v[26:29]
	v_mfma_f32_16x16x32_f16 v[14:17], v[160:163], v[214:217], v[14:17]
	v_mfma_f32_16x16x32_f16 v[10:13], v[168:171], v[214:217], v[10:13]
	v_mfma_f32_16x16x32_f16 v[62:65], v[164:167], v[180:183], v[62:65]
	v_mfma_f32_16x16x32_f16 v[58:61], v[172:175], v[180:183], v[58:61]
	v_mfma_f32_16x16x32_f16 v[46:49], v[164:167], v[202:205], v[46:49]
	v_mfma_f32_16x16x32_f16 v[42:45], v[172:175], v[202:205], v[42:45]
	v_mfma_f32_16x16x32_f16 v[30:33], v[164:167], v[210:213], v[30:33]
	v_mfma_f32_16x16x32_f16 v[26:29], v[172:175], v[210:213], v[26:29]
	v_mfma_f32_16x16x32_f16 v[14:17], v[164:167], v[218:221], v[14:17]
	v_mfma_f32_16x16x32_f16 v[10:13], v[172:175], v[218:221], v[10:13]
	s_nop 0
	s_barrier
	s_add_u32 s20, s20, 0x40080
	s_addc_u32 s21, s21, 0
	s_mov_b32 m0, s41
	v_lshl_add_u64 v[160:161], s[20:21], 0, v[132:133]
	global_load_lds_dwordx4 v[160:161], off
	v_lshl_add_u64 v[160:161], s[20:21], 0, v[130:131]
	s_mov_b32 m0, s42
	s_nop 0
	global_load_lds_dwordx4 v[160:161], off
	v_or_b32_e32 v159, 0x10000, v140
	v_add_u32_e32 v164, 0x10400, v140
	ds_read_b128 v[160:163], v159
	ds_read_b128 v[164:167], v164
	v_add_u32_e32 v159, 0x10800, v140
	v_add_u32_e32 v172, 0x10c00, v140
	ds_read_b128 v[168:171], v159
	ds_read_b128 v[172:175], v172
	s_waitcnt vmcnt(6)
	s_barrier
; #define G8_MMA(ai, bj, At, Bt_) do { __builtin_amdgcn_s_setprio(1); _Pragma("unroll") for (int m = 0; m < 4; ++m) _Pragma("unroll") for (int n = 0; n < 2; ++n) _Pragma("unroll") for (int k = 0; k < 2; ++k) \
;     acc[ai][bj][m][n] = __builtin_amdgcn_mfma_f32_16x16x32_f16(Bt_[n][k], At[m][k], acc[ai][bj][m][n], 0, 0, 0); __builtin_amdgcn_s_setprio(0); } while (0)
; #define G8_WAIT_V(n) asm volatile("s_waitcnt vmcnt(" #n ")" ::: "memory")
; #define G8_BAR __builtin_amdgcn_s_barrier()
; template <class Epi>
; __device__ __forceinline__ void gemm_phase(LAS unsigned char* lds, const h16* A, const h16* Bt, int K, const Order& S, const Epi& E) {
;     ...
;       G8_WAIT_V(6); G8_BAR; G8_MMA(1, 1, At, B1); G8_BAR;
;     }
;   __device__ __forceinline__ void operator()(const f32x4 (&acc)[2][2][4][2], const g8::Unit& u, int ui, int wr, int wc, int fr, int fq) const {
; #pragma unroll
;     for (int ai = 0; ai < 2; ++ai)
; #pragma unroll
;       for (int m = 0; m < 4; ++m) {
;         const int rl = 128 * ai + 64 * wr + 16 * m + fr;
;         const float r = rsl[ui * 256 + rl];
;         h16* rowp = hid + (size_t)(u.pm * 256 + rl) * DFF + 256 * u.pn + 32 * wc + 8 * fq;
; #pragma unroll
;         for (int bj = 0; bj < 2; ++bj) {
;           f32x4 v[2];
; #pragma unroll
;           for (int n = 0; n < 2; ++n) {
;             v[n] = acc[ai][bj][m][n] * r;
; #pragma unroll
;             for (int j = 0; j < 4; ++j) { const float t = fmaxf(v[n][j], 0.f); v[n][j] = t * t; }
;           }
;           __builtin_nontemporal_store(pack8(v[0], v[1]), (h16x8*)(rowp + 128 * bj));
;         }
;       }
;   }
	s_nop 0
	v_mfma_f32_16x16x32_f16 v[54:57], v[222:225], v[176:179], v[54:57]
	v_mfma_f32_16x16x32_f16 v[50:53], v[230:233], v[176:179], v[50:53]
	v_mfma_f32_16x16x32_f16 v[38:41], v[222:225], v[184:187], v[38:41]
	v_mfma_f32_16x16x32_f16 v[34:37], v[230:233], v[184:187], v[34:37]
	v_mfma_f32_16x16x32_f16 v[22:25], v[222:225], v[206:209], v[22:25]
	v_mfma_f32_16x16x32_f16 v[18:21], v[230:233], v[206:209], v[18:21]
	v_mfma_f32_16x16x32_f16 v[6:9], v[222:225], v[214:217], v[6:9]
	v_mfma_f32_16x16x32_f16 v[2:5], v[230:233], v[214:217], v[2:5]
	v_mfma_f32_16x16x32_f16 v[54:57], v[226:229], v[180:183], v[54:57]
	v_mfma_f32_16x16x32_f16 v[50:53], v[234:237], v[180:183], v[50:53]
	v_mfma_f32_16x16x32_f16 v[38:41], v[226:229], v[202:205], v[38:41]
	v_mfma_f32_16x16x32_f16 v[34:37], v[234:237], v[202:205], v[34:37]
	v_mfma_f32_16x16x32_f16 v[22:25], v[226:229], v[210:213], v[22:25]
	v_mfma_f32_16x16x32_f16 v[18:21], v[234:237], v[210:213], v[18:21]
	v_mfma_f32_16x16x32_f16 v[6:9], v[226:229], v[218:221], v[6:9]
	v_mfma_f32_16x16x32_f16 v[2:5], v[234:237], v[218:221], v[2:5]
	s_nop 0
	s_add_i32 s51, s51, 2
	s_add_u32 s18, s18, 0x100
	s_addc_u32 s19, s19, 0
	s_add_u32 s49, s49, 0x100
	s_addc_u32 s50, s50, 0
	s_cmp_gt_u32 s51, 13
	s_barrier
	s_cbranch_scc0 .LBB0_2473
	s_waitcnt lgkmcnt(0)
	s_setprio 0
	v_lshl_add_u32 v159, s44, 10, v158
	s_waitcnt vmcnt(0)
	ds_read2_b32 v[160:161], v159 offset1:16
	s_lshl_b32 s11, s46, 8
	v_add_u32_e32 v162, s11, v138
	s_lshl_b32 s18, s45, 8
	v_ashrrev_i32_e32 v163, 31, v162
	s_waitcnt lgkmcnt(0)
	v_pk_mul_f32 v[128:129], v[128:129], v[160:161] op_sel_hi:[1,0]
	v_pk_mul_f32 v[126:127], v[126:127], v[160:161] op_sel_hi:[1,0]
	v_pk_mul_f32 v[122:123], v[122:123], v[160:161] op_sel_hi:[1,0]
	v_max_f32_e32 v166, 0, v126
	v_max_f32_e32 v126, 0, v127
	v_max_f32_e32 v127, 0, v128
	v_max_f32_e32 v128, 0, v129
	v_pk_mul_f32 v[124:125], v[124:125], v[160:161] op_sel_hi:[1,0]
	v_max_f32_e32 v129, 0, v122
	v_max_f32_e32 v164, 0, v123
	v_pk_mul_f32 v[122:123], v[126:127], v[126:127]
	v_max_f32_e32 v165, 0, v124
	v_fma_mixlo_f16 v124, v166, v166, 0
	v_cvt_pk_f16_f32 v123, v122, v123
	s_ashr_i32 s19, s18, 31
	v_lshlrev_b64 v[162:163], 13, v[162:163]
	v_max_f32_e32 v167, 0, v125
	v_pack_b32_f16 v122, v124, v123
	v_pk_mul_f32 v[124:125], v[128:129], v[128:129]
	v_lshl_add_u64 v[162:163], s[0:1], 0, v[162:163]
	s_lshl_b64 s[18:19], s[18:19], 1
	v_cvt_pk_f16_f32 v126, v124, v125
	v_pk_mul_f32 v[124:125], v[164:165], v[164:165]
	v_lshl_add_u64 v[162:163], v[162:163], 0, s[18:19]
	v_cvt_pk_f16_f32 v125, v124, v125
	v_lshl_add_u64 v[162:163], v[162:163], 0, s[92:93]
	v_alignbit_b32 v124, v125, v126, 16
	v_lshrrev_b32_e32 v125, 16, v125
	v_lshl_add_u64 v[162:163], v[162:163], 0, v[0:1]
	v_alignbit_b32 v123, v126, v123, 16
	v_fma_mixhi_f16 v125, v167, v167, 0
	v_pk_mul_f32 v[120:121], v[120:121], v[160:161] op_sel_hi:[1,0]
	v_pk_mul_f32 v[118:119], v[118:119], v[160:161] op_sel_hi:[1,0]
	global_store_dwordx4 v[162:163], v[122:125], off nt
	v_pk_mul_f32 v[114:115], v[114:115], v[160:161] op_sel_hi:[1,0]
	v_pk_mul_f32 v[116:117], v[116:117], v[160:161] op_sel_hi:[1,0]
	v_max_f32_e32 v124, 0, v118
	v_max_f32_e32 v118, 0, v119
	v_max_f32_e32 v119, 0, v120
	v_max_f32_e32 v120, 0, v121
	v_max_f32_e32 v121, 0, v114
	v_max_f32_e32 v122, 0, v115
	v_pk_mul_f32 v[114:115], v[118:119], v[118:119]
	v_max_f32_e32 v123, 0, v116
	v_fma_mixlo_f16 v116, v124, v124, 0
	v_cvt_pk_f16_f32 v115, v114, v115
	v_max_f32_e32 v125, 0, v117
	v_pack_b32_f16 v114, v116, v115
	v_pk_mul_f32 v[116:117], v[120:121], v[120:121]
	s_and_b64 vcc, exec, s[6:7]
	v_cvt_pk_f16_f32 v118, v116, v117
	v_pk_mul_f32 v[116:117], v[122:123], v[122:123]
	v_alignbit_b32 v115, v118, v115, 16
	v_cvt_pk_f16_f32 v117, v116, v117
	v_alignbit_b32 v116, v117, v118, 16
	v_lshrrev_b32_e32 v117, 16, v117
	v_fma_mixhi_f16 v117, v125, v125, 0
	global_store_dwordx4 v[162:163], v[114:117], off offset:256 nt
	s_mov_b32 s45, s10
	s_mov_b32 s46, s12
	v_mov_b32_e32 v116, v161
	v_pk_mul_f32 v[110:111], v[110:111], v[116:117] op_sel_hi:[1,0]
	v_pk_mul_f32 v[112:113], v[112:113], v[116:117] op_sel_hi:[1,0]
	v_max_f32_e32 v117, 0, v110
	v_max_f32_e32 v110, 0, v111
	v_max_f32_e32 v111, 0, v112
	v_pk_mul_f32 v[106:107], v[106:107], v[116:117] op_sel_hi:[1,0]
	v_add_u32_e32 v114, s11, v141
	v_max_f32_e32 v112, 0, v113
	v_pk_mul_f32 v[108:109], v[108:109], v[116:117] op_sel_hi:[1,0]
	v_max_f32_e32 v113, 0, v106
	v_max_f32_e32 v118, 0, v107
	v_pk_mul_f32 v[106:107], v[110:111], v[110:111]
	v_ashrrev_i32_e32 v115, 31, v114
	v_max_f32_e32 v119, 0, v108
	v_fma_mixlo_f16 v108, v117, v117, 0
	v_cvt_pk_f16_f32 v107, v106, v107
	v_lshlrev_b64 v[114:115], 13, v[114:115]
	v_max_f32_e32 v120, 0, v109
	v_pack_b32_f16 v106, v108, v107
	v_pk_mul_f32 v[108:109], v[112:113], v[112:113]
	v_lshl_add_u64 v[114:115], s[0:1], 0, v[114:115]
	v_cvt_pk_f16_f32 v110, v108, v109
	v_pk_mul_f32 v[108:109], v[118:119], v[118:119]
	v_lshl_add_u64 v[114:115], v[114:115], 0, s[18:19]
	v_cvt_pk_f16_f32 v109, v108, v109
	v_lshl_add_u64 v[114:115], v[114:115], 0, s[92:93]
	v_alignbit_b32 v108, v109, v110, 16
	v_lshrrev_b32_e32 v109, 16, v109
	v_lshl_add_u64 v[114:115], v[114:115], 0, v[0:1]
	v_alignbit_b32 v107, v110, v107, 16
	v_fma_mixhi_f16 v109, v120, v120, 0
	v_pk_mul_f32 v[104:105], v[104:105], v[116:117] op_sel_hi:[1,0]
	v_pk_mul_f32 v[102:103], v[102:103], v[116:117] op_sel_hi:[1,0]
	global_store_dwordx4 v[114:115], v[106:109], off nt
	v_pk_mul_f32 v[98:99], v[98:99], v[116:117] op_sel_hi:[1,0]
	v_pk_mul_f32 v[100:101], v[100:101], v[116:117] op_sel_hi:[1,0]
	v_max_f32_e32 v108, 0, v102
	v_max_f32_e32 v102, 0, v103
	v_max_f32_e32 v103, 0, v104
	v_max_f32_e32 v104, 0, v105
	v_max_f32_e32 v105, 0, v98
	v_max_f32_e32 v106, 0, v99
	v_pk_mul_f32 v[98:99], v[102:103], v[102:103]
	v_max_f32_e32 v107, 0, v100
	v_fma_mixlo_f16 v100, v108, v108, 0
	v_cvt_pk_f16_f32 v99, v98, v99
	v_max_f32_e32 v109, 0, v101
	v_pack_b32_f16 v98, v100, v99
	v_pk_mul_f32 v[100:101], v[104:105], v[104:105]
	s_mov_b64 s[20:21], s[16:17]
	v_cvt_pk_f16_f32 v102, v100, v101
	v_pk_mul_f32 v[100:101], v[106:107], v[106:107]
	v_alignbit_b32 v99, v102, v99, 16
	v_cvt_pk_f16_f32 v101, v100, v101
	v_alignbit_b32 v100, v101, v102, 16
	v_lshrrev_b32_e32 v101, 16, v101
	v_fma_mixhi_f16 v101, v109, v109, 0
	global_store_dwordx4 v[114:115], v[98:101], off offset:256 nt
	ds_read2_b32 v[98:99], v159 offset0:32 offset1:48
	s_mov_b32 s44, s43
	v_add_u32_e32 v100, s11, v152
	v_ashrrev_i32_e32 v101, 31, v100
	v_lshlrev_b64 v[100:101], 13, v[100:101]
	s_waitcnt lgkmcnt(0)
;   __device__ __forceinline__ void operator()(const f32x4 (&acc)[2][2][4][2], const g8::Unit& u, int ui, int wr, int wc, int fr, int fq) const {
; #pragma unroll
;     for (int ai = 0; ai < 2; ++ai)
; #pragma unroll
;       for (int m = 0; m < 4; ++m) {
;         const int rl = 128 * ai + 64 * wr + 16 * m + fr;
;         const float r = rsl[ui * 256 + rl];
;         h16* rowp = hid + (size_t)(u.pm * 256 + rl) * DFF + 256 * u.pn + 32 * wc + 8 * fq;
; #pragma unroll
;         for (int bj = 0; bj < 2; ++bj) {
;           f32x4 v[2];
; #pragma unroll
;           for (int n = 0; n < 2; ++n) {
;             v[n] = acc[ai][bj][m][n] * r;
; #pragma unroll
;             for (int j = 0; j < 4; ++j) { const float t = fmaxf(v[n][j], 0.f); v[n][j] = t * t; }
;           }
;           __builtin_nontemporal_store(pack8(v[0], v[1]), (h16x8*)(rowp + 128 * bj));
;         }
;       }
;   }
	v_pk_mul_f32 v[96:97], v[96:97], v[98:99] op_sel_hi:[1,0]
	v_pk_mul_f32 v[94:95], v[94:95], v[98:99] op_sel_hi:[1,0]
	v_pk_mul_f32 v[90:91], v[90:91], v[98:99] op_sel_hi:[1,0]
	v_max_f32_e32 v104, 0, v94
	v_max_f32_e32 v94, 0, v95
	v_max_f32_e32 v95, 0, v96
	v_max_f32_e32 v96, 0, v97
	v_pk_mul_f32 v[92:93], v[92:93], v[98:99] op_sel_hi:[1,0]
	v_max_f32_e32 v97, 0, v90
	v_max_f32_e32 v102, 0, v91
	v_pk_mul_f32 v[90:91], v[94:95], v[94:95]
	v_max_f32_e32 v103, 0, v92
	v_fma_mixlo_f16 v92, v104, v104, 0
	v_cvt_pk_f16_f32 v91, v90, v91
	v_max_f32_e32 v105, 0, v93
	v_pack_b32_f16 v90, v92, v91
	v_pk_mul_f32 v[92:93], v[96:97], v[96:97]
	v_lshl_add_u64 v[100:101], s[0:1], 0, v[100:101]
	v_cvt_pk_f16_f32 v94, v92, v93
	v_pk_mul_f32 v[92:93], v[102:103], v[102:103]
	v_lshl_add_u64 v[100:101], v[100:101], 0, s[18:19]
	v_cvt_pk_f16_f32 v93, v92, v93
	v_lshl_add_u64 v[100:101], v[100:101], 0, s[92:93]
	v_alignbit_b32 v92, v93, v94, 16
	v_lshrrev_b32_e32 v93, 16, v93
	v_lshl_add_u64 v[100:101], v[100:101], 0, v[0:1]
	v_alignbit_b32 v91, v94, v91, 16
	v_fma_mixhi_f16 v93, v105, v105, 0
	v_pk_mul_f32 v[88:89], v[88:89], v[98:99] op_sel_hi:[1,0]
	v_pk_mul_f32 v[86:87], v[86:87], v[98:99] op_sel_hi:[1,0]
	global_store_dwordx4 v[100:101], v[90:93], off nt
	v_pk_mul_f32 v[82:83], v[82:83], v[98:99] op_sel_hi:[1,0]
	v_pk_mul_f32 v[84:85], v[84:85], v[98:99] op_sel_hi:[1,0]
	v_max_f32_e32 v92, 0, v86
	v_max_f32_e32 v86, 0, v87
	v_max_f32_e32 v87, 0, v88
	v_max_f32_e32 v88, 0, v89
	v_max_f32_e32 v89, 0, v82
	v_max_f32_e32 v90, 0, v83
	v_pk_mul_f32 v[82:83], v[86:87], v[86:87]
	v_max_f32_e32 v91, 0, v84
	v_fma_mixlo_f16 v84, v92, v92, 0
	v_cvt_pk_f16_f32 v83, v82, v83
	v_max_f32_e32 v93, 0, v85
	v_pack_b32_f16 v82, v84, v83
	v_pk_mul_f32 v[84:85], v[88:89], v[88:89]
	s_nop 0
	v_cvt_pk_f16_f32 v86, v84, v85
	v_pk_mul_f32 v[84:85], v[90:91], v[90:91]
	v_alignbit_b32 v83, v86, v83, 16
	v_cvt_pk_f16_f32 v85, v84, v85
	v_alignbit_b32 v84, v85, v86, 16
	v_lshrrev_b32_e32 v85, 16, v85
	v_fma_mixhi_f16 v85, v93, v93, 0
	global_store_dwordx4 v[100:101], v[82:85], off offset:256 nt
	s_nop 1
	v_mov_b32_e32 v84, v99
	v_pk_mul_f32 v[78:79], v[78:79], v[84:85] op_sel_hi:[1,0]
	v_pk_mul_f32 v[80:81], v[80:81], v[84:85] op_sel_hi:[1,0]
	v_max_f32_e32 v85, 0, v78
	v_max_f32_e32 v78, 0, v79
	v_max_f32_e32 v79, 0, v80
	v_pk_mul_f32 v[74:75], v[74:75], v[84:85] op_sel_hi:[1,0]
	v_add_u32_e32 v82, s11, v153
	v_max_f32_e32 v80, 0, v81
	v_pk_mul_f32 v[76:77], v[76:77], v[84:85] op_sel_hi:[1,0]
	v_max_f32_e32 v81, 0, v74
	v_max_f32_e32 v86, 0, v75
	v_pk_mul_f32 v[74:75], v[78:79], v[78:79]
	v_ashrrev_i32_e32 v83, 31, v82
	v_max_f32_e32 v87, 0, v76
	v_fma_mixlo_f16 v76, v85, v85, 0
	v_cvt_pk_f16_f32 v75, v74, v75
	v_lshlrev_b64 v[82:83], 13, v[82:83]
	v_max_f32_e32 v88, 0, v77
	v_pack_b32_f16 v74, v76, v75
	v_pk_mul_f32 v[76:77], v[80:81], v[80:81]
	v_lshl_add_u64 v[82:83], s[0:1], 0, v[82:83]
	v_cvt_pk_f16_f32 v78, v76, v77
	v_pk_mul_f32 v[76:77], v[86:87], v[86:87]
	v_lshl_add_u64 v[82:83], v[82:83], 0, s[18:19]
	v_cvt_pk_f16_f32 v77, v76, v77
	v_lshl_add_u64 v[82:83], v[82:83], 0, s[92:93]
	v_alignbit_b32 v76, v77, v78, 16
	v_lshrrev_b32_e32 v77, 16, v77
	v_lshl_add_u64 v[82:83], v[82:83], 0, v[0:1]
	v_alignbit_b32 v75, v78, v75, 16
	v_fma_mixhi_f16 v77, v88, v88, 0
	v_pk_mul_f32 v[72:73], v[72:73], v[84:85] op_sel_hi:[1,0]
	v_pk_mul_f32 v[70:71], v[70:71], v[84:85] op_sel_hi:[1,0]
	global_store_dwordx4 v[82:83], v[74:77], off nt
	v_pk_mul_f32 v[66:67], v[66:67], v[84:85] op_sel_hi:[1,0]
	v_pk_mul_f32 v[68:69], v[68:69], v[84:85] op_sel_hi:[1,0]
	v_max_f32_e32 v76, 0, v70
	v_max_f32_e32 v70, 0, v71
	v_max_f32_e32 v71, 0, v72
	v_max_f32_e32 v72, 0, v73
	v_max_f32_e32 v73, 0, v66
	v_max_f32_e32 v74, 0, v67
	v_pk_mul_f32 v[66:67], v[70:71], v[70:71]
	v_max_f32_e32 v75, 0, v68
	v_fma_mixlo_f16 v68, v76, v76, 0
	v_cvt_pk_f16_f32 v67, v66, v67
	v_max_f32_e32 v77, 0, v69
	v_pack_b32_f16 v66, v68, v67
	v_pk_mul_f32 v[68:69], v[72:73], v[72:73]
	s_nop 0
	v_cvt_pk_f16_f32 v70, v68, v69
	v_pk_mul_f32 v[68:69], v[74:75], v[74:75]
	v_alignbit_b32 v67, v70, v67, 16
	v_cvt_pk_f16_f32 v69, v68, v69
	v_alignbit_b32 v68, v69, v70, 16
	v_lshrrev_b32_e32 v69, 16, v69
	v_fma_mixhi_f16 v69, v77, v77, 0
	global_store_dwordx4 v[82:83], v[66:69], off offset:256 nt
	ds_read2_b32 v[66:67], v159 offset0:128 offset1:144
	s_waitcnt lgkmcnt(0)
;   __device__ __forceinline__ void operator()(const f32x4 (&acc)[2][2][4][2], const g8::Unit& u, int ui, int wr, int wc, int fr, int fq) const {
; #pragma unroll
;     for (int ai = 0; ai < 2; ++ai)
; #pragma unroll
;       for (int m = 0; m < 4; ++m) {
;         const int rl = 128 * ai + 64 * wr + 16 * m + fr;
;         const float r = rsl[ui * 256 + rl];
;         h16* rowp = hid + (size_t)(u.pm * 256 + rl) * DFF + 256 * u.pn + 32 * wc + 8 * fq;
; #pragma unroll
;         for (int bj = 0; bj < 2; ++bj) {
;           f32x4 v[2];
; #pragma unroll
;           for (int n = 0; n < 2; ++n) {
;             v[n] = acc[ai][bj][m][n] * r;
; #pragma unroll
;             for (int j = 0; j < 4; ++j) { const float t = fmaxf(v[n][j], 0.f); v[n][j] = t * t; }
;           }
;           __builtin_nontemporal_store(pack8(v[0], v[1]), (h16x8*)(rowp + 128 * bj));
;         }
;       }
;   }
	v_pk_mul_f32 v[64:65], v[64:65], v[66:67] op_sel_hi:[1,0]
	v_pk_mul_f32 v[62:63], v[62:63], v[66:67] op_sel_hi:[1,0]
	v_pk_mul_f32 v[58:59], v[58:59], v[66:67] op_sel_hi:[1,0]
	v_max_f32_e32 v72, 0, v62
	v_max_f32_e32 v62, 0, v63
	v_max_f32_e32 v63, 0, v64
	v_add_u32_e32 v68, s11, v154
	v_max_f32_e32 v64, 0, v65
	v_pk_mul_f32 v[60:61], v[60:61], v[66:67] op_sel_hi:[1,0]
	v_max_f32_e32 v65, 0, v58
	v_max_f32_e32 v70, 0, v59
	v_pk_mul_f32 v[58:59], v[62:63], v[62:63]
	v_ashrrev_i32_e32 v69, 31, v68
	v_max_f32_e32 v71, 0, v60
	v_fma_mixlo_f16 v60, v72, v72, 0
	v_cvt_pk_f16_f32 v59, v58, v59
	v_lshlrev_b64 v[68:69], 13, v[68:69]
	v_max_f32_e32 v73, 0, v61
	v_pack_b32_f16 v58, v60, v59
	v_pk_mul_f32 v[60:61], v[64:65], v[64:65]
	v_lshl_add_u64 v[68:69], s[0:1], 0, v[68:69]
	v_cvt_pk_f16_f32 v62, v60, v61
	v_pk_mul_f32 v[60:61], v[70:71], v[70:71]
	v_lshl_add_u64 v[68:69], v[68:69], 0, s[18:19]
	v_cvt_pk_f16_f32 v61, v60, v61
	v_lshl_add_u64 v[68:69], v[68:69], 0, s[92:93]
	v_alignbit_b32 v60, v61, v62, 16
	v_lshrrev_b32_e32 v61, 16, v61
	v_lshl_add_u64 v[68:69], v[68:69], 0, v[0:1]
	v_alignbit_b32 v59, v62, v59, 16
	v_fma_mixhi_f16 v61, v73, v73, 0
	v_pk_mul_f32 v[56:57], v[56:57], v[66:67] op_sel_hi:[1,0]
	v_pk_mul_f32 v[54:55], v[54:55], v[66:67] op_sel_hi:[1,0]
	global_store_dwordx4 v[68:69], v[58:61], off nt
	v_pk_mul_f32 v[50:51], v[50:51], v[66:67] op_sel_hi:[1,0]
	v_pk_mul_f32 v[52:53], v[52:53], v[66:67] op_sel_hi:[1,0]
	v_max_f32_e32 v60, 0, v54
	v_max_f32_e32 v54, 0, v55
	v_max_f32_e32 v55, 0, v56
	v_max_f32_e32 v56, 0, v57
	v_max_f32_e32 v57, 0, v50
	v_max_f32_e32 v58, 0, v51
	v_pk_mul_f32 v[50:51], v[54:55], v[54:55]
	v_max_f32_e32 v59, 0, v52
	v_fma_mixlo_f16 v52, v60, v60, 0
	v_cvt_pk_f16_f32 v51, v50, v51
	v_max_f32_e32 v61, 0, v53
	v_pack_b32_f16 v50, v52, v51
	v_pk_mul_f32 v[52:53], v[56:57], v[56:57]
	s_nop 0
	v_cvt_pk_f16_f32 v54, v52, v53
	v_pk_mul_f32 v[52:53], v[58:59], v[58:59]
	v_alignbit_b32 v51, v54, v51, 16
	v_cvt_pk_f16_f32 v53, v52, v53
	v_alignbit_b32 v52, v53, v54, 16
	v_lshrrev_b32_e32 v53, 16, v53
	v_fma_mixhi_f16 v53, v61, v61, 0
	global_store_dwordx4 v[68:69], v[50:53], off offset:256 nt
	s_nop 1
	v_mov_b32_e32 v52, v67
	v_pk_mul_f32 v[46:47], v[46:47], v[52:53] op_sel_hi:[1,0]
	v_pk_mul_f32 v[48:49], v[48:49], v[52:53] op_sel_hi:[1,0]
	v_max_f32_e32 v53, 0, v46
	v_max_f32_e32 v46, 0, v47
	v_max_f32_e32 v47, 0, v48
	v_pk_mul_f32 v[42:43], v[42:43], v[52:53] op_sel_hi:[1,0]
	v_add_u32_e32 v50, s11, v155
	v_max_f32_e32 v48, 0, v49
	v_pk_mul_f32 v[44:45], v[44:45], v[52:53] op_sel_hi:[1,0]
	v_max_f32_e32 v49, 0, v42
	v_max_f32_e32 v54, 0, v43
	v_pk_mul_f32 v[42:43], v[46:47], v[46:47]
	v_ashrrev_i32_e32 v51, 31, v50
	v_max_f32_e32 v55, 0, v44
	v_fma_mixlo_f16 v44, v53, v53, 0
	v_cvt_pk_f16_f32 v43, v42, v43
	v_lshlrev_b64 v[50:51], 13, v[50:51]
	v_max_f32_e32 v56, 0, v45
	v_pack_b32_f16 v42, v44, v43
	v_pk_mul_f32 v[44:45], v[48:49], v[48:49]
	v_lshl_add_u64 v[50:51], s[0:1], 0, v[50:51]
	v_cvt_pk_f16_f32 v46, v44, v45
	v_pk_mul_f32 v[44:45], v[54:55], v[54:55]
	v_lshl_add_u64 v[50:51], v[50:51], 0, s[18:19]
	v_cvt_pk_f16_f32 v45, v44, v45
	v_lshl_add_u64 v[50:51], v[50:51], 0, s[92:93]
	v_alignbit_b32 v44, v45, v46, 16
	v_lshrrev_b32_e32 v45, 16, v45
	v_lshl_add_u64 v[50:51], v[50:51], 0, v[0:1]
	v_alignbit_b32 v43, v46, v43, 16
	v_fma_mixhi_f16 v45, v56, v56, 0
	v_pk_mul_f32 v[40:41], v[40:41], v[52:53] op_sel_hi:[1,0]
	v_pk_mul_f32 v[38:39], v[38:39], v[52:53] op_sel_hi:[1,0]
	global_store_dwordx4 v[50:51], v[42:45], off nt
	v_pk_mul_f32 v[34:35], v[34:35], v[52:53] op_sel_hi:[1,0]
	v_pk_mul_f32 v[36:37], v[36:37], v[52:53] op_sel_hi:[1,0]
	v_max_f32_e32 v44, 0, v38
	v_max_f32_e32 v38, 0, v39
	v_max_f32_e32 v39, 0, v40
	v_max_f32_e32 v40, 0, v41
	v_max_f32_e32 v41, 0, v34
	v_max_f32_e32 v42, 0, v35
	v_pk_mul_f32 v[34:35], v[38:39], v[38:39]
	v_max_f32_e32 v43, 0, v36
	v_fma_mixlo_f16 v36, v44, v44, 0
	v_cvt_pk_f16_f32 v35, v34, v35
	v_max_f32_e32 v45, 0, v37
	v_pack_b32_f16 v34, v36, v35
	v_pk_mul_f32 v[36:37], v[40:41], v[40:41]
	s_nop 0
	v_cvt_pk_f16_f32 v38, v36, v37
	v_pk_mul_f32 v[36:37], v[42:43], v[42:43]
	v_alignbit_b32 v35, v38, v35, 16
	v_cvt_pk_f16_f32 v37, v36, v37
	v_alignbit_b32 v36, v37, v38, 16
	v_lshrrev_b32_e32 v37, 16, v37
	v_fma_mixhi_f16 v37, v45, v45, 0
	global_store_dwordx4 v[50:51], v[34:37], off offset:256 nt
	ds_read2_b32 v[34:35], v159 offset0:160 offset1:176
	s_waitcnt lgkmcnt(0)
; #define G8_WAIT_V(n) asm volatile("s_waitcnt vmcnt(" #n ")" ::: "memory")
; #define G8_BAR __builtin_amdgcn_s_barrier()
; template <class Epi>
; __device__ __forceinline__ void gemm_phase(LAS unsigned char* lds, const h16* A, const h16* Bt, int K, const Order& S, const Epi& E) {
;     ...
;     E(acc, cur, ui, wr, wc, fr, fq);
;     if (!has_next) break;
; #pragma unroll
;     for (int a = 0; a < 2; ++a)
; #pragma unroll
;       for (int b = 0; b < 2; ++b)
; #pragma unroll
;         for (int m = 0; m < 4; ++m)
; #pragma unroll
;           for (int n = 0; n < 2; ++n) acc[a][b][m][n] = (f32x4){0.f, 0.f, 0.f, 0.f};
;     cur = nxt; cA = nA; cB = nB; ++ui;
;   }
;   G8_WAIT_V(0);
;   if (wr == 0) G8_BAR;
;   G8_BAR;
;   __device__ __forceinline__ void operator()(const f32x4 (&acc)[2][2][4][2], const g8::Unit& u, int ui, int wr, int wc, int fr, int fq) const {
; #pragma unroll
;     for (int ai = 0; ai < 2; ++ai)
; #pragma unroll
;       for (int m = 0; m < 4; ++m) {
;         const int rl = 128 * ai + 64 * wr + 16 * m + fr;
;         const float r = rsl[ui * 256 + rl];
;         h16* rowp = hid + (size_t)(u.pm * 256 + rl) * DFF + 256 * u.pn + 32 * wc + 8 * fq;
; #pragma unroll
;         for (int bj = 0; bj < 2; ++bj) {
;           f32x4 v[2];
; #pragma unroll
;           for (int n = 0; n < 2; ++n) {
;             v[n] = acc[ai][bj][m][n] * r;
; #pragma unroll
;             for (int j = 0; j < 4; ++j) { const float t = fmaxf(v[n][j], 0.f); v[n][j] = t * t; }
;           }
;           __builtin_nontemporal_store(pack8(v[0], v[1]), (h16x8*)(rowp + 128 * bj));
;         }
;       }
;   }
	v_pk_mul_f32 v[32:33], v[32:33], v[34:35] op_sel_hi:[1,0]
	v_pk_mul_f32 v[30:31], v[30:31], v[34:35] op_sel_hi:[1,0]
	v_pk_mul_f32 v[26:27], v[26:27], v[34:35] op_sel_hi:[1,0]
	v_max_f32_e32 v40, 0, v30
	v_max_f32_e32 v30, 0, v31
	v_max_f32_e32 v31, 0, v32
	v_add_u32_e32 v36, s11, v156
	v_max_f32_e32 v32, 0, v33
	v_pk_mul_f32 v[28:29], v[28:29], v[34:35] op_sel_hi:[1,0]
	v_max_f32_e32 v33, 0, v26
	v_max_f32_e32 v38, 0, v27
	v_pk_mul_f32 v[26:27], v[30:31], v[30:31]
	v_ashrrev_i32_e32 v37, 31, v36
	v_max_f32_e32 v39, 0, v28
	v_fma_mixlo_f16 v28, v40, v40, 0
	v_cvt_pk_f16_f32 v27, v26, v27
	v_lshlrev_b64 v[36:37], 13, v[36:37]
	v_max_f32_e32 v41, 0, v29
	v_pack_b32_f16 v26, v28, v27
	v_pk_mul_f32 v[28:29], v[32:33], v[32:33]
	v_lshl_add_u64 v[36:37], s[0:1], 0, v[36:37]
	v_cvt_pk_f16_f32 v30, v28, v29
	v_pk_mul_f32 v[28:29], v[38:39], v[38:39]
	v_lshl_add_u64 v[36:37], v[36:37], 0, s[18:19]
	v_cvt_pk_f16_f32 v29, v28, v29
	v_lshl_add_u64 v[36:37], v[36:37], 0, s[92:93]
	v_alignbit_b32 v28, v29, v30, 16
	v_lshrrev_b32_e32 v29, 16, v29
	v_lshl_add_u64 v[36:37], v[36:37], 0, v[0:1]
	v_alignbit_b32 v27, v30, v27, 16
	v_fma_mixhi_f16 v29, v41, v41, 0
	v_pk_mul_f32 v[24:25], v[24:25], v[34:35] op_sel_hi:[1,0]
	v_pk_mul_f32 v[22:23], v[22:23], v[34:35] op_sel_hi:[1,0]
	global_store_dwordx4 v[36:37], v[26:29], off nt
	v_pk_mul_f32 v[18:19], v[18:19], v[34:35] op_sel_hi:[1,0]
	v_pk_mul_f32 v[20:21], v[20:21], v[34:35] op_sel_hi:[1,0]
	v_max_f32_e32 v28, 0, v22
	v_max_f32_e32 v22, 0, v23
	v_max_f32_e32 v23, 0, v24
	v_max_f32_e32 v24, 0, v25
	v_max_f32_e32 v25, 0, v18
	v_max_f32_e32 v26, 0, v19
	v_pk_mul_f32 v[18:19], v[22:23], v[22:23]
	v_max_f32_e32 v27, 0, v20
	v_fma_mixlo_f16 v20, v28, v28, 0
	v_cvt_pk_f16_f32 v19, v18, v19
	v_max_f32_e32 v29, 0, v21
	v_pack_b32_f16 v18, v20, v19
	v_pk_mul_f32 v[20:21], v[24:25], v[24:25]
	s_nop 0
	v_cvt_pk_f16_f32 v22, v20, v21
	v_pk_mul_f32 v[20:21], v[26:27], v[26:27]
	v_alignbit_b32 v19, v22, v19, 16
	v_cvt_pk_f16_f32 v21, v20, v21
	v_alignbit_b32 v20, v21, v22, 16
	v_lshrrev_b32_e32 v21, 16, v21
	v_fma_mixhi_f16 v21, v29, v29, 0
	global_store_dwordx4 v[36:37], v[18:21], off offset:256 nt
	s_nop 1
	v_mov_b32_e32 v20, v35
	v_pk_mul_f32 v[14:15], v[14:15], v[20:21] op_sel_hi:[1,0]
	v_pk_mul_f32 v[16:17], v[16:17], v[20:21] op_sel_hi:[1,0]
	v_max_f32_e32 v21, 0, v14
	v_max_f32_e32 v14, 0, v15
	v_max_f32_e32 v15, 0, v16
	v_pk_mul_f32 v[10:11], v[10:11], v[20:21] op_sel_hi:[1,0]
	v_add_u32_e32 v18, s11, v157
	v_max_f32_e32 v16, 0, v17
	v_pk_mul_f32 v[12:13], v[12:13], v[20:21] op_sel_hi:[1,0]
	v_max_f32_e32 v17, 0, v10
	v_max_f32_e32 v22, 0, v11
	v_pk_mul_f32 v[10:11], v[14:15], v[14:15]
	v_ashrrev_i32_e32 v19, 31, v18
	v_max_f32_e32 v23, 0, v12
	v_fma_mixlo_f16 v12, v21, v21, 0
	v_cvt_pk_f16_f32 v11, v10, v11
	v_lshlrev_b64 v[18:19], 13, v[18:19]
	v_max_f32_e32 v24, 0, v13
	v_pack_b32_f16 v10, v12, v11
	v_pk_mul_f32 v[12:13], v[16:17], v[16:17]
	v_lshl_add_u64 v[18:19], s[0:1], 0, v[18:19]
	v_cvt_pk_f16_f32 v14, v12, v13
	v_pk_mul_f32 v[12:13], v[22:23], v[22:23]
	v_lshl_add_u64 v[18:19], v[18:19], 0, s[18:19]
	v_cvt_pk_f16_f32 v13, v12, v13
	v_lshl_add_u64 v[18:19], v[18:19], 0, s[92:93]
	v_alignbit_b32 v12, v13, v14, 16
	v_lshrrev_b32_e32 v13, 16, v13
	v_lshl_add_u64 v[18:19], v[18:19], 0, v[0:1]
	v_alignbit_b32 v11, v14, v11, 16
	v_fma_mixhi_f16 v13, v24, v24, 0
	v_pk_mul_f32 v[8:9], v[8:9], v[20:21] op_sel_hi:[1,0]
	v_pk_mul_f32 v[6:7], v[6:7], v[20:21] op_sel_hi:[1,0]
	global_store_dwordx4 v[18:19], v[10:13], off nt
	v_pk_mul_f32 v[2:3], v[2:3], v[20:21] op_sel_hi:[1,0]
	v_pk_mul_f32 v[4:5], v[4:5], v[20:21] op_sel_hi:[1,0]
	v_max_f32_e32 v12, 0, v6
	v_max_f32_e32 v6, 0, v7
	v_max_f32_e32 v7, 0, v8
	v_max_f32_e32 v8, 0, v9
	v_max_f32_e32 v9, 0, v2
	v_max_f32_e32 v10, 0, v3
	v_pk_mul_f32 v[2:3], v[6:7], v[6:7]
	v_max_f32_e32 v11, 0, v4
	v_fma_mixlo_f16 v4, v12, v12, 0
	v_cvt_pk_f16_f32 v3, v2, v3
	v_max_f32_e32 v13, 0, v5
	v_pack_b32_f16 v2, v4, v3
	v_pk_mul_f32 v[4:5], v[8:9], v[8:9]
	s_mov_b64 s[18:19], s[14:15]
	v_cvt_pk_f16_f32 v6, v4, v5
	v_pk_mul_f32 v[4:5], v[10:11], v[10:11]
	v_alignbit_b32 v3, v6, v3, 16
	v_cvt_pk_f16_f32 v5, v4, v5
	v_alignbit_b32 v4, v5, v6, 16
	v_lshrrev_b32_e32 v5, 16, v5
	v_fma_mixhi_f16 v5, v13, v13, 0
	global_store_dwordx4 v[18:19], v[2:5], off offset:256 nt
	s_cbranch_vccz .LBB0_2466
	s_waitcnt vmcnt(0)
	s_cmpk_gt_u32 s2, 0xff
	s_cbranch_scc1 .LBB0_2477
	s_barrier

; #define G8_STAGE(bufoff, gbase) do { _Pragma("unroll") for (int _i = 0; _i < 2; ++_i) \
;     __builtin_amdgcn_global_load_lds((const unsigned*)((const char*)(gbase) + voffA[_i]), (LAS unsigned*)(lds + (bufoff) + ldsw + _i * 8192), 16, 0, 0); } while (0)
; #define G8_LDA(dst, b, h) do { _Pragma("unroll") for (int m = 0; m < 4; ++m) _Pragma("unroll") for (int k = 0; k < 2; ++k) dst[m][k] = *(const LAS h16x8*)(lds + G8_SA(b, h) + aoff + m * 2048 + k * 1024); } while (0)
; #define G8_WAIT_V(n) asm volatile("s_waitcnt vmcnt(" #n ")" ::: "memory")
; #define G8_WAIT_L(n) asm volatile("s_waitcnt lgkmcnt(" #n ")" ::: "memory")
; template <class Epi>
; __device__ __forceinline__ void gemm_phase(LAS unsigned char* lds, const h16* A, const h16* Bt, int K, const Order& S, const Epi& E) {
;     ...
;   f32x4 acc[2][2][4][2];
; #pragma unroll
;   for (int a = 0; a < 2; ++a)
; #pragma unroll
;     for (int b = 0; b < 2; ++b)
; #pragma unroll
;       for (int m = 0; m < 4; ++m)
; #pragma unroll
;         for (int n = 0; n < 2; ++n) acc[a][b][m][n] = (f32x4){0.f, 0.f, 0.f, 0.f};
;   h16x8 At[4][2], B0[2][2], B1[2][2];
;   const char* cA = (const char*)A + (size_t)cur.pm * tstep;
;   const char* cB = (const char*)Bt + (size_t)cur.pn * tstep;
;   G8_STAGE(G8_SB(0, 0), cB); G8_STAGE(G8_SA(0, 0), cA); G8_STAGE(G8_SB(0, 1), cB + hstep); G8_STAGE(G8_SA(0, 1), cA + hstep);
;   if (wr == 1) G8_BAR;
;   G8_WAIT_V(4); G8_BAR;
;   G8_STAGE(G8_SB(1, 0), cB + kstep); G8_STAGE(G8_SA(1, 0), cA + kstep); G8_STAGE(G8_SB(1, 1), cB + hstep + kstep);
;   G8_WAIT_V(6); G8_BAR;
;   for (;;) {
;     const bool has_next = S.next(ui + 1, nxt);
;     const char* nA = has_next ? (const char*)A + (size_t)nxt.pm * tstep : cA;
;     const char* nB = has_next ? (const char*)Bt + (size_t)nxt.pn * tstep : cB;
;     for (int t = 0; t < nt; t += 2) {
;       const bool last = (t == nt - 2);
;       const char* a1 = cA + (size_t)(t + 1) * kstep;
;       const char* a2 = last ? nA : cA + (size_t)(t + 2) * kstep;
;       const char* b2 = last ? nB : cB + (size_t)(t + 2) * kstep;
;       const char* a3 = a2 + kstep;
;       const char* b3 = b2 + kstep;
;       if (Epi::MID_T >= 0 && t == Epi::MID_T) E.mid(acc, ui, wr, fr);
;       G8_LDB(B0, 0, 0); G8_SCHED; G8_LDA(At, 0, 0); G8_STAGE(G8_SA(1, 1), a1 + hstep);
;       G8_WAIT_L(8); G8_BAR; G8_WAIT_L(0); G8_MMA(0, 0, At, B0); G8_BAR; G8_SCHED;
.LBB0_2541:
	s_ashr_i32 s17, s16, 31
	v_cmp_lt_i64_e32 vcc, s[18:19], v[148:149]
	s_lshl_b64 s[18:19], s[16:17], 21
	s_add_u32 s18, s29, s18
	s_addc_u32 s19, s30, s19
	s_and_b64 s[20:21], vcc, exec
	s_cselect_b32 s3, s19, s23
	s_cselect_b32 s9, s18, s22
	s_ashr_i32 s15, s14, 31
	s_lshl_b64 s[20:21], s[14:15], 21
	s_add_u32 s20, s31, s20
	s_addc_u32 s21, s34, s21
	s_and_b64 s[26:27], vcc, exec
	s_cselect_b32 s15, s21, s25
	s_cselect_b32 s17, s20, s24
	s_add_u32 s22, s22, 0x100080
	s_addc_u32 s23, s23, 0
	s_add_u32 s51, s24, 0x100
	v_mov_b32_e32 v2, 0
	s_addc_u32 s52, s25, 0
	s_mov_b32 s53, -2
	s_waitcnt lgkmcnt(0)
	v_mov_b32_e32 v3, v2
	v_mov_b32_e32 v4, v2
	v_mov_b32_e32 v5, v2
	v_mov_b32_e32 v6, v2
	v_mov_b32_e32 v7, v2
	v_mov_b32_e32 v8, v2
	v_mov_b32_e32 v9, v2
	v_mov_b32_e32 v18, v2
	v_mov_b32_e32 v19, v2
	v_mov_b32_e32 v20, v2
	v_mov_b32_e32 v21, v2
	v_mov_b32_e32 v22, v2
	v_mov_b32_e32 v23, v2
	v_mov_b32_e32 v24, v2
	v_mov_b32_e32 v25, v2
	v_mov_b32_e32 v34, v2
	v_mov_b32_e32 v35, v2
	v_mov_b32_e32 v36, v2
	v_mov_b32_e32 v37, v2
	v_mov_b32_e32 v38, v2
	v_mov_b32_e32 v39, v2
	v_mov_b32_e32 v40, v2
	v_mov_b32_e32 v41, v2
	v_mov_b32_e32 v50, v2
	v_mov_b32_e32 v51, v2
	v_mov_b32_e32 v52, v2
	v_mov_b32_e32 v53, v2
	v_mov_b32_e32 v54, v2
	v_mov_b32_e32 v55, v2
	v_mov_b32_e32 v56, v2
	v_mov_b32_e32 v57, v2
	v_mov_b32_e32 v10, v2
	v_mov_b32_e32 v11, v2
	v_mov_b32_e32 v12, v2
	v_mov_b32_e32 v13, v2
	v_mov_b32_e32 v14, v2
	v_mov_b32_e32 v15, v2
	v_mov_b32_e32 v16, v2
	v_mov_b32_e32 v17, v2
	v_mov_b32_e32 v26, v2
	v_mov_b32_e32 v27, v2
	v_mov_b32_e32 v28, v2
	v_mov_b32_e32 v29, v2
	v_mov_b32_e32 v30, v2
	v_mov_b32_e32 v31, v2
	v_mov_b32_e32 v32, v2
	v_mov_b32_e32 v33, v2
	v_mov_b32_e32 v42, v2
	v_mov_b32_e32 v43, v2
	v_mov_b32_e32 v44, v2
	v_mov_b32_e32 v45, v2
	v_mov_b32_e32 v46, v2
	v_mov_b32_e32 v47, v2
	v_mov_b32_e32 v48, v2
	v_mov_b32_e32 v49, v2
	v_mov_b32_e32 v58, v2
	v_mov_b32_e32 v59, v2
	v_mov_b32_e32 v60, v2
	v_mov_b32_e32 v61, v2
	v_mov_b32_e32 v62, v2
	v_mov_b32_e32 v63, v2
	v_mov_b32_e32 v64, v2
	v_mov_b32_e32 v65, v2
	v_mov_b32_e32 v66, v2
	v_mov_b32_e32 v67, v2
	v_mov_b32_e32 v68, v2
	v_mov_b32_e32 v69, v2
	v_mov_b32_e32 v70, v2
	v_mov_b32_e32 v71, v2
	v_mov_b32_e32 v72, v2
	v_mov_b32_e32 v73, v2
	v_mov_b32_e32 v82, v2
	v_mov_b32_e32 v83, v2
	v_mov_b32_e32 v84, v2
	v_mov_b32_e32 v85, v2
	v_mov_b32_e32 v86, v2
	v_mov_b32_e32 v87, v2
	v_mov_b32_e32 v88, v2
	v_mov_b32_e32 v89, v2
	v_mov_b32_e32 v98, v2
	v_mov_b32_e32 v99, v2
	v_mov_b32_e32 v100, v2
	v_mov_b32_e32 v101, v2
	v_mov_b32_e32 v102, v2
	v_mov_b32_e32 v103, v2
	v_mov_b32_e32 v104, v2
	v_mov_b32_e32 v105, v2
	v_mov_b32_e32 v114, v2
	v_mov_b32_e32 v115, v2
	v_mov_b32_e32 v116, v2
	v_mov_b32_e32 v117, v2
	v_mov_b32_e32 v118, v2
	v_mov_b32_e32 v119, v2
	v_mov_b32_e32 v120, v2
	v_mov_b32_e32 v121, v2
	v_mov_b32_e32 v74, v2
	v_mov_b32_e32 v75, v2
	v_mov_b32_e32 v76, v2
	v_mov_b32_e32 v77, v2
	v_mov_b32_e32 v78, v2
	v_mov_b32_e32 v79, v2
	v_mov_b32_e32 v80, v2
	v_mov_b32_e32 v81, v2
	v_mov_b32_e32 v90, v2
	v_mov_b32_e32 v91, v2
	v_mov_b32_e32 v92, v2
	v_mov_b32_e32 v93, v2
	v_mov_b32_e32 v94, v2
	v_mov_b32_e32 v95, v2
	v_mov_b32_e32 v96, v2
	v_mov_b32_e32 v97, v2
	v_mov_b32_e32 v106, v2
	v_mov_b32_e32 v107, v2
	v_mov_b32_e32 v108, v2
	v_mov_b32_e32 v109, v2
	v_mov_b32_e32 v110, v2
	v_mov_b32_e32 v111, v2
	v_mov_b32_e32 v112, v2
	v_mov_b32_e32 v113, v2
	v_mov_b32_e32 v122, v2
	v_mov_b32_e32 v123, v2
	v_mov_b32_e32 v124, v2
	v_mov_b32_e32 v125, v2
	v_mov_b32_e32 v126, v2
	v_mov_b32_e32 v127, v2
	v_mov_b32_e32 v128, v2
	v_mov_b32_e32 v129, v2
	v_readfirstlane_b32 vcc_lo, v145
	s_cmp_lt_u32 vcc_lo, 0x100
	s_cbranch_scc1 .Lgprio_dn
	s_setprio 1
.Lgprio_dn:
	v_or_b32_e32 v140, 0x10000, v158
	v_add_u32_e32 v141, 0x10400, v158
	ds_read_b128 v[152:155], v140
	ds_read_b128 v[160:163], v141
	v_add_u32_e32 v140, 0x10800, v158
	v_add_u32_e32 v141, 0x10c00, v158
	ds_read_b128 v[164:167], v140
	ds_read_b128 v[168:171], v141
.LBB0_2542:
	s_add_u32 s24, s22, 0xfff00080
	s_addc_u32 s25, s23, -1
	s_cmp_eq_u32 s53, 60
	s_cselect_b32 s27, s3, s25
	s_cselect_b32 s26, s9, s24
	s_cselect_b32 s25, s15, s52
	s_cselect_b32 s24, s17, s51
	v_lshl_add_u64 v[140:141], s[22:23], 0, v[136:137]
	s_add_i32 m0, s35, 0xc000
	ds_read_b128 v[172:175], v135
	ds_read_b128 v[176:179], v135 offset:1024
	ds_read_b128 v[180:183], v135 offset:2048
	ds_read_b128 v[184:187], v135 offset:3072
	ds_read_b128 v[202:205], v135 offset:4096
	ds_read_b128 v[206:209], v135 offset:5120
	ds_read_b128 v[210:213], v135 offset:6144
	ds_read_b128 v[214:217], v135 offset:7168
	global_load_lds_dwordx4 v[140:141], off
	v_lshl_add_u64 v[140:141], s[22:23], 0, v[138:139]
	s_add_i32 m0, s35, 0xe000
	s_nop 0
	global_load_lds_dwordx4 v[140:141], off
	s_waitcnt lgkmcnt(8)
	s_barrier
	s_waitcnt lgkmcnt(0)
	s_nop 0
	s_waitcnt lgkmcnt(0)
	v_mfma_f32_16x16x32_f16 v[126:129], v[152:155], v[172:175], v[126:129]
	v_mfma_f32_16x16x32_f16 v[122:125], v[164:167], v[172:175], v[122:125]
	v_mfma_f32_16x16x32_f16 v[110:113], v[152:155], v[180:183], v[110:113]
	v_mfma_f32_16x16x32_f16 v[106:109], v[164:167], v[180:183], v[106:109]
	v_mfma_f32_16x16x32_f16 v[94:97], v[152:155], v[202:205], v[94:97]
	v_mfma_f32_16x16x32_f16 v[90:93], v[164:167], v[202:205], v[90:93]
	v_mfma_f32_16x16x32_f16 v[78:81], v[152:155], v[210:213], v[78:81]
	v_mfma_f32_16x16x32_f16 v[74:77], v[164:167], v[210:213], v[74:77]
	v_mfma_f32_16x16x32_f16 v[126:129], v[160:163], v[176:179], v[126:129]
	v_mfma_f32_16x16x32_f16 v[122:125], v[168:171], v[176:179], v[122:125]
	v_mfma_f32_16x16x32_f16 v[110:113], v[160:163], v[184:187], v[110:113]
	v_mfma_f32_16x16x32_f16 v[106:109], v[168:171], v[184:187], v[106:109]
	v_mfma_f32_16x16x32_f16 v[94:97], v[160:163], v[206:209], v[94:97]
	v_mfma_f32_16x16x32_f16 v[90:93], v[168:171], v[206:209], v[90:93]
	v_mfma_f32_16x16x32_f16 v[78:81], v[160:163], v[214:217], v[78:81]
	v_mfma_f32_16x16x32_f16 v[74:77], v[168:171], v[214:217], v[74:77]
	s_nop 0
	s_barrier
; #define G8_STAGE(bufoff, gbase) do { _Pragma("unroll") for (int _i = 0; _i < 2; ++_i) \
;     __builtin_amdgcn_global_load_lds((const unsigned*)((const char*)(gbase) + voffA[_i]), (LAS unsigned*)(lds + (bufoff) + ldsw + _i * 8192), 16, 0, 0); } while (0)
; #define G8_LDA(dst, b, h) do { _Pragma("unroll") for (int m = 0; m < 4; ++m) _Pragma("unroll") for (int k = 0; k < 2; ++k) dst[m][k] = *(const LAS h16x8*)(lds + G8_SA(b, h) + aoff + m * 2048 + k * 1024); } while (0)
; #define G8_LDB(dst, b, h) do { _Pragma("unroll") for (int n = 0; n < 2; ++n) _Pragma("unroll") for (int k = 0; k < 2; ++k) dst[n][k] = *(const LAS h16x8*)(lds + G8_SB(b, h) + boff + n * 2048 + k * 1024); } while (0)
; #define G8_MMA(ai, bj, At, Bt_) do { __builtin_amdgcn_s_setprio(1); _Pragma("unroll") for (int m = 0; m < 4; ++m) _Pragma("unroll") for (int n = 0; n < 2; ++n) _Pragma("unroll") for (int k = 0; k < 2; ++k) \
;     acc[ai][bj][m][n] = __builtin_amdgcn_mfma_f32_16x16x32_f16(Bt_[n][k], At[m][k], acc[ai][bj][m][n], 0, 0, 0); __builtin_amdgcn_s_setprio(0); } while (0)
; #define G8_WAIT_V(n) asm volatile("s_waitcnt vmcnt(" #n ")" ::: "memory")
; #define G8_WAIT_L(n) asm volatile("s_waitcnt lgkmcnt(" #n ")" ::: "memory")
; #define G8_BAR __builtin_amdgcn_s_barrier()
; #define G8_SCHED __builtin_amdgcn_sched_barrier(0)
; template <class Epi>
; __device__ __forceinline__ void gemm_phase(LAS unsigned char* lds, const h16* A, const h16* Bt, int K, const Order& S, const Epi& E) {
;     ...
;       G8_LDB(B1, 0, 1); G8_STAGE(G8_SB(0, 0), b2);
;       G8_BAR; G8_WAIT_L(0); G8_MMA(0, 1, At, B1); G8_BAR;
;       G8_LDA(At, 0, 1); G8_STAGE(G8_SA(0, 0), a2);
;       G8_BAR; G8_WAIT_L(0); G8_MMA(1, 0, At, B0); G8_BAR; G8_SCHED;
;       G8_STAGE(G8_SB(0, 1), b2 + hstep);
;       G8_WAIT_V(6); G8_BAR; G8_MMA(1, 1, At, B1); G8_BAR;
;       G8_LDB(B0, 1, 0); G8_SCHED; G8_LDA(At, 1, 0); G8_STAGE(G8_SA(0, 1), a2 + hstep);
;       G8_WAIT_L(8); G8_BAR; G8_WAIT_L(0); G8_MMA(0, 0, At, B0); G8_BAR; G8_SCHED;
;       G8_LDB(B1, 1, 1); G8_STAGE(G8_SB(1, 0), b3);
;       G8_BAR; G8_WAIT_L(0); G8_MMA(0, 1, At, B1); G8_BAR;
;       G8_LDA(At, 1, 1); G8_STAGE(G8_SA(1, 0), a3);
	v_or_b32_e32 v140, 0x14000, v158
	v_add_u32_e32 v141, 0x14400, v158
	ds_read_b128 v[218:221], v140
	ds_read_b128 v[222:225], v141
	v_add_u32_e32 v140, 0x14800, v158
	v_add_u32_e32 v141, 0x14c00, v158
	s_mov_b32 m0, s36
	ds_read_b128 v[226:229], v140
	ds_read_b128 v[230:233], v141
	v_lshl_add_u64 v[140:141], s[24:25], 0, v[0:1]
	global_load_lds_dwordx4 v[140:141], off
	v_lshl_add_u64 v[156:157], s[24:25], 0, v[130:131]
	s_mov_b32 m0, s37
	s_nop 0
	global_load_lds_dwordx4 v[156:157], off
	s_barrier
	s_waitcnt lgkmcnt(0)
	s_nop 0
	s_waitcnt lgkmcnt(0)
	v_mfma_f32_16x16x32_f16 v[118:121], v[218:221], v[172:175], v[118:121]
	v_mfma_f32_16x16x32_f16 v[114:117], v[226:229], v[172:175], v[114:117]
	v_mfma_f32_16x16x32_f16 v[102:105], v[218:221], v[180:183], v[102:105]
	v_mfma_f32_16x16x32_f16 v[98:101], v[226:229], v[180:183], v[98:101]
	v_mfma_f32_16x16x32_f16 v[86:89], v[218:221], v[202:205], v[86:89]
	v_mfma_f32_16x16x32_f16 v[82:85], v[226:229], v[202:205], v[82:85]
	v_mfma_f32_16x16x32_f16 v[70:73], v[218:221], v[210:213], v[70:73]
	v_mfma_f32_16x16x32_f16 v[66:69], v[226:229], v[210:213], v[66:69]
	v_mfma_f32_16x16x32_f16 v[118:121], v[222:225], v[176:179], v[118:121]
	v_mfma_f32_16x16x32_f16 v[114:117], v[230:233], v[176:179], v[114:117]
	v_mfma_f32_16x16x32_f16 v[102:105], v[222:225], v[184:187], v[102:105]
	v_mfma_f32_16x16x32_f16 v[98:101], v[230:233], v[184:187], v[98:101]
	v_mfma_f32_16x16x32_f16 v[86:89], v[222:225], v[206:209], v[86:89]
	v_mfma_f32_16x16x32_f16 v[82:85], v[230:233], v[206:209], v[82:85]
	v_mfma_f32_16x16x32_f16 v[70:73], v[222:225], v[214:217], v[70:73]
	v_mfma_f32_16x16x32_f16 v[66:69], v[230:233], v[214:217], v[66:69]
	s_nop 0
	s_mov_b32 m0, s35
	v_lshl_add_u64 v[188:189], s[26:27], 0, v[0:1]
	s_barrier
	ds_read_b128 v[172:175], v135 offset:16384
	ds_read_b128 v[176:179], v135 offset:17408
	ds_read_b128 v[180:183], v135 offset:18432
	ds_read_b128 v[184:187], v135 offset:19456
	ds_read_b128 v[202:205], v135 offset:20480
	ds_read_b128 v[206:209], v135 offset:21504
	ds_read_b128 v[210:213], v135 offset:22528
	ds_read_b128 v[214:217], v135 offset:23552
	global_load_lds_dwordx4 v[188:189], off
	v_lshl_add_u64 v[234:235], s[26:27], 0, v[130:131]
	s_mov_b32 m0, s38
	s_nop 0
	global_load_lds_dwordx4 v[234:235], off
	s_waitcnt vmcnt(10)
	s_barrier
	s_waitcnt lgkmcnt(0)
	s_nop 0
	s_waitcnt lgkmcnt(0)
	v_mfma_f32_16x16x32_f16 v[62:65], v[152:155], v[172:175], v[62:65]
	v_mfma_f32_16x16x32_f16 v[58:61], v[164:167], v[172:175], v[58:61]
	v_mfma_f32_16x16x32_f16 v[46:49], v[152:155], v[180:183], v[46:49]
	v_mfma_f32_16x16x32_f16 v[42:45], v[164:167], v[180:183], v[42:45]
	v_mfma_f32_16x16x32_f16 v[30:33], v[152:155], v[202:205], v[30:33]
	v_mfma_f32_16x16x32_f16 v[26:29], v[164:167], v[202:205], v[26:29]
	v_mfma_f32_16x16x32_f16 v[14:17], v[152:155], v[210:213], v[14:17]
	v_mfma_f32_16x16x32_f16 v[10:13], v[164:167], v[210:213], v[10:13]
	v_mfma_f32_16x16x32_f16 v[62:65], v[160:163], v[176:179], v[62:65]
	v_mfma_f32_16x16x32_f16 v[58:61], v[168:171], v[176:179], v[58:61]
	v_mfma_f32_16x16x32_f16 v[46:49], v[160:163], v[184:187], v[46:49]
	v_mfma_f32_16x16x32_f16 v[42:45], v[168:171], v[184:187], v[42:45]
	v_mfma_f32_16x16x32_f16 v[30:33], v[160:163], v[206:209], v[30:33]
	v_mfma_f32_16x16x32_f16 v[26:29], v[168:171], v[206:209], v[26:29]
	v_mfma_f32_16x16x32_f16 v[14:17], v[160:163], v[214:217], v[14:17]
	v_mfma_f32_16x16x32_f16 v[10:13], v[168:171], v[214:217], v[10:13]
	s_nop 0
	s_barrier
	s_add_u32 s54, s24, 0x100000
	s_addc_u32 s55, s25, 0
	s_mov_b32 m0, s39
	v_lshl_add_u64 v[152:153], s[54:55], 0, v[0:1]
	global_load_lds_dwordx4 v[152:153], off
	v_lshl_add_u64 v[152:153], s[54:55], 0, v[130:131]
	s_mov_b32 m0, s40
	s_nop 0
	global_load_lds_dwordx4 v[152:153], off
	v_or_b32_e32 v152, 0x18000, v158
	v_add_u32_e32 v159, 0x18400, v158
	ds_read_b128 v[152:155], v152
	ds_read_b128 v[160:163], v159
	v_add_u32_e32 v159, 0x18800, v158
	v_add_u32_e32 v168, 0x18c00, v158
	ds_read_b128 v[164:167], v159
	ds_read_b128 v[168:171], v168
	s_waitcnt vmcnt(6)
	s_barrier
	s_nop 0
	v_mfma_f32_16x16x32_f16 v[54:57], v[218:221], v[172:175], v[54:57]
	v_mfma_f32_16x16x32_f16 v[50:53], v[226:229], v[172:175], v[50:53]
	v_mfma_f32_16x16x32_f16 v[38:41], v[218:221], v[180:183], v[38:41]
	v_mfma_f32_16x16x32_f16 v[34:37], v[226:229], v[180:183], v[34:37]
	v_mfma_f32_16x16x32_f16 v[22:25], v[218:221], v[202:205], v[22:25]
	v_mfma_f32_16x16x32_f16 v[18:21], v[226:229], v[202:205], v[18:21]
	v_mfma_f32_16x16x32_f16 v[6:9], v[218:221], v[210:213], v[6:9]
	v_mfma_f32_16x16x32_f16 v[2:5], v[226:229], v[210:213], v[2:5]
	v_mfma_f32_16x16x32_f16 v[54:57], v[222:225], v[176:179], v[54:57]
	v_mfma_f32_16x16x32_f16 v[50:53], v[230:233], v[176:179], v[50:53]
	v_mfma_f32_16x16x32_f16 v[38:41], v[222:225], v[184:187], v[38:41]
	v_mfma_f32_16x16x32_f16 v[34:37], v[230:233], v[184:187], v[34:37]
	v_mfma_f32_16x16x32_f16 v[22:25], v[222:225], v[206:209], v[22:25]
	v_mfma_f32_16x16x32_f16 v[18:21], v[230:233], v[206:209], v[18:21]
	v_mfma_f32_16x16x32_f16 v[6:9], v[222:225], v[214:217], v[6:9]
	v_mfma_f32_16x16x32_f16 v[2:5], v[230:233], v[214:217], v[2:5]
	s_nop 0
	s_barrier
	s_add_u32 s26, s26, 0x100000
	s_addc_u32 s27, s27, 0
	s_mov_b32 m0, s41
	v_lshl_add_u64 v[218:219], s[26:27], 0, v[0:1]
	ds_read_b128 v[172:175], v135 offset:32768
	ds_read_b128 v[176:179], v135 offset:33792
	ds_read_b128 v[180:183], v135 offset:34816
	ds_read_b128 v[184:187], v135 offset:35840
	ds_read_b128 v[202:205], v135 offset:36864
	ds_read_b128 v[206:209], v135 offset:37888
	ds_read_b128 v[210:213], v135 offset:38912
	ds_read_b128 v[214:217], v135 offset:39936
	global_load_lds_dwordx4 v[218:219], off
	v_lshl_add_u64 v[218:219], s[26:27], 0, v[130:131]
	s_mov_b32 m0, s42
	s_nop 0
	global_load_lds_dwordx4 v[218:219], off
	s_waitcnt lgkmcnt(8)
	s_barrier
; #define G8_STAGE(bufoff, gbase) do { _Pragma("unroll") for (int _i = 0; _i < 2; ++_i) \
;     __builtin_amdgcn_global_load_lds((const unsigned*)((const char*)(gbase) + voffA[_i]), (LAS unsigned*)(lds + (bufoff) + ldsw + _i * 8192), 16, 0, 0); } while (0)
; #define G8_LDA(dst, b, h) do { _Pragma("unroll") for (int m = 0; m < 4; ++m) _Pragma("unroll") for (int k = 0; k < 2; ++k) dst[m][k] = *(const LAS h16x8*)(lds + G8_SA(b, h) + aoff + m * 2048 + k * 1024); } while (0)
; #define G8_LDB(dst, b, h) do { _Pragma("unroll") for (int n = 0; n < 2; ++n) _Pragma("unroll") for (int k = 0; k < 2; ++k) dst[n][k] = *(const LAS h16x8*)(lds + G8_SB(b, h) + boff + n * 2048 + k * 1024); } while (0)
; #define G8_MMA(ai, bj, At, Bt_) do { __builtin_amdgcn_s_setprio(1); _Pragma("unroll") for (int m = 0; m < 4; ++m) _Pragma("unroll") for (int n = 0; n < 2; ++n) _Pragma("unroll") for (int k = 0; k < 2; ++k) \
;     acc[ai][bj][m][n] = __builtin_amdgcn_mfma_f32_16x16x32_f16(Bt_[n][k], At[m][k], acc[ai][bj][m][n], 0, 0, 0); __builtin_amdgcn_s_setprio(0); } while (0)
; #define G8_WAIT_L(n) asm volatile("s_waitcnt lgkmcnt(" #n ")" ::: "memory")
; #define G8_BAR __builtin_amdgcn_s_barrier()
; #define G8_SCHED __builtin_amdgcn_sched_barrier(0)
; template <class Epi>
; __device__ __forceinline__ void gemm_phase(LAS unsigned char* lds, const h16* A, const h16* Bt, int K, const Order& S, const Epi& E) {
;     ...
;       G8_WAIT_L(8); G8_BAR; G8_WAIT_L(0); G8_MMA(0, 0, At, B0); G8_BAR; G8_SCHED;
;       G8_LDB(B1, 1, 1); G8_STAGE(G8_SB(1, 0), b3);
;       G8_BAR; G8_WAIT_L(0); G8_MMA(0, 1, At, B1); G8_BAR;
;       G8_LDA(At, 1, 1); G8_STAGE(G8_SA(1, 0), a3);
;       G8_BAR; G8_WAIT_L(0); G8_MMA(1, 0, At, B0); G8_BAR; G8_SCHED;
	s_waitcnt lgkmcnt(0)
	s_nop 0
	s_waitcnt lgkmcnt(0)
	v_mfma_f32_16x16x32_f16 v[126:129], v[152:155], v[172:175], v[126:129]
	v_mfma_f32_16x16x32_f16 v[122:125], v[164:167], v[172:175], v[122:125]
	v_mfma_f32_16x16x32_f16 v[110:113], v[152:155], v[180:183], v[110:113]
	v_mfma_f32_16x16x32_f16 v[106:109], v[164:167], v[180:183], v[106:109]
	v_mfma_f32_16x16x32_f16 v[94:97], v[152:155], v[202:205], v[94:97]
	v_mfma_f32_16x16x32_f16 v[90:93], v[164:167], v[202:205], v[90:93]
	v_mfma_f32_16x16x32_f16 v[78:81], v[152:155], v[210:213], v[78:81]
	v_mfma_f32_16x16x32_f16 v[74:77], v[164:167], v[210:213], v[74:77]
	v_mfma_f32_16x16x32_f16 v[126:129], v[160:163], v[176:179], v[126:129]
	v_mfma_f32_16x16x32_f16 v[122:125], v[168:171], v[176:179], v[122:125]
	v_mfma_f32_16x16x32_f16 v[110:113], v[160:163], v[184:187], v[110:113]
	v_mfma_f32_16x16x32_f16 v[106:109], v[168:171], v[184:187], v[106:109]
	v_mfma_f32_16x16x32_f16 v[94:97], v[160:163], v[206:209], v[94:97]
	v_mfma_f32_16x16x32_f16 v[90:93], v[168:171], v[206:209], v[90:93]
	v_mfma_f32_16x16x32_f16 v[78:81], v[160:163], v[214:217], v[78:81]
	v_mfma_f32_16x16x32_f16 v[74:77], v[168:171], v[214:217], v[74:77]
	s_nop 0
	s_barrier
	v_or_b32_e32 v159, 0x1c000, v158
	s_mov_b32 m0, s44
	v_add_u32_e32 v195, 0x1c400, v158
	ds_read_b128 v[218:221], v159
	ds_read_b128 v[222:225], v195
	v_add_u32_e32 v159, 0x1c800, v158
	v_lshl_add_u64 v[140:141], v[140:141], 0, s[94:95]
	v_add_u32_e32 v195, 0x1cc00, v158
	ds_read_b128 v[226:229], v159
	ds_read_b128 v[230:233], v195
	global_load_lds_dwordx4 v[140:141], off
	v_lshl_add_u64 v[140:141], v[156:157], 0, s[94:95]
	s_mov_b32 m0, s45
	s_nop 0
	global_load_lds_dwordx4 v[140:141], off
	s_barrier
	s_waitcnt lgkmcnt(0)
	s_nop 0
	s_waitcnt lgkmcnt(0)
	v_mfma_f32_16x16x32_f16 v[118:121], v[218:221], v[172:175], v[118:121]
	v_mfma_f32_16x16x32_f16 v[114:117], v[226:229], v[172:175], v[114:117]
	v_mfma_f32_16x16x32_f16 v[102:105], v[218:221], v[180:183], v[102:105]
	v_mfma_f32_16x16x32_f16 v[98:101], v[226:229], v[180:183], v[98:101]
	v_mfma_f32_16x16x32_f16 v[86:89], v[218:221], v[202:205], v[86:89]
	v_mfma_f32_16x16x32_f16 v[82:85], v[226:229], v[202:205], v[82:85]
	v_mfma_f32_16x16x32_f16 v[70:73], v[218:221], v[210:213], v[70:73]
	v_mfma_f32_16x16x32_f16 v[66:69], v[226:229], v[210:213], v[66:69]
	v_mfma_f32_16x16x32_f16 v[118:121], v[222:225], v[176:179], v[118:121]
	v_mfma_f32_16x16x32_f16 v[114:117], v[230:233], v[176:179], v[114:117]
	v_mfma_f32_16x16x32_f16 v[102:105], v[222:225], v[184:187], v[102:105]
	v_mfma_f32_16x16x32_f16 v[98:101], v[230:233], v[184:187], v[98:101]
	v_mfma_f32_16x16x32_f16 v[86:89], v[222:225], v[206:209], v[86:89]
	v_mfma_f32_16x16x32_f16 v[82:85], v[230:233], v[206:209], v[82:85]
	v_mfma_f32_16x16x32_f16 v[70:73], v[222:225], v[214:217], v[70:73]
	v_mfma_f32_16x16x32_f16 v[66:69], v[230:233], v[214:217], v[66:69]
	s_nop 0
	s_mov_b32 m0, s46
	v_lshl_add_u64 v[140:141], v[188:189], 0, s[94:95]
	s_barrier
	ds_read_b128 v[172:175], v135 offset:49152
	ds_read_b128 v[176:179], v135 offset:50176
	ds_read_b128 v[180:183], v135 offset:51200
	ds_read_b128 v[184:187], v135 offset:52224
	ds_read_b128 v[202:205], v135 offset:53248
	ds_read_b128 v[206:209], v135 offset:54272
	ds_read_b128 v[210:213], v135 offset:55296
	ds_read_b128 v[214:217], v135 offset:56320
	global_load_lds_dwordx4 v[140:141], off
	v_lshl_add_u64 v[140:141], v[234:235], 0, s[94:95]
	s_mov_b32 m0, s47
	s_nop 0
	global_load_lds_dwordx4 v[140:141], off
	s_waitcnt vmcnt(10)
	s_barrier
	s_waitcnt lgkmcnt(0)
	s_nop 0
	s_waitcnt lgkmcnt(0)
	v_mfma_f32_16x16x32_f16 v[62:65], v[152:155], v[172:175], v[62:65]
	v_mfma_f32_16x16x32_f16 v[58:61], v[164:167], v[172:175], v[58:61]
	v_mfma_f32_16x16x32_f16 v[46:49], v[152:155], v[180:183], v[46:49]
	v_mfma_f32_16x16x32_f16 v[42:45], v[164:167], v[180:183], v[42:45]
	v_mfma_f32_16x16x32_f16 v[30:33], v[152:155], v[202:205], v[30:33]
	v_mfma_f32_16x16x32_f16 v[26:29], v[164:167], v[202:205], v[26:29]
	v_mfma_f32_16x16x32_f16 v[14:17], v[152:155], v[210:213], v[14:17]
	v_mfma_f32_16x16x32_f16 v[10:13], v[164:167], v[210:213], v[10:13]
	v_mfma_f32_16x16x32_f16 v[62:65], v[160:163], v[176:179], v[62:65]
	v_mfma_f32_16x16x32_f16 v[58:61], v[168:171], v[176:179], v[58:61]
	v_mfma_f32_16x16x32_f16 v[46:49], v[160:163], v[184:187], v[46:49]
	v_mfma_f32_16x16x32_f16 v[42:45], v[168:171], v[184:187], v[42:45]
	v_mfma_f32_16x16x32_f16 v[30:33], v[160:163], v[206:209], v[30:33]
	v_mfma_f32_16x16x32_f16 v[26:29], v[168:171], v[206:209], v[26:29]
	v_mfma_f32_16x16x32_f16 v[14:17], v[160:163], v[214:217], v[14:17]
	v_mfma_f32_16x16x32_f16 v[10:13], v[168:171], v[214:217], v[10:13]
	s_nop 0
	s_barrier
; #define G8_STAGE(bufoff, gbase) do { _Pragma("unroll") for (int _i = 0; _i < 2; ++_i) \
;     __builtin_amdgcn_global_load_lds((const unsigned*)((const char*)(gbase) + voffA[_i]), (LAS unsigned*)(lds + (bufoff) + ldsw + _i * 8192), 16, 0, 0); } while (0)
; #define G8_MMA(ai, bj, At, Bt_) do { __builtin_amdgcn_s_setprio(1); _Pragma("unroll") for (int m = 0; m < 4; ++m) _Pragma("unroll") for (int n = 0; n < 2; ++n) _Pragma("unroll") for (int k = 0; k < 2; ++k) \
;     acc[ai][bj][m][n] = __builtin_amdgcn_mfma_f32_16x16x32_f16(Bt_[n][k], At[m][k], acc[ai][bj][m][n], 0, 0, 0); __builtin_amdgcn_s_setprio(0); } while (0)
; #define G8_WAIT_V(n) asm volatile("s_waitcnt vmcnt(" #n ")" ::: "memory")
; #define G8_BAR __builtin_amdgcn_s_barrier()
; template <class Epi>
; __device__ __forceinline__ void gemm_phase(LAS unsigned char* lds, const h16* A, const h16* Bt, int K, const Order& S, const Epi& E) {
;     ...
;       G8_STAGE(G8_SB(1, 1), b3 + hstep);
;       G8_WAIT_V(6); G8_BAR; G8_MMA(1, 1, At, B1); G8_BAR;
;     }
;     E(acc, cur, ui, wr, wc, fr, fq);
;   __device__ __forceinline__ void operator()(const f32x4 (&acc)[2][2][4][2], const g8::Unit& u, int ui, int wr, int wc, int fr, int fq) const {
; #pragma unroll
;     for (int ai = 0; ai < 2; ++ai)
; #pragma unroll
;       for (int m = 0; m < 4; ++m) {
;         const size_t row = (size_t)u.pm * 256 + 128 * ai + 64 * wr + 16 * m + fr;
;         const size_t base = row * DM + 256 * u.pn + 32 * wc + 8 * fq;
;         float ss = 0.f;
; #pragma unroll
;         for (int bj = 0; bj < 2; ++bj) {
;           const size_t idx = base + 128 * bj;
;           const h16x8 xv = *(const h16x8*)(xb + idx);
;           f32x4 x0 = acc[ai][bj][m][0], x1 = acc[ai][bj][m][1];
; #pragma unroll
;           for (int j = 0; j < 4; ++j) { x0[j] += (float)xv[j]; x1[j] += (float)xv[4 + j]; ss += x0[j] * x0[j] + x1[j] * x1[j]; }
;           if (final_out) {
;             __builtin_nontemporal_store(x0, (f32x4*)(xo + idx));
;             __builtin_nontemporal_store(x1, (f32x4*)(xo + idx + 4));
;           } else {
;             *(h16x8*)(xb + idx) = pack8(x0, x1);
	s_add_u32 s24, s24, 0x100080
	s_addc_u32 s25, s25, 0
	s_mov_b32 m0, s48
	v_lshl_add_u64 v[140:141], s[24:25], 0, v[0:1]
	global_load_lds_dwordx4 v[140:141], off
	v_lshl_add_u64 v[140:141], s[24:25], 0, v[130:131]
	s_mov_b32 m0, s49
	s_nop 0
	global_load_lds_dwordx4 v[140:141], off
	v_or_b32_e32 v140, 0x10000, v158
	v_add_u32_e32 v141, 0x10400, v158
	ds_read_b128 v[152:155], v140
	ds_read_b128 v[160:163], v141
	v_add_u32_e32 v140, 0x10800, v158
	v_add_u32_e32 v141, 0x10c00, v158
	ds_read_b128 v[164:167], v140
	ds_read_b128 v[168:171], v141
	s_waitcnt vmcnt(6)
	s_barrier
	s_nop 0
	v_mfma_f32_16x16x32_f16 v[54:57], v[218:221], v[172:175], v[54:57]
	v_mfma_f32_16x16x32_f16 v[50:53], v[226:229], v[172:175], v[50:53]
	v_mfma_f32_16x16x32_f16 v[38:41], v[218:221], v[180:183], v[38:41]
	v_mfma_f32_16x16x32_f16 v[34:37], v[226:229], v[180:183], v[34:37]
	v_mfma_f32_16x16x32_f16 v[22:25], v[218:221], v[202:205], v[22:25]
	v_mfma_f32_16x16x32_f16 v[18:21], v[226:229], v[202:205], v[18:21]
	v_mfma_f32_16x16x32_f16 v[6:9], v[218:221], v[210:213], v[6:9]
	v_mfma_f32_16x16x32_f16 v[2:5], v[226:229], v[210:213], v[2:5]
	v_mfma_f32_16x16x32_f16 v[54:57], v[222:225], v[176:179], v[54:57]
	v_mfma_f32_16x16x32_f16 v[50:53], v[230:233], v[176:179], v[50:53]
	v_mfma_f32_16x16x32_f16 v[38:41], v[222:225], v[184:187], v[38:41]
	v_mfma_f32_16x16x32_f16 v[34:37], v[230:233], v[184:187], v[34:37]
	v_mfma_f32_16x16x32_f16 v[22:25], v[222:225], v[206:209], v[22:25]
	v_mfma_f32_16x16x32_f16 v[18:21], v[230:233], v[206:209], v[18:21]
	v_mfma_f32_16x16x32_f16 v[6:9], v[222:225], v[214:217], v[6:9]
	v_mfma_f32_16x16x32_f16 v[2:5], v[230:233], v[214:217], v[2:5]
	s_nop 0
	s_add_i32 s53, s53, 2
	s_add_u32 s22, s22, 0x100
	s_addc_u32 s23, s23, 0
	s_add_u32 s51, s51, 0x100
	s_addc_u32 s52, s52, 0
	s_cmp_gt_u32 s53, 61
	s_barrier
	s_cbranch_scc0 .LBB0_2542
	s_waitcnt lgkmcnt(0)
	s_setprio 0
	s_ashr_i32 s9, s8, 31
	s_lshl_b64 s[8:9], s[8:9], 8
	s_lshl_b32 s3, s2, 8
	v_lshl_add_u64 v[140:141], s[8:9], 0, v[132:133]
	s_ashr_i32 s8, s3, 31
	v_mov_b32_e32 v153, s8
	v_or_b32_e32 v152, s3, v134
	v_lshlrev_b64 v[154:155], 10, v[140:141]
	v_lshl_add_u64 v[156:157], v[154:155], 0, v[152:153]
	v_lshl_add_u64 v[154:155], v[156:157], 1, s[10:11]
	global_load_dwordx4 v[166:169], v[154:155], off
	global_load_dwordx4 v[170:173], v[154:155], off offset:256
	s_mov_b32 s9, 0
	s_mov_b32 s8, 0x8000
	v_lshl_add_u64 v[234:235], v[154:155], 0, s[8:9]
	global_load_dwordx4 v[174:177], v[234:235], off
	global_load_dwordx4 v[178:181], v[234:235], off offset:256
	s_mov_b32 s8, 0x10000
	v_lshl_add_u64 v[234:235], v[154:155], 0, s[8:9]
	global_load_dwordx4 v[182:185], v[234:235], off
	global_load_dwordx4 v[186:189], v[234:235], off offset:256
	s_mov_b32 s8, 0x18000
	v_lshl_add_u64 v[234:235], v[154:155], 0, s[8:9]
	global_load_dwordx4 v[202:205], v[234:235], off
	global_load_dwordx4 v[206:209], v[234:235], off offset:256
	s_mov_b32 s8, 0x40000
	v_lshl_add_u64 v[234:235], v[154:155], 0, s[8:9]
	global_load_dwordx4 v[210:213], v[234:235], off
	global_load_dwordx4 v[214:217], v[234:235], off offset:256
	s_mov_b32 s8, 0x48000
	v_lshl_add_u64 v[234:235], v[154:155], 0, s[8:9]
	global_load_dwordx4 v[218:221], v[234:235], off
	global_load_dwordx4 v[222:225], v[234:235], off offset:256
	s_mov_b32 s8, 0x50000
	v_lshl_add_u64 v[234:235], v[154:155], 0, s[8:9]
	global_load_dwordx4 v[226:229], v[234:235], off
	global_load_dwordx4 v[230:233], v[234:235], off offset:256
	s_mov_b64 s[8:9], -1
	s_and_b64 vcc, exec, s[0:1]
	s_waitcnt vmcnt(13)
	v_cvt_f32_f16_e32 v164, v166
	v_cvt_f32_f16_sdwa v165, v166 dst_sel:DWORD dst_unused:UNUSED_PAD src0_sel:WORD_1
	v_cvt_f32_f16_e32 v160, v167
	v_cvt_f32_f16_sdwa v161, v167 dst_sel:DWORD dst_unused:UNUSED_PAD src0_sel:WORD_1
	v_pk_add_f32 v[126:127], v[126:127], v[164:165]
	v_cvt_f32_f16_e32 v164, v168
	v_cvt_f32_f16_sdwa v165, v168 dst_sel:DWORD dst_unused:UNUSED_PAD src0_sel:WORD_1
	v_pk_add_f32 v[128:129], v[128:129], v[160:161]
	v_cvt_f32_f16_e32 v160, v169
	v_cvt_f32_f16_sdwa v161, v169 dst_sel:DWORD dst_unused:UNUSED_PAD src0_sel:WORD_1
	v_pk_add_f32 v[122:123], v[122:123], v[164:165]
	v_pk_add_f32 v[124:125], v[124:125], v[160:161]
	s_cbranch_vccz .LBB0_2545
	v_cvt_pk_f16_f32 v163, v124, v125
	v_cvt_pk_f16_f32 v162, v122, v123
	v_cvt_pk_f16_f32 v161, v128, v129
	v_cvt_pk_f16_f32 v160, v126, v127
	global_store_dwordx4 v[154:155], v[160:163], off
	s_mov_b64 s[8:9], 0
